# GEMM K-loops: priority raised during load segments (LDS reads and LDS-DMA issue), dropped for MFMA clusters, on top of v74
# baseline (speedup 1.0000x reference)
; #define PG8_STAGE(bufoff, gbase, voff) do { _Pragma("unroll") for (int _i = 0; _i < 2; ++_i) \
;         __builtin_amdgcn_global_load_lds((const unsigned*)((const char*)(gbase) + (voff)[_i]), (LAS unsigned*)(lds + (bufoff) + ldsw + _i * 8192), 16, 0, 0); } while (0)
; #define PG8_LDA(dst, b, h) do { _Pragma("unroll") for (int m = 0; m < 4; ++m) _Pragma("unroll") for (int k = 0; k < 2; ++k) dst[m][k] = *(const LAS h16x8*)(lds + PG8_SA(b, h) + aoff + m * 2048 + k * 1024); } while (0)
; #define PG8_LDB(dst, b, h) do { _Pragma("unroll") for (int n = 0; n < 2; ++n) _Pragma("unroll") for (int k = 0; k < 2; ++k) dst[n][k] = *(const LAS h16x8*)(lds + PG8_SB(b, h) + boff + n * 2048 + k * 1024); } while (0)
; #define PG8_MMA(ai, bj, At, Bt) do { __builtin_amdgcn_s_setprio(1); _Pragma("unroll") for (int m = 0; m < 4; ++m) _Pragma("unroll") for (int n = 0; n < 2; ++n) _Pragma("unroll") for (int k = 0; k < 2; ++k) \
;         acc[ai][bj][m][n] = __builtin_amdgcn_mfma_f32_16x16x32_f16(Bt[n][k], At[m][k], acc[ai][bj][m][n], 0, 0, 0); __builtin_amdgcn_s_setprio(0); } while (0)
; #define PG8_WAIT_V(n) asm volatile("s_waitcnt vmcnt(" #n ")" ::: "memory")
; #define PG8_WAIT_L(n) asm volatile("s_waitcnt lgkmcnt(" #n ")" ::: "memory")
; #define PG8_BAR __builtin_amdgcn_s_barrier()
; #define PG8_SCHED __builtin_amdgcn_sched_barrier(0)
; template <class Epi>
; __device__ __forceinline__ void gemm_phase(LAS unsigned char* lds, const Gemm g, const StaticOrder& S, const Epi& E) {
;     ...
;             PG8_LDB(B0, 0, 0); PG8_LDB(B1, 0, 1); PG8_SCHED; PG8_LDA(At, 0, 0); PG8_STAGE(PG8_SA(1, 1), a1 + hstepA, voffA);
;             PG8_WAIT_V(8); PG8_WAIT_L(0); PG8_BAR; PG8_MMA(0, 0, At, B0); PG8_MMA(0, 1, At, B1); PG8_BAR; PG8_SCHED;
;             PG8_LDA(At, 0, 1); PG8_STAGE(PG8_SB(0, 0), b2, voffB); PG8_STAGE(PG8_SB(0, 1), b2 + hstepB, voffB); PG8_STAGE(PG8_SA(0, 0), a2, voffA);
;             PG8_WAIT_V(8); PG8_WAIT_L(0); PG8_BAR; PG8_MMA(1, 0, At, B0); PG8_MMA(1, 1, At, B1); PG8_BAR; PG8_SCHED;
.Lprio_140:
.LBB0_140:
	s_add_i32 s95, s22, 2
	s_add_u32 s96, s6, 0x80
	s_addc_u32 s23, s7, 0
	s_add_i32 vcc_lo, 0, 0x10000
	s_cmp_eq_u32 s79, s22
	s_cselect_b32 s23, s1, s23
	s_cselect_b32 s22, s0, s96
	v_add_u32_e32 v32, vcc_lo, v156
	s_cselect_b32 s97, s21, s94
	s_cselect_b32 s96, s20, s93
	s_add_i32 vcc_hi, 0, 0x14000
	ds_read_b128 v[130:133], v32
	ds_read_b128 v[134:137], v32 offset:1024
	ds_read_b128 v[150:153], v32 offset:2048
	ds_read_b128 v[160:163], v32 offset:3072
	v_add_u32_e32 v32, vcc_hi, v156
	ds_read_b128 v[164:167], v32
	ds_read_b128 v[168:171], v32 offset:1024
	ds_read_b128 v[172:175], v32 offset:2048
	ds_read_b128 v[176:179], v32 offset:3072
	v_lshl_add_u64 v[154:155], s[6:7], 0, v[148:149]
	s_add_i32 m0, s71, 0xc000
	ds_read_b128 v[196:199], v159
	ds_read_b128 v[204:207], v159 offset:1024
	ds_read_b128 v[208:211], v159 offset:2048
	ds_read_b128 v[212:215], v159 offset:3072
	ds_read_b128 v[216:219], v159 offset:4096
	ds_read_b128 v[220:223], v159 offset:5120
	ds_read_b128 v[224:227], v159 offset:6144
	ds_read_b128 v[228:231], v159 offset:7168
	global_load_lds_dwordx4 v[154:155], off
	v_lshl_add_u64 v[154:155], s[6:7], 0, v[146:147]
	s_add_i32 m0, s71, 0xe000
	s_nop 0
	global_load_lds_dwordx4 v[154:155], off
	s_waitcnt vmcnt(8)
	s_waitcnt lgkmcnt(0)
	s_barrier
	s_setprio 0
	s_waitcnt lgkmcnt(0)
	v_mfma_f32_16x16x32_f16 v[126:129], v[130:133], v[196:199], v[126:129]
	v_mfma_f32_16x16x32_f16 v[122:125], v[150:153], v[196:199], v[122:125]
	v_mfma_f32_16x16x32_f16 v[110:113], v[130:133], v[208:211], v[110:113]
	v_mfma_f32_16x16x32_f16 v[106:109], v[150:153], v[208:211], v[106:109]
	v_mfma_f32_16x16x32_f16 v[94:97], v[130:133], v[216:219], v[94:97]
	v_mfma_f32_16x16x32_f16 v[90:93], v[150:153], v[216:219], v[90:93]
	v_mfma_f32_16x16x32_f16 v[78:81], v[130:133], v[224:227], v[78:81]
	v_mfma_f32_16x16x32_f16 v[74:77], v[150:153], v[224:227], v[74:77]
	v_mfma_f32_16x16x32_f16 v[126:129], v[134:137], v[204:207], v[126:129]
	v_mfma_f32_16x16x32_f16 v[122:125], v[160:163], v[204:207], v[122:125]
	v_mfma_f32_16x16x32_f16 v[110:113], v[134:137], v[212:215], v[110:113]
	v_mfma_f32_16x16x32_f16 v[106:109], v[160:163], v[212:215], v[106:109]
	v_mfma_f32_16x16x32_f16 v[94:97], v[134:137], v[220:223], v[94:97]
	v_mfma_f32_16x16x32_f16 v[90:93], v[160:163], v[220:223], v[90:93]
	v_mfma_f32_16x16x32_f16 v[78:81], v[134:137], v[228:231], v[78:81]
	v_mfma_f32_16x16x32_f16 v[74:77], v[160:163], v[228:231], v[74:77]
	v_mfma_f32_16x16x32_f16 v[118:121], v[164:167], v[196:199], v[118:121]
	v_mfma_f32_16x16x32_f16 v[114:117], v[172:175], v[196:199], v[114:117]
	v_mfma_f32_16x16x32_f16 v[102:105], v[164:167], v[208:211], v[102:105]
	v_mfma_f32_16x16x32_f16 v[98:101], v[172:175], v[208:211], v[98:101]
	v_mfma_f32_16x16x32_f16 v[86:89], v[164:167], v[216:219], v[86:89]
	v_mfma_f32_16x16x32_f16 v[82:85], v[172:175], v[216:219], v[82:85]
	v_mfma_f32_16x16x32_f16 v[70:73], v[164:167], v[224:227], v[70:73]
	v_mfma_f32_16x16x32_f16 v[66:69], v[172:175], v[224:227], v[66:69]
	v_mfma_f32_16x16x32_f16 v[118:121], v[168:171], v[204:207], v[118:121]
	v_mfma_f32_16x16x32_f16 v[114:117], v[176:179], v[204:207], v[114:117]
	v_mfma_f32_16x16x32_f16 v[102:105], v[168:171], v[212:215], v[102:105]
	v_mfma_f32_16x16x32_f16 v[98:101], v[176:179], v[212:215], v[98:101]
	v_mfma_f32_16x16x32_f16 v[86:89], v[168:171], v[220:223], v[86:89]
	v_mfma_f32_16x16x32_f16 v[82:85], v[176:179], v[220:223], v[82:85]
	v_mfma_f32_16x16x32_f16 v[70:73], v[168:171], v[228:231], v[70:73]
	v_mfma_f32_16x16x32_f16 v[66:69], v[176:179], v[228:231], v[66:69]
	s_setprio 2
	s_barrier
	s_add_i32 vcc_lo, vcc_lo, s70
	v_lshl_add_u64 v[154:155], s[96:97], 0, v[142:143]
	s_mov_b32 m0, vcc_lo
	ds_read_b128 v[196:199], v159 offset:16384
	ds_read_b128 v[204:207], v159 offset:17408
	ds_read_b128 v[208:211], v159 offset:18432
	ds_read_b128 v[212:215], v159 offset:19456
	ds_read_b128 v[216:219], v159 offset:20480
	ds_read_b128 v[220:223], v159 offset:21504
	ds_read_b128 v[224:227], v159 offset:22528
	ds_read_b128 v[228:231], v159 offset:23552
	global_load_lds_dwordx4 v[154:155], off
	s_add_i32 m0, vcc_lo, 0x2000
	v_lshl_add_u64 v[180:181], s[96:97], 0, v[138:139]
	s_add_u32 s96, s96, s55
	s_addc_u32 s97, s97, 0
	s_add_i32 vcc_lo, vcc_hi, s70
	global_load_lds_dwordx4 v[180:181], off
	v_lshl_add_u64 v[190:191], s[96:97], 0, v[142:143]
	s_mov_b32 m0, vcc_lo
	v_lshl_add_u64 v[232:233], s[96:97], 0, v[138:139]
	global_load_lds_dwordx4 v[190:191], off
	s_add_i32 m0, vcc_lo, 0x2000
	v_lshl_add_u64 v[234:235], s[22:23], 0, v[144:145]
	global_load_lds_dwordx4 v[232:233], off
	s_mov_b32 m0, s71
	v_lshl_add_u64 v[236:237], s[22:23], 0, v[140:141]
	global_load_lds_dwordx4 v[234:235], off
	s_mov_b32 m0, s72
	s_nop 0
	global_load_lds_dwordx4 v[236:237], off
	s_waitcnt vmcnt(8)
	s_waitcnt lgkmcnt(0)
	s_barrier
; #define PG8_STAGE(bufoff, gbase, voff) do { _Pragma("unroll") for (int _i = 0; _i < 2; ++_i) \
;         __builtin_amdgcn_global_load_lds((const unsigned*)((const char*)(gbase) + (voff)[_i]), (LAS unsigned*)(lds + (bufoff) + ldsw + _i * 8192), 16, 0, 0); } while (0)
; #define PG8_LDA(dst, b, h) do { _Pragma("unroll") for (int m = 0; m < 4; ++m) _Pragma("unroll") for (int k = 0; k < 2; ++k) dst[m][k] = *(const LAS h16x8*)(lds + PG8_SA(b, h) + aoff + m * 2048 + k * 1024); } while (0)
; #define PG8_LDB(dst, b, h) do { _Pragma("unroll") for (int n = 0; n < 2; ++n) _Pragma("unroll") for (int k = 0; k < 2; ++k) dst[n][k] = *(const LAS h16x8*)(lds + PG8_SB(b, h) + boff + n * 2048 + k * 1024); } while (0)
; #define PG8_MMA(ai, bj, At, Bt) do { __builtin_amdgcn_s_setprio(1); _Pragma("unroll") for (int m = 0; m < 4; ++m) _Pragma("unroll") for (int n = 0; n < 2; ++n) _Pragma("unroll") for (int k = 0; k < 2; ++k) \
;         acc[ai][bj][m][n] = __builtin_amdgcn_mfma_f32_16x16x32_f16(Bt[n][k], At[m][k], acc[ai][bj][m][n], 0, 0, 0); __builtin_amdgcn_s_setprio(0); } while (0)
; #define PG8_WAIT_V(n) asm volatile("s_waitcnt vmcnt(" #n ")" ::: "memory")
; #define PG8_WAIT_L(n) asm volatile("s_waitcnt lgkmcnt(" #n ")" ::: "memory")
; #define PG8_BAR __builtin_amdgcn_s_barrier()
; #define PG8_SCHED __builtin_amdgcn_sched_barrier(0)
; template <class Epi>
; __device__ __forceinline__ void gemm_phase(LAS unsigned char* lds, const Gemm g, const StaticOrder& S, const Epi& E) {
;     ...
;             PG8_WAIT_V(8); PG8_WAIT_L(0); PG8_BAR; PG8_MMA(1, 0, At, B0); PG8_MMA(1, 1, At, B1); PG8_BAR; PG8_SCHED;
;             PG8_LDB(B0, 1, 0); PG8_LDB(B1, 1, 1); PG8_SCHED; PG8_LDA(At, 1, 0); PG8_STAGE(PG8_SA(0, 1), a2 + hstepA, voffA);
;             PG8_WAIT_V(8); PG8_WAIT_L(0); PG8_BAR; PG8_MMA(0, 0, At, B0); PG8_MMA(0, 1, At, B1); PG8_BAR; PG8_SCHED;
;             PG8_LDA(At, 1, 1); PG8_STAGE(PG8_SB(1, 0), b3, voffB); PG8_STAGE(PG8_SB(1, 1), b3 + hstepB, voffB); PG8_STAGE(PG8_SA(1, 0), a3, voffA);
;             PG8_WAIT_V(8); PG8_WAIT_L(0); PG8_BAR; PG8_MMA(1, 0, At, B0); PG8_MMA(1, 1, At, B1); PG8_BAR; PG8_SCHED;
	s_setprio 0
	s_waitcnt lgkmcnt(0)
	v_mfma_f32_16x16x32_f16 v[62:65], v[130:133], v[196:199], v[62:65]
	v_mfma_f32_16x16x32_f16 v[58:61], v[150:153], v[196:199], v[58:61]
	v_mfma_f32_16x16x32_f16 v[46:49], v[130:133], v[208:211], v[46:49]
	v_mfma_f32_16x16x32_f16 v[42:45], v[150:153], v[208:211], v[42:45]
	v_mfma_f32_16x16x32_f16 v[28:31], v[130:133], v[216:219], v[28:31]
	v_mfma_f32_16x16x32_f16 v[24:27], v[150:153], v[216:219], v[24:27]
	v_mfma_f32_16x16x32_f16 v[12:15], v[130:133], v[224:227], v[12:15]
	v_mfma_f32_16x16x32_f16 v[8:11], v[150:153], v[224:227], v[8:11]
	v_mfma_f32_16x16x32_f16 v[62:65], v[134:137], v[204:207], v[62:65]
	v_mfma_f32_16x16x32_f16 v[58:61], v[160:163], v[204:207], v[58:61]
	v_mfma_f32_16x16x32_f16 v[46:49], v[134:137], v[212:215], v[46:49]
	v_mfma_f32_16x16x32_f16 v[42:45], v[160:163], v[212:215], v[42:45]
	v_mfma_f32_16x16x32_f16 v[28:31], v[134:137], v[220:223], v[28:31]
	v_mfma_f32_16x16x32_f16 v[24:27], v[160:163], v[220:223], v[24:27]
	v_mfma_f32_16x16x32_f16 v[12:15], v[134:137], v[228:231], v[12:15]
	v_mfma_f32_16x16x32_f16 v[8:11], v[160:163], v[228:231], v[8:11]
	v_mfma_f32_16x16x32_f16 v[54:57], v[164:167], v[196:199], v[54:57]
	v_mfma_f32_16x16x32_f16 v[50:53], v[172:175], v[196:199], v[50:53]
	v_mfma_f32_16x16x32_f16 v[38:41], v[164:167], v[208:211], v[38:41]
	v_mfma_f32_16x16x32_f16 v[34:37], v[172:175], v[208:211], v[34:37]
	v_mfma_f32_16x16x32_f16 v[20:23], v[164:167], v[216:219], v[20:23]
	v_mfma_f32_16x16x32_f16 v[16:19], v[172:175], v[216:219], v[16:19]
	v_mfma_f32_16x16x32_f16 v[4:7], v[164:167], v[224:227], v[4:7]
	v_mfma_f32_16x16x32_f16 v[0:3], v[172:175], v[224:227], v[0:3]
	v_mfma_f32_16x16x32_f16 v[54:57], v[168:171], v[204:207], v[54:57]
	v_mfma_f32_16x16x32_f16 v[50:53], v[176:179], v[204:207], v[50:53]
	v_mfma_f32_16x16x32_f16 v[38:41], v[168:171], v[212:215], v[38:41]
	v_mfma_f32_16x16x32_f16 v[34:37], v[176:179], v[212:215], v[34:37]
	v_mfma_f32_16x16x32_f16 v[20:23], v[168:171], v[220:223], v[20:23]
	v_mfma_f32_16x16x32_f16 v[16:19], v[176:179], v[220:223], v[16:19]
	v_mfma_f32_16x16x32_f16 v[4:7], v[168:171], v[228:231], v[4:7]
	v_mfma_f32_16x16x32_f16 v[0:3], v[176:179], v[228:231], v[0:3]
	s_setprio 2
	s_barrier
	s_add_i32 s96, 0, 0x18000
	v_add_u32_e32 v32, s96, v156
	s_add_i32 s97, 0, 0x1c000
	ds_read_b128 v[130:133], v32
	ds_read_b128 v[134:137], v32 offset:1024
	ds_read_b128 v[150:153], v32 offset:2048
	ds_read_b128 v[160:163], v32 offset:3072
	v_add_u32_e32 v32, s97, v156
	ds_read_b128 v[164:167], v32
	ds_read_b128 v[168:171], v32 offset:1024
	ds_read_b128 v[172:175], v32 offset:2048
	ds_read_b128 v[176:179], v32 offset:3072
	s_add_u32 s22, s22, s24
	s_addc_u32 s23, s23, 0
	s_mov_b32 m0, s73
	v_lshl_add_u64 v[238:239], s[22:23], 0, v[144:145]
	ds_read_b128 v[196:199], v159 offset:32768
	ds_read_b128 v[204:207], v159 offset:33792
	ds_read_b128 v[208:211], v159 offset:34816
	ds_read_b128 v[212:215], v159 offset:35840
	ds_read_b128 v[216:219], v159 offset:36864
	ds_read_b128 v[220:223], v159 offset:37888
	ds_read_b128 v[224:227], v159 offset:38912
	ds_read_b128 v[228:231], v159 offset:39936
	global_load_lds_dwordx4 v[238:239], off
	v_lshl_add_u64 v[238:239], s[22:23], 0, v[140:141]
	s_mov_b32 m0, s75
	s_nop 0
	global_load_lds_dwordx4 v[238:239], off
	s_waitcnt vmcnt(8)
	s_waitcnt lgkmcnt(0)
	s_barrier
	s_setprio 0
	s_waitcnt lgkmcnt(0)
	v_mfma_f32_16x16x32_f16 v[126:129], v[130:133], v[196:199], v[126:129]
	v_mfma_f32_16x16x32_f16 v[122:125], v[150:153], v[196:199], v[122:125]
	v_mfma_f32_16x16x32_f16 v[110:113], v[130:133], v[208:211], v[110:113]
	v_mfma_f32_16x16x32_f16 v[106:109], v[150:153], v[208:211], v[106:109]
	v_mfma_f32_16x16x32_f16 v[94:97], v[130:133], v[216:219], v[94:97]
	v_mfma_f32_16x16x32_f16 v[90:93], v[150:153], v[216:219], v[90:93]
	v_mfma_f32_16x16x32_f16 v[78:81], v[130:133], v[224:227], v[78:81]
	v_mfma_f32_16x16x32_f16 v[74:77], v[150:153], v[224:227], v[74:77]
	v_mfma_f32_16x16x32_f16 v[126:129], v[134:137], v[204:207], v[126:129]
	v_mfma_f32_16x16x32_f16 v[122:125], v[160:163], v[204:207], v[122:125]
	v_mfma_f32_16x16x32_f16 v[110:113], v[134:137], v[212:215], v[110:113]
	v_mfma_f32_16x16x32_f16 v[106:109], v[160:163], v[212:215], v[106:109]
	v_mfma_f32_16x16x32_f16 v[94:97], v[134:137], v[220:223], v[94:97]
	v_mfma_f32_16x16x32_f16 v[90:93], v[160:163], v[220:223], v[90:93]
	v_mfma_f32_16x16x32_f16 v[78:81], v[134:137], v[228:231], v[78:81]
	v_mfma_f32_16x16x32_f16 v[74:77], v[160:163], v[228:231], v[74:77]
	v_mfma_f32_16x16x32_f16 v[118:121], v[164:167], v[196:199], v[118:121]
	v_mfma_f32_16x16x32_f16 v[114:117], v[172:175], v[196:199], v[114:117]
	v_mfma_f32_16x16x32_f16 v[102:105], v[164:167], v[208:211], v[102:105]
	v_mfma_f32_16x16x32_f16 v[98:101], v[172:175], v[208:211], v[98:101]
	v_mfma_f32_16x16x32_f16 v[86:89], v[164:167], v[216:219], v[86:89]
	v_mfma_f32_16x16x32_f16 v[82:85], v[172:175], v[216:219], v[82:85]
	v_mfma_f32_16x16x32_f16 v[70:73], v[164:167], v[224:227], v[70:73]
	v_mfma_f32_16x16x32_f16 v[66:69], v[172:175], v[224:227], v[66:69]
	v_mfma_f32_16x16x32_f16 v[118:121], v[168:171], v[204:207], v[118:121]
	v_mfma_f32_16x16x32_f16 v[114:117], v[176:179], v[204:207], v[114:117]
	v_mfma_f32_16x16x32_f16 v[102:105], v[168:171], v[212:215], v[102:105]
	v_mfma_f32_16x16x32_f16 v[98:101], v[176:179], v[212:215], v[98:101]
	v_mfma_f32_16x16x32_f16 v[86:89], v[168:171], v[220:223], v[86:89]
	v_mfma_f32_16x16x32_f16 v[82:85], v[176:179], v[220:223], v[82:85]
	v_mfma_f32_16x16x32_f16 v[70:73], v[168:171], v[228:231], v[70:73]
	v_mfma_f32_16x16x32_f16 v[66:69], v[176:179], v[228:231], v[66:69]
	s_setprio 2
	s_barrier
; #define PG8_STAGE(bufoff, gbase, voff) do { _Pragma("unroll") for (int _i = 0; _i < 2; ++_i) \
;         __builtin_amdgcn_global_load_lds((const unsigned*)((const char*)(gbase) + (voff)[_i]), (LAS unsigned*)(lds + (bufoff) + ldsw + _i * 8192), 16, 0, 0); } while (0)
; #define PG8_LDA(dst, b, h) do { _Pragma("unroll") for (int m = 0; m < 4; ++m) _Pragma("unroll") for (int k = 0; k < 2; ++k) dst[m][k] = *(const LAS h16x8*)(lds + PG8_SA(b, h) + aoff + m * 2048 + k * 1024); } while (0)
; #define PG8_LDB(dst, b, h) do { _Pragma("unroll") for (int n = 0; n < 2; ++n) _Pragma("unroll") for (int k = 0; k < 2; ++k) dst[n][k] = *(const LAS h16x8*)(lds + PG8_SB(b, h) + boff + n * 2048 + k * 1024); } while (0)
; #define PG8_WAIT_V(n) asm volatile("s_waitcnt vmcnt(" #n ")" ::: "memory")
; template <class Epi>
; __device__ __forceinline__ void gemm_phase(LAS unsigned char* lds, const Gemm g, const StaticOrder& S, const Epi& E) {
;     ...
;         for (int t = 0; t < nt; t += 2) {
;             const bool last = (t == nt - 2);
;             const char* a1 = cA + (size_t)(t + 1) * kstep;
;             const char* a2 = last ? nA : cA + (size_t)(t + 2) * kstep; const char* b2 = last ? nB : cB + (size_t)(t + 2) * kstep;
;             const char* a3 = a2 + kstep; const char* b3 = b2 + kstep;
;             PG8_LDB(B0, 0, 0); PG8_LDB(B1, 0, 1); PG8_SCHED; PG8_LDA(At, 0, 0); PG8_STAGE(PG8_SA(1, 1), a1 + hstepA, voffA);
;             PG8_WAIT_V(8); PG8_WAIT_L(0); PG8_BAR; PG8_MMA(0, 0, At, B0); PG8_MMA(0, 1, At, B1); PG8_BAR; PG8_SCHED;
;             PG8_LDA(At, 0, 1); PG8_STAGE(PG8_SB(0, 0), b2, voffB); PG8_STAGE(PG8_SB(0, 1), b2 + hstepB, voffB); PG8_STAGE(PG8_SA(0, 0), a2, voffA);
;             PG8_WAIT_V(8); PG8_WAIT_L(0); PG8_BAR; PG8_MMA(1, 0, At, B0); PG8_MMA(1, 1, At, B1); PG8_BAR; PG8_SCHED;
;             PG8_LDB(B0, 1, 0); PG8_LDB(B1, 1, 1); PG8_SCHED; PG8_LDA(At, 1, 0); PG8_STAGE(PG8_SA(0, 1), a2 + hstepA, voffA);
;             PG8_WAIT_V(8); PG8_WAIT_L(0); PG8_BAR; PG8_MMA(0, 0, At, B0); PG8_MMA(0, 1, At, B1); PG8_BAR; PG8_SCHED;
;             PG8_LDA(At, 1, 1); PG8_STAGE(PG8_SB(1, 0), b3, voffB); PG8_STAGE(PG8_SB(1, 1), b3 + hstepB, voffB); PG8_STAGE(PG8_SA(1, 0), a3, voffA);
;             PG8_WAIT_V(8); PG8_WAIT_L(0); PG8_BAR; PG8_MMA(1, 0, At, B0); PG8_MMA(1, 1, At, B1); PG8_BAR; PG8_SCHED;
;         }
;         if (wr == 0) PG8_BAR;
	s_add_i32 s22, s96, s70
	v_lshl_add_u64 v[154:155], v[154:155], 0, s[90:91]
	s_mov_b32 m0, s22
	ds_read_b128 v[196:199], v159 offset:49152
	ds_read_b128 v[204:207], v159 offset:50176
	ds_read_b128 v[208:211], v159 offset:51200
	ds_read_b128 v[212:215], v159 offset:52224
	ds_read_b128 v[216:219], v159 offset:53248
	ds_read_b128 v[220:223], v159 offset:54272
	ds_read_b128 v[224:227], v159 offset:55296
	ds_read_b128 v[228:231], v159 offset:56320
	global_load_lds_dwordx4 v[154:155], off
	v_lshl_add_u64 v[154:155], v[180:181], 0, s[90:91]
	s_add_i32 m0, s22, 0x2000
	s_add_i32 s22, s97, s70
	global_load_lds_dwordx4 v[154:155], off
	v_lshl_add_u64 v[154:155], v[190:191], 0, s[90:91]
	s_mov_b32 m0, s22
	s_nop 0
	global_load_lds_dwordx4 v[154:155], off
	v_lshl_add_u64 v[154:155], v[232:233], 0, s[90:91]
	s_add_i32 m0, s22, 0x2000
	s_nop 0
	global_load_lds_dwordx4 v[154:155], off
	v_lshl_add_u64 v[154:155], v[234:235], 0, s[90:91]
	s_mov_b32 m0, s77
	s_nop 0
	global_load_lds_dwordx4 v[154:155], off
	v_lshl_add_u64 v[154:155], v[236:237], 0, s[90:91]
	s_mov_b32 m0, s78
	s_nop 0
	global_load_lds_dwordx4 v[154:155], off
	s_waitcnt vmcnt(8)
	s_waitcnt lgkmcnt(0)
	s_barrier
	s_setprio 0
	s_waitcnt lgkmcnt(0)
	v_mfma_f32_16x16x32_f16 v[62:65], v[130:133], v[196:199], v[62:65]
	v_mfma_f32_16x16x32_f16 v[58:61], v[150:153], v[196:199], v[58:61]
	v_mfma_f32_16x16x32_f16 v[46:49], v[130:133], v[208:211], v[46:49]
	v_mfma_f32_16x16x32_f16 v[42:45], v[150:153], v[208:211], v[42:45]
	v_mfma_f32_16x16x32_f16 v[28:31], v[130:133], v[216:219], v[28:31]
	v_mfma_f32_16x16x32_f16 v[24:27], v[150:153], v[216:219], v[24:27]
	v_mfma_f32_16x16x32_f16 v[12:15], v[130:133], v[224:227], v[12:15]
	v_mfma_f32_16x16x32_f16 v[8:11], v[150:153], v[224:227], v[8:11]
	v_mfma_f32_16x16x32_f16 v[62:65], v[134:137], v[204:207], v[62:65]
	v_mfma_f32_16x16x32_f16 v[58:61], v[160:163], v[204:207], v[58:61]
	v_mfma_f32_16x16x32_f16 v[46:49], v[134:137], v[212:215], v[46:49]
	v_mfma_f32_16x16x32_f16 v[42:45], v[160:163], v[212:215], v[42:45]
	v_mfma_f32_16x16x32_f16 v[28:31], v[134:137], v[220:223], v[28:31]
	v_mfma_f32_16x16x32_f16 v[24:27], v[160:163], v[220:223], v[24:27]
	v_mfma_f32_16x16x32_f16 v[12:15], v[134:137], v[228:231], v[12:15]
	v_mfma_f32_16x16x32_f16 v[8:11], v[160:163], v[228:231], v[8:11]
	v_mfma_f32_16x16x32_f16 v[54:57], v[164:167], v[196:199], v[54:57]
	v_mfma_f32_16x16x32_f16 v[50:53], v[172:175], v[196:199], v[50:53]
	v_mfma_f32_16x16x32_f16 v[38:41], v[164:167], v[208:211], v[38:41]
	v_mfma_f32_16x16x32_f16 v[34:37], v[172:175], v[208:211], v[34:37]
	v_mfma_f32_16x16x32_f16 v[20:23], v[164:167], v[216:219], v[20:23]
	v_mfma_f32_16x16x32_f16 v[16:19], v[172:175], v[216:219], v[16:19]
	v_mfma_f32_16x16x32_f16 v[4:7], v[164:167], v[224:227], v[4:7]
	v_mfma_f32_16x16x32_f16 v[0:3], v[172:175], v[224:227], v[0:3]
	v_mfma_f32_16x16x32_f16 v[54:57], v[168:171], v[204:207], v[54:57]
	v_mfma_f32_16x16x32_f16 v[50:53], v[176:179], v[204:207], v[50:53]
	v_mfma_f32_16x16x32_f16 v[38:41], v[168:171], v[212:215], v[38:41]
	v_mfma_f32_16x16x32_f16 v[34:37], v[176:179], v[212:215], v[34:37]
	v_mfma_f32_16x16x32_f16 v[20:23], v[168:171], v[220:223], v[20:23]
	v_mfma_f32_16x16x32_f16 v[16:19], v[176:179], v[220:223], v[16:19]
	v_mfma_f32_16x16x32_f16 v[4:7], v[168:171], v[228:231], v[4:7]
	v_mfma_f32_16x16x32_f16 v[0:3], v[176:179], v[228:231], v[0:3]
	s_setprio 2
	s_barrier
	s_add_u32 s93, s93, 0x100
	s_addc_u32 s94, s94, 0
	s_add_u32 s6, s6, 0x100
	s_addc_u32 s7, s7, 0
	s_cmp_ge_u32 s95, s76
	s_mov_b32 s22, s95
	s_cbranch_scc0 .LBB0_140
	s_setprio 0
	s_and_b64 vcc, exec, s[18:19]
	s_cbranch_vccz .LBB0_143
	s_barrier

; #define PG8_STAGE(bufoff, gbase, voff) do { _Pragma("unroll") for (int _i = 0; _i < 2; ++_i) \
;         __builtin_amdgcn_global_load_lds((const unsigned*)((const char*)(gbase) + (voff)[_i]), (LAS unsigned*)(lds + (bufoff) + ldsw + _i * 8192), 16, 0, 0); } while (0)
; #define PG8_LDA(dst, b, h) do { _Pragma("unroll") for (int m = 0; m < 4; ++m) _Pragma("unroll") for (int k = 0; k < 2; ++k) dst[m][k] = *(const LAS h16x8*)(lds + PG8_SA(b, h) + aoff + m * 2048 + k * 1024); } while (0)
; #define PG8_LDB(dst, b, h) do { _Pragma("unroll") for (int n = 0; n < 2; ++n) _Pragma("unroll") for (int k = 0; k < 2; ++k) dst[n][k] = *(const LAS h16x8*)(lds + PG8_SB(b, h) + boff + n * 2048 + k * 1024); } while (0)
; #define PG8_MMA(ai, bj, At, Bt) do { __builtin_amdgcn_s_setprio(1); _Pragma("unroll") for (int m = 0; m < 4; ++m) _Pragma("unroll") for (int n = 0; n < 2; ++n) _Pragma("unroll") for (int k = 0; k < 2; ++k) \
;         acc[ai][bj][m][n] = __builtin_amdgcn_mfma_f32_16x16x32_f16(Bt[n][k], At[m][k], acc[ai][bj][m][n], 0, 0, 0); __builtin_amdgcn_s_setprio(0); } while (0)
; #define PG8_WAIT_V(n) asm volatile("s_waitcnt vmcnt(" #n ")" ::: "memory")
; #define PG8_WAIT_L(n) asm volatile("s_waitcnt lgkmcnt(" #n ")" ::: "memory")
; #define PG8_BAR __builtin_amdgcn_s_barrier()
; #define PG8_SCHED __builtin_amdgcn_sched_barrier(0)
; template <class Epi>
; __device__ __forceinline__ void gemm_phase(LAS unsigned char* lds, const Gemm g, const StaticOrder& S, const Epi& E) {
;     ...
;             const bool last = (t == nt - 2);
;             const char* a1 = cA + (size_t)(t + 1) * kstep;
;             const char* a2 = last ? nA : cA + (size_t)(t + 2) * kstep; const char* b2 = last ? nB : cB + (size_t)(t + 2) * kstep;
;             const char* a3 = a2 + kstep; const char* b3 = b2 + kstep;
;             PG8_LDB(B0, 0, 0); PG8_LDB(B1, 0, 1); PG8_SCHED; PG8_LDA(At, 0, 0); PG8_STAGE(PG8_SA(1, 1), a1 + hstepA, voffA);
;             PG8_WAIT_V(8); PG8_WAIT_L(0); PG8_BAR; PG8_MMA(0, 0, At, B0); PG8_MMA(0, 1, At, B1); PG8_BAR; PG8_SCHED;
;             PG8_LDA(At, 0, 1); PG8_STAGE(PG8_SB(0, 0), b2, voffB); PG8_STAGE(PG8_SB(0, 1), b2 + hstepB, voffB); PG8_STAGE(PG8_SA(0, 0), a2, voffA);
.Lprio_214:
.LBB0_214:
	s_add_u32 s20, s18, 0xfffc0080
	s_addc_u32 s21, s19, -1
	s_add_i32 s76, 0, 0x10000
	s_cmp_eq_u32 s75, 12
	s_cselect_b32 s23, s13, s21
	s_cselect_b32 s22, s70, s20
	v_add_u32_e32 v32, s76, v145
	s_cselect_b32 s21, s11, s73
	s_cselect_b32 s20, s71, s72
	s_add_i32 s78, 0, 0x14000
	ds_read_b128 v[148:151], v32
	ds_read_b128 v[152:155], v32 offset:1024
	ds_read_b128 v[156:159], v32 offset:2048
	ds_read_b128 v[160:163], v32 offset:3072
	v_add_u32_e32 v32, s78, v145
	ds_read_b128 v[164:167], v32
	ds_read_b128 v[168:171], v32 offset:1024
	ds_read_b128 v[172:175], v32 offset:2048
	ds_read_b128 v[176:179], v32 offset:3072
	v_lshl_add_u64 v[180:181], s[18:19], 0, v[142:143]
	s_add_i32 m0, s28, 0xc000
	ds_read_b128 v[196:199], v147
	ds_read_b128 v[204:207], v147 offset:1024
	ds_read_b128 v[208:211], v147 offset:2048
	ds_read_b128 v[212:215], v147 offset:3072
	ds_read_b128 v[216:219], v147 offset:4096
	ds_read_b128 v[220:223], v147 offset:5120
	ds_read_b128 v[224:227], v147 offset:6144
	ds_read_b128 v[228:231], v147 offset:7168
	global_load_lds_dwordx4 v[180:181], off
	v_lshl_add_u64 v[180:181], s[18:19], 0, v[140:141]
	s_add_i32 m0, s28, 0xe000
	s_nop 0
	global_load_lds_dwordx4 v[180:181], off
	s_waitcnt vmcnt(8)
	s_waitcnt lgkmcnt(0)
	s_barrier
	s_setprio 0
	s_waitcnt lgkmcnt(0)
	v_mfma_f32_16x16x32_f16 v[126:129], v[148:151], v[196:199], v[126:129]
	v_mfma_f32_16x16x32_f16 v[122:125], v[156:159], v[196:199], v[122:125]
	v_mfma_f32_16x16x32_f16 v[110:113], v[148:151], v[208:211], v[110:113]
	v_mfma_f32_16x16x32_f16 v[106:109], v[156:159], v[208:211], v[106:109]
	v_mfma_f32_16x16x32_f16 v[94:97], v[148:151], v[216:219], v[94:97]
	v_mfma_f32_16x16x32_f16 v[90:93], v[156:159], v[216:219], v[90:93]
	v_mfma_f32_16x16x32_f16 v[78:81], v[148:151], v[224:227], v[78:81]
	v_mfma_f32_16x16x32_f16 v[74:77], v[156:159], v[224:227], v[74:77]
	v_mfma_f32_16x16x32_f16 v[126:129], v[152:155], v[204:207], v[126:129]
	v_mfma_f32_16x16x32_f16 v[122:125], v[160:163], v[204:207], v[122:125]
	v_mfma_f32_16x16x32_f16 v[110:113], v[152:155], v[212:215], v[110:113]
	v_mfma_f32_16x16x32_f16 v[106:109], v[160:163], v[212:215], v[106:109]
	v_mfma_f32_16x16x32_f16 v[94:97], v[152:155], v[220:223], v[94:97]
	v_mfma_f32_16x16x32_f16 v[90:93], v[160:163], v[220:223], v[90:93]
	v_mfma_f32_16x16x32_f16 v[78:81], v[152:155], v[228:231], v[78:81]
	v_mfma_f32_16x16x32_f16 v[74:77], v[160:163], v[228:231], v[74:77]
	v_mfma_f32_16x16x32_f16 v[118:121], v[164:167], v[196:199], v[118:121]
	v_mfma_f32_16x16x32_f16 v[114:117], v[172:175], v[196:199], v[114:117]
	v_mfma_f32_16x16x32_f16 v[102:105], v[164:167], v[208:211], v[102:105]
	v_mfma_f32_16x16x32_f16 v[98:101], v[172:175], v[208:211], v[98:101]
	v_mfma_f32_16x16x32_f16 v[86:89], v[164:167], v[216:219], v[86:89]
	v_mfma_f32_16x16x32_f16 v[82:85], v[172:175], v[216:219], v[82:85]
	v_mfma_f32_16x16x32_f16 v[70:73], v[164:167], v[224:227], v[70:73]
	v_mfma_f32_16x16x32_f16 v[66:69], v[172:175], v[224:227], v[66:69]
	v_mfma_f32_16x16x32_f16 v[118:121], v[168:171], v[204:207], v[118:121]
	v_mfma_f32_16x16x32_f16 v[114:117], v[176:179], v[204:207], v[114:117]
	v_mfma_f32_16x16x32_f16 v[102:105], v[168:171], v[212:215], v[102:105]
	v_mfma_f32_16x16x32_f16 v[98:101], v[176:179], v[212:215], v[98:101]
	v_mfma_f32_16x16x32_f16 v[86:89], v[168:171], v[220:223], v[86:89]
	v_mfma_f32_16x16x32_f16 v[82:85], v[176:179], v[220:223], v[82:85]
	v_mfma_f32_16x16x32_f16 v[70:73], v[168:171], v[228:231], v[70:73]
	v_mfma_f32_16x16x32_f16 v[66:69], v[176:179], v[228:231], v[66:69]
	s_setprio 2
	s_barrier
	s_add_i32 s76, s76, s24
	v_lshl_add_u64 v[180:181], s[20:21], 0, v[134:135]
	s_mov_b32 m0, s76
	ds_read_b128 v[196:199], v147 offset:16384
	ds_read_b128 v[204:207], v147 offset:17408
	ds_read_b128 v[208:211], v147 offset:18432
	ds_read_b128 v[212:215], v147 offset:19456
	ds_read_b128 v[216:219], v147 offset:20480
	ds_read_b128 v[220:223], v147 offset:21504
	ds_read_b128 v[224:227], v147 offset:22528
	ds_read_b128 v[228:231], v147 offset:23552
	global_load_lds_dwordx4 v[180:181], off
	s_add_i32 m0, s76, 0x2000
	s_add_u32 s76, s20, 0x40000
	v_lshl_add_u64 v[190:191], s[20:21], 0, v[130:131]
	s_addc_u32 s77, s21, 0
	s_add_i32 s78, s78, s24
	global_load_lds_dwordx4 v[190:191], off
	v_lshl_add_u64 v[232:233], s[76:77], 0, v[134:135]
	s_mov_b32 m0, s78
	v_lshl_add_u64 v[234:235], s[22:23], 0, v[132:133]
	global_load_lds_dwordx4 v[232:233], off
	v_lshl_add_u64 v[232:233], s[76:77], 0, v[130:131]
	s_add_i32 m0, s78, 0x2000
	s_nop 0
	global_load_lds_dwordx4 v[232:233], off
	v_lshl_add_u64 v[232:233], s[22:23], 0, v[136:137]
	s_mov_b32 m0, s28
	s_nop 0
	global_load_lds_dwordx4 v[232:233], off
	s_mov_b32 m0, s29
	s_nop 0
	global_load_lds_dwordx4 v[234:235], off
	s_waitcnt vmcnt(8)
	s_waitcnt lgkmcnt(0)
	s_barrier
; #define PG8_STAGE(bufoff, gbase, voff) do { _Pragma("unroll") for (int _i = 0; _i < 2; ++_i) \
;         __builtin_amdgcn_global_load_lds((const unsigned*)((const char*)(gbase) + (voff)[_i]), (LAS unsigned*)(lds + (bufoff) + ldsw + _i * 8192), 16, 0, 0); } while (0)
; #define PG8_LDA(dst, b, h) do { _Pragma("unroll") for (int m = 0; m < 4; ++m) _Pragma("unroll") for (int k = 0; k < 2; ++k) dst[m][k] = *(const LAS h16x8*)(lds + PG8_SA(b, h) + aoff + m * 2048 + k * 1024); } while (0)
; #define PG8_LDB(dst, b, h) do { _Pragma("unroll") for (int n = 0; n < 2; ++n) _Pragma("unroll") for (int k = 0; k < 2; ++k) dst[n][k] = *(const LAS h16x8*)(lds + PG8_SB(b, h) + boff + n * 2048 + k * 1024); } while (0)
; #define PG8_MMA(ai, bj, At, Bt) do { __builtin_amdgcn_s_setprio(1); _Pragma("unroll") for (int m = 0; m < 4; ++m) _Pragma("unroll") for (int n = 0; n < 2; ++n) _Pragma("unroll") for (int k = 0; k < 2; ++k) \
;         acc[ai][bj][m][n] = __builtin_amdgcn_mfma_f32_16x16x32_f16(Bt[n][k], At[m][k], acc[ai][bj][m][n], 0, 0, 0); __builtin_amdgcn_s_setprio(0); } while (0)
; #define PG8_WAIT_V(n) asm volatile("s_waitcnt vmcnt(" #n ")" ::: "memory")
; #define PG8_WAIT_L(n) asm volatile("s_waitcnt lgkmcnt(" #n ")" ::: "memory")
; #define PG8_BAR __builtin_amdgcn_s_barrier()
; #define PG8_SCHED __builtin_amdgcn_sched_barrier(0)
; template <class Epi>
; __device__ __forceinline__ void gemm_phase(LAS unsigned char* lds, const Gemm g, const StaticOrder& S, const Epi& E) {
;     ...
;             PG8_WAIT_V(8); PG8_WAIT_L(0); PG8_BAR; PG8_MMA(1, 0, At, B0); PG8_MMA(1, 1, At, B1); PG8_BAR; PG8_SCHED;
;             PG8_LDB(B0, 1, 0); PG8_LDB(B1, 1, 1); PG8_SCHED; PG8_LDA(At, 1, 0); PG8_STAGE(PG8_SA(0, 1), a2 + hstepA, voffA);
;             PG8_WAIT_V(8); PG8_WAIT_L(0); PG8_BAR; PG8_MMA(0, 0, At, B0); PG8_MMA(0, 1, At, B1); PG8_BAR; PG8_SCHED;
	s_setprio 0
	s_waitcnt lgkmcnt(0)
	v_mfma_f32_16x16x32_f16 v[62:65], v[148:151], v[196:199], v[62:65]
	v_mfma_f32_16x16x32_f16 v[58:61], v[156:159], v[196:199], v[58:61]
	v_mfma_f32_16x16x32_f16 v[46:49], v[148:151], v[208:211], v[46:49]
	v_mfma_f32_16x16x32_f16 v[42:45], v[156:159], v[208:211], v[42:45]
	v_mfma_f32_16x16x32_f16 v[28:31], v[148:151], v[216:219], v[28:31]
	v_mfma_f32_16x16x32_f16 v[24:27], v[156:159], v[216:219], v[24:27]
	v_mfma_f32_16x16x32_f16 v[12:15], v[148:151], v[224:227], v[12:15]
	v_mfma_f32_16x16x32_f16 v[8:11], v[156:159], v[224:227], v[8:11]
	v_mfma_f32_16x16x32_f16 v[62:65], v[152:155], v[204:207], v[62:65]
	v_mfma_f32_16x16x32_f16 v[58:61], v[160:163], v[204:207], v[58:61]
	v_mfma_f32_16x16x32_f16 v[46:49], v[152:155], v[212:215], v[46:49]
	v_mfma_f32_16x16x32_f16 v[42:45], v[160:163], v[212:215], v[42:45]
	v_mfma_f32_16x16x32_f16 v[28:31], v[152:155], v[220:223], v[28:31]
	v_mfma_f32_16x16x32_f16 v[24:27], v[160:163], v[220:223], v[24:27]
	v_mfma_f32_16x16x32_f16 v[12:15], v[152:155], v[228:231], v[12:15]
	v_mfma_f32_16x16x32_f16 v[8:11], v[160:163], v[228:231], v[8:11]
	v_mfma_f32_16x16x32_f16 v[54:57], v[164:167], v[196:199], v[54:57]
	v_mfma_f32_16x16x32_f16 v[50:53], v[172:175], v[196:199], v[50:53]
	v_mfma_f32_16x16x32_f16 v[38:41], v[164:167], v[208:211], v[38:41]
	v_mfma_f32_16x16x32_f16 v[34:37], v[172:175], v[208:211], v[34:37]
	v_mfma_f32_16x16x32_f16 v[20:23], v[164:167], v[216:219], v[20:23]
	v_mfma_f32_16x16x32_f16 v[16:19], v[172:175], v[216:219], v[16:19]
	v_mfma_f32_16x16x32_f16 v[4:7], v[164:167], v[224:227], v[4:7]
	v_mfma_f32_16x16x32_f16 v[0:3], v[172:175], v[224:227], v[0:3]
	v_mfma_f32_16x16x32_f16 v[54:57], v[168:171], v[204:207], v[54:57]
	v_mfma_f32_16x16x32_f16 v[50:53], v[176:179], v[204:207], v[50:53]
	v_mfma_f32_16x16x32_f16 v[38:41], v[168:171], v[212:215], v[38:41]
	v_mfma_f32_16x16x32_f16 v[34:37], v[176:179], v[212:215], v[34:37]
	v_mfma_f32_16x16x32_f16 v[20:23], v[168:171], v[220:223], v[20:23]
	v_mfma_f32_16x16x32_f16 v[16:19], v[176:179], v[220:223], v[16:19]
	v_mfma_f32_16x16x32_f16 v[4:7], v[168:171], v[228:231], v[4:7]
	v_mfma_f32_16x16x32_f16 v[0:3], v[176:179], v[228:231], v[0:3]
	s_setprio 2
	s_barrier
	s_add_i32 s76, 0, 0x18000
	v_add_u32_e32 v32, s76, v145
	s_add_i32 s77, 0, 0x1c000
	ds_read_b128 v[148:151], v32
	ds_read_b128 v[152:155], v32 offset:1024
	ds_read_b128 v[156:159], v32 offset:2048
	ds_read_b128 v[160:163], v32 offset:3072
	v_add_u32_e32 v32, s77, v145
	ds_read_b128 v[164:167], v32
	ds_read_b128 v[168:171], v32 offset:1024
	ds_read_b128 v[172:175], v32 offset:2048
	ds_read_b128 v[176:179], v32 offset:3072
	s_add_u32 s22, s22, 0x40000
	s_addc_u32 s23, s23, 0
	s_mov_b32 m0, s30
	v_lshl_add_u64 v[236:237], s[22:23], 0, v[136:137]
	ds_read_b128 v[196:199], v147 offset:32768
	ds_read_b128 v[204:207], v147 offset:33792
	ds_read_b128 v[208:211], v147 offset:34816
	ds_read_b128 v[212:215], v147 offset:35840
	ds_read_b128 v[216:219], v147 offset:36864
	ds_read_b128 v[220:223], v147 offset:37888
	ds_read_b128 v[224:227], v147 offset:38912
	ds_read_b128 v[228:231], v147 offset:39936
	global_load_lds_dwordx4 v[236:237], off
	v_lshl_add_u64 v[236:237], s[22:23], 0, v[132:133]
	s_mov_b32 m0, s31
	s_nop 0
	global_load_lds_dwordx4 v[236:237], off
	s_waitcnt vmcnt(8)
	s_waitcnt lgkmcnt(0)
	s_barrier
	s_setprio 0
	s_waitcnt lgkmcnt(0)
	v_mfma_f32_16x16x32_f16 v[126:129], v[148:151], v[196:199], v[126:129]
	v_mfma_f32_16x16x32_f16 v[122:125], v[156:159], v[196:199], v[122:125]
	v_mfma_f32_16x16x32_f16 v[110:113], v[148:151], v[208:211], v[110:113]
	v_mfma_f32_16x16x32_f16 v[106:109], v[156:159], v[208:211], v[106:109]
	v_mfma_f32_16x16x32_f16 v[94:97], v[148:151], v[216:219], v[94:97]
	v_mfma_f32_16x16x32_f16 v[90:93], v[156:159], v[216:219], v[90:93]
	v_mfma_f32_16x16x32_f16 v[78:81], v[148:151], v[224:227], v[78:81]
	v_mfma_f32_16x16x32_f16 v[74:77], v[156:159], v[224:227], v[74:77]
	v_mfma_f32_16x16x32_f16 v[126:129], v[152:155], v[204:207], v[126:129]
	v_mfma_f32_16x16x32_f16 v[122:125], v[160:163], v[204:207], v[122:125]
	v_mfma_f32_16x16x32_f16 v[110:113], v[152:155], v[212:215], v[110:113]
	v_mfma_f32_16x16x32_f16 v[106:109], v[160:163], v[212:215], v[106:109]
	v_mfma_f32_16x16x32_f16 v[94:97], v[152:155], v[220:223], v[94:97]
	v_mfma_f32_16x16x32_f16 v[90:93], v[160:163], v[220:223], v[90:93]
	v_mfma_f32_16x16x32_f16 v[78:81], v[152:155], v[228:231], v[78:81]
	v_mfma_f32_16x16x32_f16 v[74:77], v[160:163], v[228:231], v[74:77]
	v_mfma_f32_16x16x32_f16 v[118:121], v[164:167], v[196:199], v[118:121]
	v_mfma_f32_16x16x32_f16 v[114:117], v[172:175], v[196:199], v[114:117]
	v_mfma_f32_16x16x32_f16 v[102:105], v[164:167], v[208:211], v[102:105]
	v_mfma_f32_16x16x32_f16 v[98:101], v[172:175], v[208:211], v[98:101]
	v_mfma_f32_16x16x32_f16 v[86:89], v[164:167], v[216:219], v[86:89]
	v_mfma_f32_16x16x32_f16 v[82:85], v[172:175], v[216:219], v[82:85]
	v_mfma_f32_16x16x32_f16 v[70:73], v[164:167], v[224:227], v[70:73]
	v_mfma_f32_16x16x32_f16 v[66:69], v[172:175], v[224:227], v[66:69]
	v_mfma_f32_16x16x32_f16 v[118:121], v[168:171], v[204:207], v[118:121]
	v_mfma_f32_16x16x32_f16 v[114:117], v[176:179], v[204:207], v[114:117]
	v_mfma_f32_16x16x32_f16 v[102:105], v[168:171], v[212:215], v[102:105]
	v_mfma_f32_16x16x32_f16 v[98:101], v[176:179], v[212:215], v[98:101]
	v_mfma_f32_16x16x32_f16 v[86:89], v[168:171], v[220:223], v[86:89]
	v_mfma_f32_16x16x32_f16 v[82:85], v[176:179], v[220:223], v[82:85]
	v_mfma_f32_16x16x32_f16 v[70:73], v[168:171], v[228:231], v[70:73]
	v_mfma_f32_16x16x32_f16 v[66:69], v[176:179], v[228:231], v[66:69]
	s_setprio 2
	s_barrier
; #define PG8_STAGE(bufoff, gbase, voff) do { _Pragma("unroll") for (int _i = 0; _i < 2; ++_i) \
;         __builtin_amdgcn_global_load_lds((const unsigned*)((const char*)(gbase) + (voff)[_i]), (LAS unsigned*)(lds + (bufoff) + ldsw + _i * 8192), 16, 0, 0); } while (0)
; #define PG8_LDA(dst, b, h) do { _Pragma("unroll") for (int m = 0; m < 4; ++m) _Pragma("unroll") for (int k = 0; k < 2; ++k) dst[m][k] = *(const LAS h16x8*)(lds + PG8_SA(b, h) + aoff + m * 2048 + k * 1024); } while (0)
; #define PG8_LDB(dst, b, h) do { _Pragma("unroll") for (int n = 0; n < 2; ++n) _Pragma("unroll") for (int k = 0; k < 2; ++k) dst[n][k] = *(const LAS h16x8*)(lds + PG8_SB(b, h) + boff + n * 2048 + k * 1024); } while (0)
; #define PG8_WAIT_V(n) asm volatile("s_waitcnt vmcnt(" #n ")" ::: "memory")
; template <class Epi>
; __device__ __forceinline__ void gemm_phase(LAS unsigned char* lds, const Gemm g, const StaticOrder& S, const Epi& E) {
;     ...
;         for (int t = 0; t < nt; t += 2) {
;             const bool last = (t == nt - 2);
;             const char* a1 = cA + (size_t)(t + 1) * kstep;
;             const char* a2 = last ? nA : cA + (size_t)(t + 2) * kstep; const char* b2 = last ? nB : cB + (size_t)(t + 2) * kstep;
;             const char* a3 = a2 + kstep; const char* b3 = b2 + kstep;
;             PG8_LDB(B0, 0, 0); PG8_LDB(B1, 0, 1); PG8_SCHED; PG8_LDA(At, 0, 0); PG8_STAGE(PG8_SA(1, 1), a1 + hstepA, voffA);
;             PG8_WAIT_V(8); PG8_WAIT_L(0); PG8_BAR; PG8_MMA(0, 0, At, B0); PG8_MMA(0, 1, At, B1); PG8_BAR; PG8_SCHED;
;             PG8_LDA(At, 0, 1); PG8_STAGE(PG8_SB(0, 0), b2, voffB); PG8_STAGE(PG8_SB(0, 1), b2 + hstepB, voffB); PG8_STAGE(PG8_SA(0, 0), a2, voffA);
;             PG8_WAIT_V(8); PG8_WAIT_L(0); PG8_BAR; PG8_MMA(1, 0, At, B0); PG8_MMA(1, 1, At, B1); PG8_BAR; PG8_SCHED;
;             PG8_LDB(B0, 1, 0); PG8_LDB(B1, 1, 1); PG8_SCHED; PG8_LDA(At, 1, 0); PG8_STAGE(PG8_SA(0, 1), a2 + hstepA, voffA);
;             PG8_WAIT_V(8); PG8_WAIT_L(0); PG8_BAR; PG8_MMA(0, 0, At, B0); PG8_MMA(0, 1, At, B1); PG8_BAR; PG8_SCHED;
;             PG8_LDA(At, 1, 1); PG8_STAGE(PG8_SB(1, 0), b3, voffB); PG8_STAGE(PG8_SB(1, 1), b3 + hstepB, voffB); PG8_STAGE(PG8_SA(1, 0), a3, voffA);
;             PG8_WAIT_V(8); PG8_WAIT_L(0); PG8_BAR; PG8_MMA(1, 0, At, B0); PG8_MMA(1, 1, At, B1); PG8_BAR; PG8_SCHED;
;         }
;         if (wr == 0) PG8_BAR;
	s_add_i32 s22, s76, s24
	v_lshl_add_u64 v[180:181], v[180:181], 0, s[90:91]
	s_mov_b32 m0, s22
	ds_read_b128 v[196:199], v147 offset:49152
	ds_read_b128 v[204:207], v147 offset:50176
	ds_read_b128 v[208:211], v147 offset:51200
	ds_read_b128 v[212:215], v147 offset:52224
	ds_read_b128 v[216:219], v147 offset:53248
	ds_read_b128 v[220:223], v147 offset:54272
	ds_read_b128 v[224:227], v147 offset:55296
	ds_read_b128 v[228:231], v147 offset:56320
	global_load_lds_dwordx4 v[180:181], off
	s_add_i32 m0, s22, 0x2000
	s_add_u32 s20, s20, 0x40080
	v_lshl_add_u64 v[180:181], v[190:191], 0, s[90:91]
	s_addc_u32 s21, s21, 0
	s_add_i32 s22, s77, s24
	global_load_lds_dwordx4 v[180:181], off
	v_lshl_add_u64 v[180:181], s[20:21], 0, v[134:135]
	s_mov_b32 m0, s22
	s_nop 0
	global_load_lds_dwordx4 v[180:181], off
	v_lshl_add_u64 v[180:181], s[20:21], 0, v[130:131]
	s_add_i32 m0, s22, 0x2000
	s_nop 0
	global_load_lds_dwordx4 v[180:181], off
	v_lshl_add_u64 v[180:181], v[232:233], 0, s[90:91]
	s_mov_b32 m0, s35
	s_nop 0
	global_load_lds_dwordx4 v[180:181], off
	v_lshl_add_u64 v[180:181], v[234:235], 0, s[90:91]
	s_mov_b32 m0, s54
	s_nop 0
	global_load_lds_dwordx4 v[180:181], off
	s_waitcnt vmcnt(8)
	s_waitcnt lgkmcnt(0)
	s_barrier
	s_setprio 0
	s_waitcnt lgkmcnt(0)
	v_mfma_f32_16x16x32_f16 v[62:65], v[148:151], v[196:199], v[62:65]
	v_mfma_f32_16x16x32_f16 v[58:61], v[156:159], v[196:199], v[58:61]
	v_mfma_f32_16x16x32_f16 v[46:49], v[148:151], v[208:211], v[46:49]
	v_mfma_f32_16x16x32_f16 v[42:45], v[156:159], v[208:211], v[42:45]
	v_mfma_f32_16x16x32_f16 v[28:31], v[148:151], v[216:219], v[28:31]
	v_mfma_f32_16x16x32_f16 v[24:27], v[156:159], v[216:219], v[24:27]
	v_mfma_f32_16x16x32_f16 v[12:15], v[148:151], v[224:227], v[12:15]
	v_mfma_f32_16x16x32_f16 v[8:11], v[156:159], v[224:227], v[8:11]
	v_mfma_f32_16x16x32_f16 v[62:65], v[152:155], v[204:207], v[62:65]
	v_mfma_f32_16x16x32_f16 v[58:61], v[160:163], v[204:207], v[58:61]
	v_mfma_f32_16x16x32_f16 v[46:49], v[152:155], v[212:215], v[46:49]
	v_mfma_f32_16x16x32_f16 v[42:45], v[160:163], v[212:215], v[42:45]
	v_mfma_f32_16x16x32_f16 v[28:31], v[152:155], v[220:223], v[28:31]
	v_mfma_f32_16x16x32_f16 v[24:27], v[160:163], v[220:223], v[24:27]
	v_mfma_f32_16x16x32_f16 v[12:15], v[152:155], v[228:231], v[12:15]
	v_mfma_f32_16x16x32_f16 v[8:11], v[160:163], v[228:231], v[8:11]
	v_mfma_f32_16x16x32_f16 v[54:57], v[164:167], v[196:199], v[54:57]
	v_mfma_f32_16x16x32_f16 v[50:53], v[172:175], v[196:199], v[50:53]
	v_mfma_f32_16x16x32_f16 v[38:41], v[164:167], v[208:211], v[38:41]
	v_mfma_f32_16x16x32_f16 v[34:37], v[172:175], v[208:211], v[34:37]
	v_mfma_f32_16x16x32_f16 v[20:23], v[164:167], v[216:219], v[20:23]
	v_mfma_f32_16x16x32_f16 v[16:19], v[172:175], v[216:219], v[16:19]
	v_mfma_f32_16x16x32_f16 v[4:7], v[164:167], v[224:227], v[4:7]
	v_mfma_f32_16x16x32_f16 v[0:3], v[172:175], v[224:227], v[0:3]
	v_mfma_f32_16x16x32_f16 v[54:57], v[168:171], v[204:207], v[54:57]
	v_mfma_f32_16x16x32_f16 v[50:53], v[176:179], v[204:207], v[50:53]
	v_mfma_f32_16x16x32_f16 v[38:41], v[168:171], v[212:215], v[38:41]
	v_mfma_f32_16x16x32_f16 v[34:37], v[176:179], v[212:215], v[34:37]
	v_mfma_f32_16x16x32_f16 v[20:23], v[168:171], v[220:223], v[20:23]
	v_mfma_f32_16x16x32_f16 v[16:19], v[176:179], v[220:223], v[16:19]
	v_mfma_f32_16x16x32_f16 v[4:7], v[168:171], v[228:231], v[4:7]
	v_mfma_f32_16x16x32_f16 v[0:3], v[176:179], v[228:231], v[0:3]
	s_setprio 2
	s_barrier
	s_add_i32 s75, s75, 2
	s_add_u32 s72, s72, 0x100
	s_addc_u32 s73, s73, 0
	s_add_u32 s18, s18, 0x100
	s_addc_u32 s19, s19, 0
	s_cmp_gt_u32 s75, 13
	s_cbranch_scc0 .LBB0_214
	s_setprio 0
	s_and_b64 vcc, exec, s[6:7]
	s_cbranch_vccnz .LBB0_219
	v_lshl_add_u32 v148, s68, 8, v144
	s_cmp_gt_i32 s69, 3
	s_mov_b64 s[18:19], -1
	s_cbranch_scc1 .LBB0_220

; #define PG8_STAGE(bufoff, gbase, voff) do { _Pragma("unroll") for (int _i = 0; _i < 2; ++_i) \
;         __builtin_amdgcn_global_load_lds((const unsigned*)((const char*)(gbase) + (voff)[_i]), (LAS unsigned*)(lds + (bufoff) + ldsw + _i * 8192), 16, 0, 0); } while (0)
; #define PG8_LDA(dst, b, h) do { _Pragma("unroll") for (int m = 0; m < 4; ++m) _Pragma("unroll") for (int k = 0; k < 2; ++k) dst[m][k] = *(const LAS h16x8*)(lds + PG8_SA(b, h) + aoff + m * 2048 + k * 1024); } while (0)
; #define PG8_LDB(dst, b, h) do { _Pragma("unroll") for (int n = 0; n < 2; ++n) _Pragma("unroll") for (int k = 0; k < 2; ++k) dst[n][k] = *(const LAS h16x8*)(lds + PG8_SB(b, h) + boff + n * 2048 + k * 1024); } while (0)
; #define PG8_MMA(ai, bj, At, Bt) do { __builtin_amdgcn_s_setprio(1); _Pragma("unroll") for (int m = 0; m < 4; ++m) _Pragma("unroll") for (int n = 0; n < 2; ++n) _Pragma("unroll") for (int k = 0; k < 2; ++k) \
;         acc[ai][bj][m][n] = __builtin_amdgcn_mfma_f32_16x16x32_f16(Bt[n][k], At[m][k], acc[ai][bj][m][n], 0, 0, 0); __builtin_amdgcn_s_setprio(0); } while (0)
; #define PG8_WAIT_V(n) asm volatile("s_waitcnt vmcnt(" #n ")" ::: "memory")
; #define PG8_WAIT_L(n) asm volatile("s_waitcnt lgkmcnt(" #n ")" ::: "memory")
; #define PG8_BAR __builtin_amdgcn_s_barrier()
; #define PG8_SCHED __builtin_amdgcn_sched_barrier(0)
; template <class Epi>
; __device__ __forceinline__ void gemm_phase(LAS unsigned char* lds, const Gemm g, const StaticOrder& S, const Epi& E) {
;     ...
;             const bool last = (t == nt - 2);
;             const char* a1 = cA + (size_t)(t + 1) * kstep;
;             const char* a2 = last ? nA : cA + (size_t)(t + 2) * kstep; const char* b2 = last ? nB : cB + (size_t)(t + 2) * kstep;
;             const char* a3 = a2 + kstep; const char* b3 = b2 + kstep;
;             PG8_LDB(B0, 0, 0); PG8_LDB(B1, 0, 1); PG8_SCHED; PG8_LDA(At, 0, 0); PG8_STAGE(PG8_SA(1, 1), a1 + hstepA, voffA);
;             PG8_WAIT_V(8); PG8_WAIT_L(0); PG8_BAR; PG8_MMA(0, 0, At, B0); PG8_MMA(0, 1, At, B1); PG8_BAR; PG8_SCHED;
;             PG8_LDA(At, 0, 1); PG8_STAGE(PG8_SB(0, 0), b2, voffB); PG8_STAGE(PG8_SB(0, 1), b2 + hstepB, voffB); PG8_STAGE(PG8_SA(0, 0), a2, voffA);
.Lprio_564:
.LBB0_564:
	s_add_i32 s68, s28, 2
	s_add_u32 s69, s26, 0x80
	s_addc_u32 s29, s27, 0
	s_add_i32 vcc_lo, 0, 0x10000
	s_cmp_eq_u32 s79, s28
	s_cselect_b32 s29, s1, s29
	s_cselect_b32 s28, s0, s69
	v_add_u32_e32 v32, vcc_lo, v178
	s_cselect_b32 s71, s23, s31
	s_cselect_b32 s70, s22, s30
	s_add_i32 s69, 0, 0x14000
	ds_read_b128 v[148:151], v32
	ds_read_b128 v[152:155], v32 offset:1024
	ds_read_b128 v[156:159], v32 offset:2048
	ds_read_b128 v[160:163], v32 offset:3072
	v_add_u32_e32 v32, s69, v178
	ds_read_b128 v[164:167], v32
	ds_read_b128 v[168:171], v32 offset:1024
	ds_read_b128 v[172:175], v32 offset:2048
	ds_read_b128 v[208:211], v32 offset:3072
	v_lshl_add_u64 v[176:177], s[26:27], 0, v[146:147]
	s_add_i32 m0, s88, 0xc000
	ds_read_b128 v[212:215], v206
	ds_read_b128 v[216:219], v206 offset:1024
	ds_read_b128 v[220:223], v206 offset:2048
	ds_read_b128 v[224:227], v206 offset:3072
	ds_read_b128 v[228:231], v206 offset:4096
	ds_read_b128 v[232:235], v206 offset:5120
	ds_read_b128 v[236:239], v206 offset:6144
	ds_read_b128 v[240:243], v206 offset:7168
	global_load_lds_dwordx4 v[176:177], off
	v_lshl_add_u64 v[176:177], s[26:27], 0, v[144:145]
	s_add_i32 m0, s88, 0xe000
	s_nop 0
	global_load_lds_dwordx4 v[176:177], off
	s_waitcnt vmcnt(8)
	s_waitcnt lgkmcnt(0)
	s_barrier
	s_setprio 0
	s_waitcnt lgkmcnt(0)
	v_mfma_f32_16x16x32_f16 v[126:129], v[148:151], v[212:215], v[126:129]
	v_mfma_f32_16x16x32_f16 v[122:125], v[156:159], v[212:215], v[122:125]
	v_mfma_f32_16x16x32_f16 v[110:113], v[148:151], v[220:223], v[110:113]
	v_mfma_f32_16x16x32_f16 v[106:109], v[156:159], v[220:223], v[106:109]
	v_mfma_f32_16x16x32_f16 v[94:97], v[148:151], v[228:231], v[94:97]
	v_mfma_f32_16x16x32_f16 v[90:93], v[156:159], v[228:231], v[90:93]
	v_mfma_f32_16x16x32_f16 v[78:81], v[148:151], v[236:239], v[78:81]
	v_mfma_f32_16x16x32_f16 v[74:77], v[156:159], v[236:239], v[74:77]
	v_mfma_f32_16x16x32_f16 v[126:129], v[152:155], v[216:219], v[126:129]
	v_mfma_f32_16x16x32_f16 v[122:125], v[160:163], v[216:219], v[122:125]
	v_mfma_f32_16x16x32_f16 v[110:113], v[152:155], v[224:227], v[110:113]
	v_mfma_f32_16x16x32_f16 v[106:109], v[160:163], v[224:227], v[106:109]
	v_mfma_f32_16x16x32_f16 v[94:97], v[152:155], v[232:235], v[94:97]
	v_mfma_f32_16x16x32_f16 v[90:93], v[160:163], v[232:235], v[90:93]
	v_mfma_f32_16x16x32_f16 v[78:81], v[152:155], v[240:243], v[78:81]
	v_mfma_f32_16x16x32_f16 v[74:77], v[160:163], v[240:243], v[74:77]
	v_mfma_f32_16x16x32_f16 v[118:121], v[164:167], v[212:215], v[118:121]
	v_mfma_f32_16x16x32_f16 v[114:117], v[172:175], v[212:215], v[114:117]
	v_mfma_f32_16x16x32_f16 v[102:105], v[164:167], v[220:223], v[102:105]
	v_mfma_f32_16x16x32_f16 v[98:101], v[172:175], v[220:223], v[98:101]
	v_mfma_f32_16x16x32_f16 v[86:89], v[164:167], v[228:231], v[86:89]
	v_mfma_f32_16x16x32_f16 v[82:85], v[172:175], v[228:231], v[82:85]
	v_mfma_f32_16x16x32_f16 v[70:73], v[164:167], v[236:239], v[70:73]
	v_mfma_f32_16x16x32_f16 v[66:69], v[172:175], v[236:239], v[66:69]
	v_mfma_f32_16x16x32_f16 v[118:121], v[168:171], v[216:219], v[118:121]
	v_mfma_f32_16x16x32_f16 v[114:117], v[208:211], v[216:219], v[114:117]
	v_mfma_f32_16x16x32_f16 v[102:105], v[168:171], v[224:227], v[102:105]
	v_mfma_f32_16x16x32_f16 v[98:101], v[208:211], v[224:227], v[98:101]
	v_mfma_f32_16x16x32_f16 v[86:89], v[168:171], v[232:235], v[86:89]
	v_mfma_f32_16x16x32_f16 v[82:85], v[208:211], v[232:235], v[82:85]
	v_mfma_f32_16x16x32_f16 v[70:73], v[168:171], v[240:243], v[70:73]
	v_mfma_f32_16x16x32_f16 v[66:69], v[208:211], v[240:243], v[66:69]
	s_setprio 2
	s_barrier
	s_add_i32 vcc_lo, vcc_lo, s35
	v_lshl_add_u64 v[176:177], s[70:71], 0, v[132:133]
	s_mov_b32 m0, vcc_lo
	ds_read_b128 v[212:215], v206 offset:16384
	ds_read_b128 v[216:219], v206 offset:17408
	ds_read_b128 v[220:223], v206 offset:18432
	ds_read_b128 v[224:227], v206 offset:19456
	ds_read_b128 v[228:231], v206 offset:20480
	ds_read_b128 v[232:235], v206 offset:21504
	ds_read_b128 v[236:239], v206 offset:22528
	ds_read_b128 v[240:243], v206 offset:23552
	global_load_lds_dwordx4 v[176:177], off
	s_add_i32 m0, vcc_lo, 0x2000
	v_lshl_add_u64 v[196:197], s[70:71], 0, v[136:137]
	s_add_u32 s70, s70, s14
	s_addc_u32 s71, s71, 0
	s_add_i32 s69, s69, s35
	global_load_lds_dwordx4 v[196:197], off
	v_lshl_add_u64 v[198:199], s[70:71], 0, v[132:133]
	s_mov_b32 m0, s69
	v_lshl_add_u64 v[244:245], s[70:71], 0, v[136:137]
	global_load_lds_dwordx4 v[198:199], off
	s_add_i32 m0, s69, 0x2000
	v_lshl_add_u64 v[246:247], s[28:29], 0, v[130:131]
	global_load_lds_dwordx4 v[244:245], off
	s_mov_b32 m0, s88
	v_lshl_add_u64 v[248:249], s[28:29], 0, v[134:135]
	global_load_lds_dwordx4 v[246:247], off
	s_mov_b32 m0, s89
	s_nop 0
	global_load_lds_dwordx4 v[248:249], off
	s_waitcnt vmcnt(8)
	s_waitcnt lgkmcnt(0)
	s_barrier
; #define PG8_STAGE(bufoff, gbase, voff) do { _Pragma("unroll") for (int _i = 0; _i < 2; ++_i) \
;         __builtin_amdgcn_global_load_lds((const unsigned*)((const char*)(gbase) + (voff)[_i]), (LAS unsigned*)(lds + (bufoff) + ldsw + _i * 8192), 16, 0, 0); } while (0)
; #define PG8_LDA(dst, b, h) do { _Pragma("unroll") for (int m = 0; m < 4; ++m) _Pragma("unroll") for (int k = 0; k < 2; ++k) dst[m][k] = *(const LAS h16x8*)(lds + PG8_SA(b, h) + aoff + m * 2048 + k * 1024); } while (0)
; #define PG8_LDB(dst, b, h) do { _Pragma("unroll") for (int n = 0; n < 2; ++n) _Pragma("unroll") for (int k = 0; k < 2; ++k) dst[n][k] = *(const LAS h16x8*)(lds + PG8_SB(b, h) + boff + n * 2048 + k * 1024); } while (0)
; #define PG8_MMA(ai, bj, At, Bt) do { __builtin_amdgcn_s_setprio(1); _Pragma("unroll") for (int m = 0; m < 4; ++m) _Pragma("unroll") for (int n = 0; n < 2; ++n) _Pragma("unroll") for (int k = 0; k < 2; ++k) \
;         acc[ai][bj][m][n] = __builtin_amdgcn_mfma_f32_16x16x32_f16(Bt[n][k], At[m][k], acc[ai][bj][m][n], 0, 0, 0); __builtin_amdgcn_s_setprio(0); } while (0)
; #define PG8_WAIT_V(n) asm volatile("s_waitcnt vmcnt(" #n ")" ::: "memory")
; #define PG8_WAIT_L(n) asm volatile("s_waitcnt lgkmcnt(" #n ")" ::: "memory")
; #define PG8_BAR __builtin_amdgcn_s_barrier()
; #define PG8_SCHED __builtin_amdgcn_sched_barrier(0)
; template <class Epi>
; __device__ __forceinline__ void gemm_phase(LAS unsigned char* lds, const Gemm g, const StaticOrder& S, const Epi& E) {
;     ...
;             PG8_WAIT_V(8); PG8_WAIT_L(0); PG8_BAR; PG8_MMA(1, 0, At, B0); PG8_MMA(1, 1, At, B1); PG8_BAR; PG8_SCHED;
;             PG8_LDB(B0, 1, 0); PG8_LDB(B1, 1, 1); PG8_SCHED; PG8_LDA(At, 1, 0); PG8_STAGE(PG8_SA(0, 1), a2 + hstepA, voffA);
;             PG8_WAIT_V(8); PG8_WAIT_L(0); PG8_BAR; PG8_MMA(0, 0, At, B0); PG8_MMA(0, 1, At, B1); PG8_BAR; PG8_SCHED;
	s_setprio 0
	s_waitcnt lgkmcnt(0)
	v_mfma_f32_16x16x32_f16 v[62:65], v[148:151], v[212:215], v[62:65]
	v_mfma_f32_16x16x32_f16 v[58:61], v[156:159], v[212:215], v[58:61]
	v_mfma_f32_16x16x32_f16 v[46:49], v[148:151], v[220:223], v[46:49]
	v_mfma_f32_16x16x32_f16 v[42:45], v[156:159], v[220:223], v[42:45]
	v_mfma_f32_16x16x32_f16 v[28:31], v[148:151], v[228:231], v[28:31]
	v_mfma_f32_16x16x32_f16 v[24:27], v[156:159], v[228:231], v[24:27]
	v_mfma_f32_16x16x32_f16 v[12:15], v[148:151], v[236:239], v[12:15]
	v_mfma_f32_16x16x32_f16 v[8:11], v[156:159], v[236:239], v[8:11]
	v_mfma_f32_16x16x32_f16 v[62:65], v[152:155], v[216:219], v[62:65]
	v_mfma_f32_16x16x32_f16 v[58:61], v[160:163], v[216:219], v[58:61]
	v_mfma_f32_16x16x32_f16 v[46:49], v[152:155], v[224:227], v[46:49]
	v_mfma_f32_16x16x32_f16 v[42:45], v[160:163], v[224:227], v[42:45]
	v_mfma_f32_16x16x32_f16 v[28:31], v[152:155], v[232:235], v[28:31]
	v_mfma_f32_16x16x32_f16 v[24:27], v[160:163], v[232:235], v[24:27]
	v_mfma_f32_16x16x32_f16 v[12:15], v[152:155], v[240:243], v[12:15]
	v_mfma_f32_16x16x32_f16 v[8:11], v[160:163], v[240:243], v[8:11]
	v_mfma_f32_16x16x32_f16 v[54:57], v[164:167], v[212:215], v[54:57]
	v_mfma_f32_16x16x32_f16 v[50:53], v[172:175], v[212:215], v[50:53]
	v_mfma_f32_16x16x32_f16 v[38:41], v[164:167], v[220:223], v[38:41]
	v_mfma_f32_16x16x32_f16 v[34:37], v[172:175], v[220:223], v[34:37]
	v_mfma_f32_16x16x32_f16 v[20:23], v[164:167], v[228:231], v[20:23]
	v_mfma_f32_16x16x32_f16 v[16:19], v[172:175], v[228:231], v[16:19]
	v_mfma_f32_16x16x32_f16 v[4:7], v[164:167], v[236:239], v[4:7]
	v_mfma_f32_16x16x32_f16 v[0:3], v[172:175], v[236:239], v[0:3]
	v_mfma_f32_16x16x32_f16 v[54:57], v[168:171], v[216:219], v[54:57]
	v_mfma_f32_16x16x32_f16 v[50:53], v[208:211], v[216:219], v[50:53]
	v_mfma_f32_16x16x32_f16 v[38:41], v[168:171], v[224:227], v[38:41]
	v_mfma_f32_16x16x32_f16 v[34:37], v[208:211], v[224:227], v[34:37]
	v_mfma_f32_16x16x32_f16 v[20:23], v[168:171], v[232:235], v[20:23]
	v_mfma_f32_16x16x32_f16 v[16:19], v[208:211], v[232:235], v[16:19]
	v_mfma_f32_16x16x32_f16 v[4:7], v[168:171], v[240:243], v[4:7]
	v_mfma_f32_16x16x32_f16 v[0:3], v[208:211], v[240:243], v[0:3]
	s_setprio 2
	s_barrier
	s_add_i32 s69, 0, 0x18000
	v_add_u32_e32 v32, s69, v178
	s_add_i32 s70, 0, 0x1c000
	ds_read_b128 v[148:151], v32
	ds_read_b128 v[152:155], v32 offset:1024
	ds_read_b128 v[156:159], v32 offset:2048
	ds_read_b128 v[160:163], v32 offset:3072
	v_add_u32_e32 v32, s70, v178
	ds_read_b128 v[164:167], v32
	ds_read_b128 v[168:171], v32 offset:1024
	ds_read_b128 v[172:175], v32 offset:2048
	ds_read_b128 v[208:211], v32 offset:3072
	s_add_u32 s28, s28, s14
	s_addc_u32 s29, s29, 0
	s_mov_b32 m0, s92
	v_lshl_add_u64 v[250:251], s[28:29], 0, v[130:131]
	ds_read_b128 v[212:215], v206 offset:32768
	ds_read_b128 v[216:219], v206 offset:33792
	ds_read_b128 v[220:223], v206 offset:34816
	ds_read_b128 v[224:227], v206 offset:35840
	ds_read_b128 v[228:231], v206 offset:36864
	ds_read_b128 v[232:235], v206 offset:37888
	ds_read_b128 v[236:239], v206 offset:38912
	ds_read_b128 v[240:243], v206 offset:39936
	global_load_lds_dwordx4 v[250:251], off
	v_lshl_add_u64 v[250:251], s[28:29], 0, v[134:135]
	s_mov_b32 m0, s93
	s_nop 0
	global_load_lds_dwordx4 v[250:251], off
	s_waitcnt vmcnt(8)
	s_waitcnt lgkmcnt(0)
	s_barrier
	s_setprio 0
	s_waitcnt lgkmcnt(0)
	v_mfma_f32_16x16x32_f16 v[126:129], v[148:151], v[212:215], v[126:129]
	v_mfma_f32_16x16x32_f16 v[122:125], v[156:159], v[212:215], v[122:125]
	v_mfma_f32_16x16x32_f16 v[110:113], v[148:151], v[220:223], v[110:113]
	v_mfma_f32_16x16x32_f16 v[106:109], v[156:159], v[220:223], v[106:109]
	v_mfma_f32_16x16x32_f16 v[94:97], v[148:151], v[228:231], v[94:97]
	v_mfma_f32_16x16x32_f16 v[90:93], v[156:159], v[228:231], v[90:93]
	v_mfma_f32_16x16x32_f16 v[78:81], v[148:151], v[236:239], v[78:81]
	v_mfma_f32_16x16x32_f16 v[74:77], v[156:159], v[236:239], v[74:77]
	v_mfma_f32_16x16x32_f16 v[126:129], v[152:155], v[216:219], v[126:129]
	v_mfma_f32_16x16x32_f16 v[122:125], v[160:163], v[216:219], v[122:125]
	v_mfma_f32_16x16x32_f16 v[110:113], v[152:155], v[224:227], v[110:113]
	v_mfma_f32_16x16x32_f16 v[106:109], v[160:163], v[224:227], v[106:109]
	v_mfma_f32_16x16x32_f16 v[94:97], v[152:155], v[232:235], v[94:97]
	v_mfma_f32_16x16x32_f16 v[90:93], v[160:163], v[232:235], v[90:93]
	v_mfma_f32_16x16x32_f16 v[78:81], v[152:155], v[240:243], v[78:81]
	v_mfma_f32_16x16x32_f16 v[74:77], v[160:163], v[240:243], v[74:77]
	v_mfma_f32_16x16x32_f16 v[118:121], v[164:167], v[212:215], v[118:121]
	v_mfma_f32_16x16x32_f16 v[114:117], v[172:175], v[212:215], v[114:117]
	v_mfma_f32_16x16x32_f16 v[102:105], v[164:167], v[220:223], v[102:105]
	v_mfma_f32_16x16x32_f16 v[98:101], v[172:175], v[220:223], v[98:101]
	v_mfma_f32_16x16x32_f16 v[86:89], v[164:167], v[228:231], v[86:89]
	v_mfma_f32_16x16x32_f16 v[82:85], v[172:175], v[228:231], v[82:85]
	v_mfma_f32_16x16x32_f16 v[70:73], v[164:167], v[236:239], v[70:73]
	v_mfma_f32_16x16x32_f16 v[66:69], v[172:175], v[236:239], v[66:69]
	v_mfma_f32_16x16x32_f16 v[118:121], v[168:171], v[216:219], v[118:121]
	v_mfma_f32_16x16x32_f16 v[114:117], v[208:211], v[216:219], v[114:117]
	v_mfma_f32_16x16x32_f16 v[102:105], v[168:171], v[224:227], v[102:105]
	v_mfma_f32_16x16x32_f16 v[98:101], v[208:211], v[224:227], v[98:101]
	v_mfma_f32_16x16x32_f16 v[86:89], v[168:171], v[232:235], v[86:89]
	v_mfma_f32_16x16x32_f16 v[82:85], v[208:211], v[232:235], v[82:85]
	v_mfma_f32_16x16x32_f16 v[70:73], v[168:171], v[240:243], v[70:73]
	v_mfma_f32_16x16x32_f16 v[66:69], v[208:211], v[240:243], v[66:69]
	s_setprio 2
	s_barrier
; #define PG8_STAGE(bufoff, gbase, voff) do { _Pragma("unroll") for (int _i = 0; _i < 2; ++_i) \
;         __builtin_amdgcn_global_load_lds((const unsigned*)((const char*)(gbase) + (voff)[_i]), (LAS unsigned*)(lds + (bufoff) + ldsw + _i * 8192), 16, 0, 0); } while (0)
; #define PG8_LDA(dst, b, h) do { _Pragma("unroll") for (int m = 0; m < 4; ++m) _Pragma("unroll") for (int k = 0; k < 2; ++k) dst[m][k] = *(const LAS h16x8*)(lds + PG8_SA(b, h) + aoff + m * 2048 + k * 1024); } while (0)
; #define PG8_LDB(dst, b, h) do { _Pragma("unroll") for (int n = 0; n < 2; ++n) _Pragma("unroll") for (int k = 0; k < 2; ++k) dst[n][k] = *(const LAS h16x8*)(lds + PG8_SB(b, h) + boff + n * 2048 + k * 1024); } while (0)
; #define PG8_WAIT_V(n) asm volatile("s_waitcnt vmcnt(" #n ")" ::: "memory")
; template <class Epi>
; __device__ __forceinline__ void gemm_phase(LAS unsigned char* lds, const Gemm g, const StaticOrder& S, const Epi& E) {
;     ...
;         for (int t = 0; t < nt; t += 2) {
;             const bool last = (t == nt - 2);
;             const char* a1 = cA + (size_t)(t + 1) * kstep;
;             const char* a2 = last ? nA : cA + (size_t)(t + 2) * kstep; const char* b2 = last ? nB : cB + (size_t)(t + 2) * kstep;
;             const char* a3 = a2 + kstep; const char* b3 = b2 + kstep;
;             PG8_LDB(B0, 0, 0); PG8_LDB(B1, 0, 1); PG8_SCHED; PG8_LDA(At, 0, 0); PG8_STAGE(PG8_SA(1, 1), a1 + hstepA, voffA);
;             PG8_WAIT_V(8); PG8_WAIT_L(0); PG8_BAR; PG8_MMA(0, 0, At, B0); PG8_MMA(0, 1, At, B1); PG8_BAR; PG8_SCHED;
;             PG8_LDA(At, 0, 1); PG8_STAGE(PG8_SB(0, 0), b2, voffB); PG8_STAGE(PG8_SB(0, 1), b2 + hstepB, voffB); PG8_STAGE(PG8_SA(0, 0), a2, voffA);
;             PG8_WAIT_V(8); PG8_WAIT_L(0); PG8_BAR; PG8_MMA(1, 0, At, B0); PG8_MMA(1, 1, At, B1); PG8_BAR; PG8_SCHED;
;             PG8_LDB(B0, 1, 0); PG8_LDB(B1, 1, 1); PG8_SCHED; PG8_LDA(At, 1, 0); PG8_STAGE(PG8_SA(0, 1), a2 + hstepA, voffA);
;             PG8_WAIT_V(8); PG8_WAIT_L(0); PG8_BAR; PG8_MMA(0, 0, At, B0); PG8_MMA(0, 1, At, B1); PG8_BAR; PG8_SCHED;
;             PG8_LDA(At, 1, 1); PG8_STAGE(PG8_SB(1, 0), b3, voffB); PG8_STAGE(PG8_SB(1, 1), b3 + hstepB, voffB); PG8_STAGE(PG8_SA(1, 0), a3, voffA);
;             PG8_WAIT_V(8); PG8_WAIT_L(0); PG8_BAR; PG8_MMA(1, 0, At, B0); PG8_MMA(1, 1, At, B1); PG8_BAR; PG8_SCHED;
;         }
;         if (wr == 0) PG8_BAR;
	s_add_i32 s28, s69, s35
	v_lshl_add_u64 v[176:177], v[176:177], 0, s[90:91]
	s_mov_b32 m0, s28
	ds_read_b128 v[212:215], v206 offset:49152
	ds_read_b128 v[216:219], v206 offset:50176
	ds_read_b128 v[220:223], v206 offset:51200
	ds_read_b128 v[224:227], v206 offset:52224
	ds_read_b128 v[228:231], v206 offset:53248
	ds_read_b128 v[232:235], v206 offset:54272
	ds_read_b128 v[236:239], v206 offset:55296
	ds_read_b128 v[240:243], v206 offset:56320
	global_load_lds_dwordx4 v[176:177], off
	v_lshl_add_u64 v[176:177], v[196:197], 0, s[90:91]
	s_add_i32 m0, s28, 0x2000
	s_add_i32 s28, s70, s35
	global_load_lds_dwordx4 v[176:177], off
	v_lshl_add_u64 v[176:177], v[198:199], 0, s[90:91]
	s_mov_b32 m0, s28
	s_nop 0
	global_load_lds_dwordx4 v[176:177], off
	v_lshl_add_u64 v[176:177], v[244:245], 0, s[90:91]
	s_add_i32 m0, s28, 0x2000
	s_nop 0
	global_load_lds_dwordx4 v[176:177], off
	v_lshl_add_u64 v[176:177], v[246:247], 0, s[90:91]
	s_mov_b32 m0, s75
	s_nop 0
	global_load_lds_dwordx4 v[176:177], off
	v_lshl_add_u64 v[176:177], v[248:249], 0, s[90:91]
	s_mov_b32 m0, s81
	s_nop 0
	global_load_lds_dwordx4 v[176:177], off
	s_waitcnt vmcnt(8)
	s_waitcnt lgkmcnt(0)
	s_barrier
	s_setprio 0
	s_waitcnt lgkmcnt(0)
	v_mfma_f32_16x16x32_f16 v[62:65], v[148:151], v[212:215], v[62:65]
	v_mfma_f32_16x16x32_f16 v[58:61], v[156:159], v[212:215], v[58:61]
	v_mfma_f32_16x16x32_f16 v[46:49], v[148:151], v[220:223], v[46:49]
	v_mfma_f32_16x16x32_f16 v[42:45], v[156:159], v[220:223], v[42:45]
	v_mfma_f32_16x16x32_f16 v[28:31], v[148:151], v[228:231], v[28:31]
	v_mfma_f32_16x16x32_f16 v[24:27], v[156:159], v[228:231], v[24:27]
	v_mfma_f32_16x16x32_f16 v[12:15], v[148:151], v[236:239], v[12:15]
	v_mfma_f32_16x16x32_f16 v[8:11], v[156:159], v[236:239], v[8:11]
	v_mfma_f32_16x16x32_f16 v[62:65], v[152:155], v[216:219], v[62:65]
	v_mfma_f32_16x16x32_f16 v[58:61], v[160:163], v[216:219], v[58:61]
	v_mfma_f32_16x16x32_f16 v[46:49], v[152:155], v[224:227], v[46:49]
	v_mfma_f32_16x16x32_f16 v[42:45], v[160:163], v[224:227], v[42:45]
	v_mfma_f32_16x16x32_f16 v[28:31], v[152:155], v[232:235], v[28:31]
	v_mfma_f32_16x16x32_f16 v[24:27], v[160:163], v[232:235], v[24:27]
	v_mfma_f32_16x16x32_f16 v[12:15], v[152:155], v[240:243], v[12:15]
	v_mfma_f32_16x16x32_f16 v[8:11], v[160:163], v[240:243], v[8:11]
	v_mfma_f32_16x16x32_f16 v[54:57], v[164:167], v[212:215], v[54:57]
	v_mfma_f32_16x16x32_f16 v[50:53], v[172:175], v[212:215], v[50:53]
	v_mfma_f32_16x16x32_f16 v[38:41], v[164:167], v[220:223], v[38:41]
	v_mfma_f32_16x16x32_f16 v[34:37], v[172:175], v[220:223], v[34:37]
	v_mfma_f32_16x16x32_f16 v[20:23], v[164:167], v[228:231], v[20:23]
	v_mfma_f32_16x16x32_f16 v[16:19], v[172:175], v[228:231], v[16:19]
	v_mfma_f32_16x16x32_f16 v[4:7], v[164:167], v[236:239], v[4:7]
	v_mfma_f32_16x16x32_f16 v[0:3], v[172:175], v[236:239], v[0:3]
	v_mfma_f32_16x16x32_f16 v[54:57], v[168:171], v[216:219], v[54:57]
	v_mfma_f32_16x16x32_f16 v[50:53], v[208:211], v[216:219], v[50:53]
	v_mfma_f32_16x16x32_f16 v[38:41], v[168:171], v[224:227], v[38:41]
	v_mfma_f32_16x16x32_f16 v[34:37], v[208:211], v[224:227], v[34:37]
	v_mfma_f32_16x16x32_f16 v[20:23], v[168:171], v[232:235], v[20:23]
	v_mfma_f32_16x16x32_f16 v[16:19], v[208:211], v[232:235], v[16:19]
	v_mfma_f32_16x16x32_f16 v[4:7], v[168:171], v[240:243], v[4:7]
	v_mfma_f32_16x16x32_f16 v[0:3], v[208:211], v[240:243], v[0:3]
	s_setprio 2
	s_barrier
	s_add_u32 s30, s30, 0x100
	s_addc_u32 s31, s31, 0
	s_add_u32 s26, s26, 0x100
	s_addc_u32 s27, s27, 0
	s_cmp_ge_u32 s68, s80
	s_mov_b32 s28, s68
	s_cbranch_scc0 .LBB0_564
	s_setprio 0
	s_and_b64 vcc, exec, s[20:21]
	s_cbranch_vccz .LBB0_567
	s_barrier

; #define PG8_STAGE(bufoff, gbase, voff) do { _Pragma("unroll") for (int _i = 0; _i < 2; ++_i) \
;         __builtin_amdgcn_global_load_lds((const unsigned*)((const char*)(gbase) + (voff)[_i]), (LAS unsigned*)(lds + (bufoff) + ldsw + _i * 8192), 16, 0, 0); } while (0)
; #define PG8_LDA(dst, b, h) do { _Pragma("unroll") for (int m = 0; m < 4; ++m) _Pragma("unroll") for (int k = 0; k < 2; ++k) dst[m][k] = *(const LAS h16x8*)(lds + PG8_SA(b, h) + aoff + m * 2048 + k * 1024); } while (0)
; #define PG8_LDB(dst, b, h) do { _Pragma("unroll") for (int n = 0; n < 2; ++n) _Pragma("unroll") for (int k = 0; k < 2; ++k) dst[n][k] = *(const LAS h16x8*)(lds + PG8_SB(b, h) + boff + n * 2048 + k * 1024); } while (0)
; #define PG8_MMA(ai, bj, At, Bt) do { __builtin_amdgcn_s_setprio(1); _Pragma("unroll") for (int m = 0; m < 4; ++m) _Pragma("unroll") for (int n = 0; n < 2; ++n) _Pragma("unroll") for (int k = 0; k < 2; ++k) \
;         acc[ai][bj][m][n] = __builtin_amdgcn_mfma_f32_16x16x32_f16(Bt[n][k], At[m][k], acc[ai][bj][m][n], 0, 0, 0); __builtin_amdgcn_s_setprio(0); } while (0)
; #define PG8_WAIT_V(n) asm volatile("s_waitcnt vmcnt(" #n ")" ::: "memory")
; #define PG8_WAIT_L(n) asm volatile("s_waitcnt lgkmcnt(" #n ")" ::: "memory")
; #define PG8_BAR __builtin_amdgcn_s_barrier()
; #define PG8_SCHED __builtin_amdgcn_sched_barrier(0)
; template <class Epi>
; __device__ __forceinline__ void gemm_phase(LAS unsigned char* lds, const Gemm g, const StaticOrder& S, const Epi& E) {
;     ...
;             const bool last = (t == nt - 2);
;             const char* a1 = cA + (size_t)(t + 1) * kstep;
;             const char* a2 = last ? nA : cA + (size_t)(t + 2) * kstep; const char* b2 = last ? nB : cB + (size_t)(t + 2) * kstep;
;             const char* a3 = a2 + kstep; const char* b3 = b2 + kstep;
;             PG8_LDB(B0, 0, 0); PG8_LDB(B1, 0, 1); PG8_SCHED; PG8_LDA(At, 0, 0); PG8_STAGE(PG8_SA(1, 1), a1 + hstepA, voffA);
;             PG8_WAIT_V(8); PG8_WAIT_L(0); PG8_BAR; PG8_MMA(0, 0, At, B0); PG8_MMA(0, 1, At, B1); PG8_BAR; PG8_SCHED;
;             PG8_LDA(At, 0, 1); PG8_STAGE(PG8_SB(0, 0), b2, voffB); PG8_STAGE(PG8_SB(0, 1), b2 + hstepB, voffB); PG8_STAGE(PG8_SA(0, 0), a2, voffA);
.Lprio_631:
.LBB0_631:
	s_add_i32 s30, s26, 2
	s_add_u32 s31, s22, 0x80
	s_addc_u32 s27, s23, 0
	s_add_i32 vcc_lo, 0, 0x10000
	s_cmp_eq_u32 s76, s26
	s_cselect_b32 s27, s1, s27
	s_cselect_b32 s26, s0, s31
	v_add_u32_e32 v32, vcc_lo, v174
	s_cselect_b32 s69, s21, s29
	s_cselect_b32 s68, s20, s28
	s_add_i32 s31, 0, 0x14000
	ds_read_b128 v[144:147], v32
	ds_read_b128 v[148:151], v32 offset:1024
	ds_read_b128 v[152:155], v32 offset:2048
	ds_read_b128 v[156:159], v32 offset:3072
	v_add_u32_e32 v32, s31, v174
	ds_read_b128 v[160:163], v32
	ds_read_b128 v[164:167], v32 offset:1024
	ds_read_b128 v[168:171], v32 offset:2048
	ds_read_b128 v[204:207], v32 offset:3072
	v_lshl_add_u64 v[172:173], s[22:23], 0, v[142:143]
	s_add_i32 m0, s54, 0xc000
	ds_read_b128 v[208:211], v190
	ds_read_b128 v[212:215], v190 offset:1024
	ds_read_b128 v[216:219], v190 offset:2048
	ds_read_b128 v[220:223], v190 offset:3072
	ds_read_b128 v[224:227], v190 offset:4096
	ds_read_b128 v[228:231], v190 offset:5120
	ds_read_b128 v[232:235], v190 offset:6144
	ds_read_b128 v[236:239], v190 offset:7168
	global_load_lds_dwordx4 v[172:173], off
	v_lshl_add_u64 v[172:173], s[22:23], 0, v[140:141]
	s_add_i32 m0, s54, 0xe000
	s_nop 0
	global_load_lds_dwordx4 v[172:173], off
	s_waitcnt vmcnt(8)
	s_waitcnt lgkmcnt(0)
	s_barrier
	s_setprio 0
	s_waitcnt lgkmcnt(0)
	v_mfma_f32_16x16x32_f16 v[126:129], v[144:147], v[208:211], v[126:129]
	v_mfma_f32_16x16x32_f16 v[122:125], v[152:155], v[208:211], v[122:125]
	v_mfma_f32_16x16x32_f16 v[110:113], v[144:147], v[216:219], v[110:113]
	v_mfma_f32_16x16x32_f16 v[106:109], v[152:155], v[216:219], v[106:109]
	v_mfma_f32_16x16x32_f16 v[94:97], v[144:147], v[224:227], v[94:97]
	v_mfma_f32_16x16x32_f16 v[90:93], v[152:155], v[224:227], v[90:93]
	v_mfma_f32_16x16x32_f16 v[78:81], v[144:147], v[232:235], v[78:81]
	v_mfma_f32_16x16x32_f16 v[74:77], v[152:155], v[232:235], v[74:77]
	v_mfma_f32_16x16x32_f16 v[126:129], v[148:151], v[212:215], v[126:129]
	v_mfma_f32_16x16x32_f16 v[122:125], v[156:159], v[212:215], v[122:125]
	v_mfma_f32_16x16x32_f16 v[110:113], v[148:151], v[220:223], v[110:113]
	v_mfma_f32_16x16x32_f16 v[106:109], v[156:159], v[220:223], v[106:109]
	v_mfma_f32_16x16x32_f16 v[94:97], v[148:151], v[228:231], v[94:97]
	v_mfma_f32_16x16x32_f16 v[90:93], v[156:159], v[228:231], v[90:93]
	v_mfma_f32_16x16x32_f16 v[78:81], v[148:151], v[236:239], v[78:81]
	v_mfma_f32_16x16x32_f16 v[74:77], v[156:159], v[236:239], v[74:77]
	v_mfma_f32_16x16x32_f16 v[118:121], v[160:163], v[208:211], v[118:121]
	v_mfma_f32_16x16x32_f16 v[114:117], v[168:171], v[208:211], v[114:117]
	v_mfma_f32_16x16x32_f16 v[102:105], v[160:163], v[216:219], v[102:105]
	v_mfma_f32_16x16x32_f16 v[98:101], v[168:171], v[216:219], v[98:101]
	v_mfma_f32_16x16x32_f16 v[86:89], v[160:163], v[224:227], v[86:89]
	v_mfma_f32_16x16x32_f16 v[82:85], v[168:171], v[224:227], v[82:85]
	v_mfma_f32_16x16x32_f16 v[70:73], v[160:163], v[232:235], v[70:73]
	v_mfma_f32_16x16x32_f16 v[66:69], v[168:171], v[232:235], v[66:69]
	v_mfma_f32_16x16x32_f16 v[118:121], v[164:167], v[212:215], v[118:121]
	v_mfma_f32_16x16x32_f16 v[114:117], v[204:207], v[212:215], v[114:117]
	v_mfma_f32_16x16x32_f16 v[102:105], v[164:167], v[220:223], v[102:105]
	v_mfma_f32_16x16x32_f16 v[98:101], v[204:207], v[220:223], v[98:101]
	v_mfma_f32_16x16x32_f16 v[86:89], v[164:167], v[228:231], v[86:89]
	v_mfma_f32_16x16x32_f16 v[82:85], v[204:207], v[228:231], v[82:85]
	v_mfma_f32_16x16x32_f16 v[70:73], v[164:167], v[236:239], v[70:73]
	v_mfma_f32_16x16x32_f16 v[66:69], v[204:207], v[236:239], v[66:69]
	s_setprio 2
	s_barrier
	s_add_i32 vcc_lo, vcc_lo, s35
	v_lshl_add_u64 v[172:173], s[68:69], 0, v[132:133]
	s_mov_b32 m0, vcc_lo
	ds_read_b128 v[208:211], v190 offset:16384
	ds_read_b128 v[212:215], v190 offset:17408
	ds_read_b128 v[216:219], v190 offset:18432
	ds_read_b128 v[220:223], v190 offset:19456
	ds_read_b128 v[224:227], v190 offset:20480
	ds_read_b128 v[228:231], v190 offset:21504
	ds_read_b128 v[232:235], v190 offset:22528
	ds_read_b128 v[236:239], v190 offset:23552
	global_load_lds_dwordx4 v[172:173], off
	s_add_i32 m0, vcc_lo, 0x2000
	v_lshl_add_u64 v[196:197], s[68:69], 0, v[136:137]
	s_add_u32 s68, s68, s14
	s_addc_u32 s69, s69, 0
	s_add_i32 s31, s31, s35
	global_load_lds_dwordx4 v[196:197], off
	v_lshl_add_u64 v[198:199], s[68:69], 0, v[132:133]
	s_mov_b32 m0, s31
	v_lshl_add_u64 v[240:241], s[68:69], 0, v[136:137]
	global_load_lds_dwordx4 v[198:199], off
	s_add_i32 m0, s31, 0x2000
	v_lshl_add_u64 v[242:243], s[26:27], 0, v[130:131]
	global_load_lds_dwordx4 v[240:241], off
	s_mov_b32 m0, s54
	v_lshl_add_u64 v[244:245], s[26:27], 0, v[134:135]
	global_load_lds_dwordx4 v[242:243], off
	s_mov_b32 m0, s55
	s_nop 0
	global_load_lds_dwordx4 v[244:245], off
	s_waitcnt vmcnt(8)
	s_waitcnt lgkmcnt(0)
	s_barrier
; #define PG8_STAGE(bufoff, gbase, voff) do { _Pragma("unroll") for (int _i = 0; _i < 2; ++_i) \
;         __builtin_amdgcn_global_load_lds((const unsigned*)((const char*)(gbase) + (voff)[_i]), (LAS unsigned*)(lds + (bufoff) + ldsw + _i * 8192), 16, 0, 0); } while (0)
; #define PG8_LDA(dst, b, h) do { _Pragma("unroll") for (int m = 0; m < 4; ++m) _Pragma("unroll") for (int k = 0; k < 2; ++k) dst[m][k] = *(const LAS h16x8*)(lds + PG8_SA(b, h) + aoff + m * 2048 + k * 1024); } while (0)
; #define PG8_LDB(dst, b, h) do { _Pragma("unroll") for (int n = 0; n < 2; ++n) _Pragma("unroll") for (int k = 0; k < 2; ++k) dst[n][k] = *(const LAS h16x8*)(lds + PG8_SB(b, h) + boff + n * 2048 + k * 1024); } while (0)
; #define PG8_MMA(ai, bj, At, Bt) do { __builtin_amdgcn_s_setprio(1); _Pragma("unroll") for (int m = 0; m < 4; ++m) _Pragma("unroll") for (int n = 0; n < 2; ++n) _Pragma("unroll") for (int k = 0; k < 2; ++k) \
;         acc[ai][bj][m][n] = __builtin_amdgcn_mfma_f32_16x16x32_f16(Bt[n][k], At[m][k], acc[ai][bj][m][n], 0, 0, 0); __builtin_amdgcn_s_setprio(0); } while (0)
; #define PG8_WAIT_V(n) asm volatile("s_waitcnt vmcnt(" #n ")" ::: "memory")
; #define PG8_WAIT_L(n) asm volatile("s_waitcnt lgkmcnt(" #n ")" ::: "memory")
; #define PG8_BAR __builtin_amdgcn_s_barrier()
; #define PG8_SCHED __builtin_amdgcn_sched_barrier(0)
; template <class Epi>
; __device__ __forceinline__ void gemm_phase(LAS unsigned char* lds, const Gemm g, const StaticOrder& S, const Epi& E) {
;     ...
;             PG8_WAIT_V(8); PG8_WAIT_L(0); PG8_BAR; PG8_MMA(1, 0, At, B0); PG8_MMA(1, 1, At, B1); PG8_BAR; PG8_SCHED;
;             PG8_LDB(B0, 1, 0); PG8_LDB(B1, 1, 1); PG8_SCHED; PG8_LDA(At, 1, 0); PG8_STAGE(PG8_SA(0, 1), a2 + hstepA, voffA);
;             PG8_WAIT_V(8); PG8_WAIT_L(0); PG8_BAR; PG8_MMA(0, 0, At, B0); PG8_MMA(0, 1, At, B1); PG8_BAR; PG8_SCHED;
	s_setprio 0
	s_waitcnt lgkmcnt(0)
	v_mfma_f32_16x16x32_f16 v[62:65], v[144:147], v[208:211], v[62:65]
	v_mfma_f32_16x16x32_f16 v[58:61], v[152:155], v[208:211], v[58:61]
	v_mfma_f32_16x16x32_f16 v[46:49], v[144:147], v[216:219], v[46:49]
	v_mfma_f32_16x16x32_f16 v[42:45], v[152:155], v[216:219], v[42:45]
	v_mfma_f32_16x16x32_f16 v[28:31], v[144:147], v[224:227], v[28:31]
	v_mfma_f32_16x16x32_f16 v[24:27], v[152:155], v[224:227], v[24:27]
	v_mfma_f32_16x16x32_f16 v[12:15], v[144:147], v[232:235], v[12:15]
	v_mfma_f32_16x16x32_f16 v[8:11], v[152:155], v[232:235], v[8:11]
	v_mfma_f32_16x16x32_f16 v[62:65], v[148:151], v[212:215], v[62:65]
	v_mfma_f32_16x16x32_f16 v[58:61], v[156:159], v[212:215], v[58:61]
	v_mfma_f32_16x16x32_f16 v[46:49], v[148:151], v[220:223], v[46:49]
	v_mfma_f32_16x16x32_f16 v[42:45], v[156:159], v[220:223], v[42:45]
	v_mfma_f32_16x16x32_f16 v[28:31], v[148:151], v[228:231], v[28:31]
	v_mfma_f32_16x16x32_f16 v[24:27], v[156:159], v[228:231], v[24:27]
	v_mfma_f32_16x16x32_f16 v[12:15], v[148:151], v[236:239], v[12:15]
	v_mfma_f32_16x16x32_f16 v[8:11], v[156:159], v[236:239], v[8:11]
	v_mfma_f32_16x16x32_f16 v[54:57], v[160:163], v[208:211], v[54:57]
	v_mfma_f32_16x16x32_f16 v[50:53], v[168:171], v[208:211], v[50:53]
	v_mfma_f32_16x16x32_f16 v[38:41], v[160:163], v[216:219], v[38:41]
	v_mfma_f32_16x16x32_f16 v[34:37], v[168:171], v[216:219], v[34:37]
	v_mfma_f32_16x16x32_f16 v[20:23], v[160:163], v[224:227], v[20:23]
	v_mfma_f32_16x16x32_f16 v[16:19], v[168:171], v[224:227], v[16:19]
	v_mfma_f32_16x16x32_f16 v[4:7], v[160:163], v[232:235], v[4:7]
	v_mfma_f32_16x16x32_f16 v[0:3], v[168:171], v[232:235], v[0:3]
	v_mfma_f32_16x16x32_f16 v[54:57], v[164:167], v[212:215], v[54:57]
	v_mfma_f32_16x16x32_f16 v[50:53], v[204:207], v[212:215], v[50:53]
	v_mfma_f32_16x16x32_f16 v[38:41], v[164:167], v[220:223], v[38:41]
	v_mfma_f32_16x16x32_f16 v[34:37], v[204:207], v[220:223], v[34:37]
	v_mfma_f32_16x16x32_f16 v[20:23], v[164:167], v[228:231], v[20:23]
	v_mfma_f32_16x16x32_f16 v[16:19], v[204:207], v[228:231], v[16:19]
	v_mfma_f32_16x16x32_f16 v[4:7], v[164:167], v[236:239], v[4:7]
	v_mfma_f32_16x16x32_f16 v[0:3], v[204:207], v[236:239], v[0:3]
	s_setprio 2
	s_barrier
	s_add_i32 s31, 0, 0x18000
	v_add_u32_e32 v32, s31, v174
	s_add_i32 s68, 0, 0x1c000
	ds_read_b128 v[144:147], v32
	ds_read_b128 v[148:151], v32 offset:1024
	ds_read_b128 v[152:155], v32 offset:2048
	ds_read_b128 v[156:159], v32 offset:3072
	v_add_u32_e32 v32, s68, v174
	ds_read_b128 v[160:163], v32
	ds_read_b128 v[164:167], v32 offset:1024
	ds_read_b128 v[168:171], v32 offset:2048
	ds_read_b128 v[204:207], v32 offset:3072
	s_add_u32 s26, s26, s14
	s_addc_u32 s27, s27, 0
	s_mov_b32 m0, s53
	v_lshl_add_u64 v[246:247], s[26:27], 0, v[130:131]
	ds_read_b128 v[208:211], v190 offset:32768
	ds_read_b128 v[212:215], v190 offset:33792
	ds_read_b128 v[216:219], v190 offset:34816
	ds_read_b128 v[220:223], v190 offset:35840
	ds_read_b128 v[224:227], v190 offset:36864
	ds_read_b128 v[228:231], v190 offset:37888
	ds_read_b128 v[232:235], v190 offset:38912
	ds_read_b128 v[236:239], v190 offset:39936
	global_load_lds_dwordx4 v[246:247], off
	v_lshl_add_u64 v[246:247], s[26:27], 0, v[134:135]
	s_mov_b32 m0, s74
	s_nop 0
	global_load_lds_dwordx4 v[246:247], off
	s_waitcnt vmcnt(8)
	s_waitcnt lgkmcnt(0)
	s_barrier
	s_setprio 0
	s_waitcnt lgkmcnt(0)
	v_mfma_f32_16x16x32_f16 v[126:129], v[144:147], v[208:211], v[126:129]
	v_mfma_f32_16x16x32_f16 v[122:125], v[152:155], v[208:211], v[122:125]
	v_mfma_f32_16x16x32_f16 v[110:113], v[144:147], v[216:219], v[110:113]
	v_mfma_f32_16x16x32_f16 v[106:109], v[152:155], v[216:219], v[106:109]
	v_mfma_f32_16x16x32_f16 v[94:97], v[144:147], v[224:227], v[94:97]
	v_mfma_f32_16x16x32_f16 v[90:93], v[152:155], v[224:227], v[90:93]
	v_mfma_f32_16x16x32_f16 v[78:81], v[144:147], v[232:235], v[78:81]
	v_mfma_f32_16x16x32_f16 v[74:77], v[152:155], v[232:235], v[74:77]
	v_mfma_f32_16x16x32_f16 v[126:129], v[148:151], v[212:215], v[126:129]
	v_mfma_f32_16x16x32_f16 v[122:125], v[156:159], v[212:215], v[122:125]
	v_mfma_f32_16x16x32_f16 v[110:113], v[148:151], v[220:223], v[110:113]
	v_mfma_f32_16x16x32_f16 v[106:109], v[156:159], v[220:223], v[106:109]
	v_mfma_f32_16x16x32_f16 v[94:97], v[148:151], v[228:231], v[94:97]
	v_mfma_f32_16x16x32_f16 v[90:93], v[156:159], v[228:231], v[90:93]
	v_mfma_f32_16x16x32_f16 v[78:81], v[148:151], v[236:239], v[78:81]
	v_mfma_f32_16x16x32_f16 v[74:77], v[156:159], v[236:239], v[74:77]
	v_mfma_f32_16x16x32_f16 v[118:121], v[160:163], v[208:211], v[118:121]
	v_mfma_f32_16x16x32_f16 v[114:117], v[168:171], v[208:211], v[114:117]
	v_mfma_f32_16x16x32_f16 v[102:105], v[160:163], v[216:219], v[102:105]
	v_mfma_f32_16x16x32_f16 v[98:101], v[168:171], v[216:219], v[98:101]
	v_mfma_f32_16x16x32_f16 v[86:89], v[160:163], v[224:227], v[86:89]
	v_mfma_f32_16x16x32_f16 v[82:85], v[168:171], v[224:227], v[82:85]
	v_mfma_f32_16x16x32_f16 v[70:73], v[160:163], v[232:235], v[70:73]
	v_mfma_f32_16x16x32_f16 v[66:69], v[168:171], v[232:235], v[66:69]
	v_mfma_f32_16x16x32_f16 v[118:121], v[164:167], v[212:215], v[118:121]
	v_mfma_f32_16x16x32_f16 v[114:117], v[204:207], v[212:215], v[114:117]
	v_mfma_f32_16x16x32_f16 v[102:105], v[164:167], v[220:223], v[102:105]
	v_mfma_f32_16x16x32_f16 v[98:101], v[204:207], v[220:223], v[98:101]
	v_mfma_f32_16x16x32_f16 v[86:89], v[164:167], v[228:231], v[86:89]
	v_mfma_f32_16x16x32_f16 v[82:85], v[204:207], v[228:231], v[82:85]
	v_mfma_f32_16x16x32_f16 v[70:73], v[164:167], v[236:239], v[70:73]
	v_mfma_f32_16x16x32_f16 v[66:69], v[204:207], v[236:239], v[66:69]
	s_setprio 2
	s_barrier
; #define PG8_STAGE(bufoff, gbase, voff) do { _Pragma("unroll") for (int _i = 0; _i < 2; ++_i) \
;         __builtin_amdgcn_global_load_lds((const unsigned*)((const char*)(gbase) + (voff)[_i]), (LAS unsigned*)(lds + (bufoff) + ldsw + _i * 8192), 16, 0, 0); } while (0)
; #define PG8_LDA(dst, b, h) do { _Pragma("unroll") for (int m = 0; m < 4; ++m) _Pragma("unroll") for (int k = 0; k < 2; ++k) dst[m][k] = *(const LAS h16x8*)(lds + PG8_SA(b, h) + aoff + m * 2048 + k * 1024); } while (0)
; #define PG8_LDB(dst, b, h) do { _Pragma("unroll") for (int n = 0; n < 2; ++n) _Pragma("unroll") for (int k = 0; k < 2; ++k) dst[n][k] = *(const LAS h16x8*)(lds + PG8_SB(b, h) + boff + n * 2048 + k * 1024); } while (0)
; #define PG8_WAIT_V(n) asm volatile("s_waitcnt vmcnt(" #n ")" ::: "memory")
; template <class Epi>
; __device__ __forceinline__ void gemm_phase(LAS unsigned char* lds, const Gemm g, const StaticOrder& S, const Epi& E) {
;     ...
;         for (int t = 0; t < nt; t += 2) {
;             const bool last = (t == nt - 2);
;             const char* a1 = cA + (size_t)(t + 1) * kstep;
;             const char* a2 = last ? nA : cA + (size_t)(t + 2) * kstep; const char* b2 = last ? nB : cB + (size_t)(t + 2) * kstep;
;             const char* a3 = a2 + kstep; const char* b3 = b2 + kstep;
;             PG8_LDB(B0, 0, 0); PG8_LDB(B1, 0, 1); PG8_SCHED; PG8_LDA(At, 0, 0); PG8_STAGE(PG8_SA(1, 1), a1 + hstepA, voffA);
;             PG8_WAIT_V(8); PG8_WAIT_L(0); PG8_BAR; PG8_MMA(0, 0, At, B0); PG8_MMA(0, 1, At, B1); PG8_BAR; PG8_SCHED;
;             PG8_LDA(At, 0, 1); PG8_STAGE(PG8_SB(0, 0), b2, voffB); PG8_STAGE(PG8_SB(0, 1), b2 + hstepB, voffB); PG8_STAGE(PG8_SA(0, 0), a2, voffA);
;             PG8_WAIT_V(8); PG8_WAIT_L(0); PG8_BAR; PG8_MMA(1, 0, At, B0); PG8_MMA(1, 1, At, B1); PG8_BAR; PG8_SCHED;
;             PG8_LDB(B0, 1, 0); PG8_LDB(B1, 1, 1); PG8_SCHED; PG8_LDA(At, 1, 0); PG8_STAGE(PG8_SA(0, 1), a2 + hstepA, voffA);
;             PG8_WAIT_V(8); PG8_WAIT_L(0); PG8_BAR; PG8_MMA(0, 0, At, B0); PG8_MMA(0, 1, At, B1); PG8_BAR; PG8_SCHED;
;             PG8_LDA(At, 1, 1); PG8_STAGE(PG8_SB(1, 0), b3, voffB); PG8_STAGE(PG8_SB(1, 1), b3 + hstepB, voffB); PG8_STAGE(PG8_SA(1, 0), a3, voffA);
;             PG8_WAIT_V(8); PG8_WAIT_L(0); PG8_BAR; PG8_MMA(1, 0, At, B0); PG8_MMA(1, 1, At, B1); PG8_BAR; PG8_SCHED;
;         }
;         if (wr == 0) PG8_BAR;
	s_add_i32 s26, s31, s35
	v_lshl_add_u64 v[172:173], v[172:173], 0, s[90:91]
	s_mov_b32 m0, s26
	ds_read_b128 v[208:211], v190 offset:49152
	ds_read_b128 v[212:215], v190 offset:50176
	ds_read_b128 v[216:219], v190 offset:51200
	ds_read_b128 v[220:223], v190 offset:52224
	ds_read_b128 v[224:227], v190 offset:53248
	ds_read_b128 v[228:231], v190 offset:54272
	ds_read_b128 v[232:235], v190 offset:55296
	ds_read_b128 v[236:239], v190 offset:56320
	global_load_lds_dwordx4 v[172:173], off
	v_lshl_add_u64 v[172:173], v[196:197], 0, s[90:91]
	s_add_i32 m0, s26, 0x2000
	s_add_i32 s26, s68, s35
	global_load_lds_dwordx4 v[172:173], off
	v_lshl_add_u64 v[172:173], v[198:199], 0, s[90:91]
	s_mov_b32 m0, s26
	s_nop 0
	global_load_lds_dwordx4 v[172:173], off
	v_lshl_add_u64 v[172:173], v[240:241], 0, s[90:91]
	s_add_i32 m0, s26, 0x2000
	s_nop 0
	global_load_lds_dwordx4 v[172:173], off
	v_lshl_add_u64 v[172:173], v[242:243], 0, s[90:91]
	s_mov_b32 m0, s89
	s_nop 0
	global_load_lds_dwordx4 v[172:173], off
	v_lshl_add_u64 v[172:173], v[244:245], 0, s[90:91]
	s_mov_b32 m0, s92
	s_nop 0
	global_load_lds_dwordx4 v[172:173], off
	s_waitcnt vmcnt(8)
	s_waitcnt lgkmcnt(0)
	s_barrier
	s_setprio 0
	s_waitcnt lgkmcnt(0)
	v_mfma_f32_16x16x32_f16 v[62:65], v[144:147], v[208:211], v[62:65]
	v_mfma_f32_16x16x32_f16 v[58:61], v[152:155], v[208:211], v[58:61]
	v_mfma_f32_16x16x32_f16 v[46:49], v[144:147], v[216:219], v[46:49]
	v_mfma_f32_16x16x32_f16 v[42:45], v[152:155], v[216:219], v[42:45]
	v_mfma_f32_16x16x32_f16 v[28:31], v[144:147], v[224:227], v[28:31]
	v_mfma_f32_16x16x32_f16 v[24:27], v[152:155], v[224:227], v[24:27]
	v_mfma_f32_16x16x32_f16 v[12:15], v[144:147], v[232:235], v[12:15]
	v_mfma_f32_16x16x32_f16 v[8:11], v[152:155], v[232:235], v[8:11]
	v_mfma_f32_16x16x32_f16 v[62:65], v[148:151], v[212:215], v[62:65]
	v_mfma_f32_16x16x32_f16 v[58:61], v[156:159], v[212:215], v[58:61]
	v_mfma_f32_16x16x32_f16 v[46:49], v[148:151], v[220:223], v[46:49]
	v_mfma_f32_16x16x32_f16 v[42:45], v[156:159], v[220:223], v[42:45]
	v_mfma_f32_16x16x32_f16 v[28:31], v[148:151], v[228:231], v[28:31]
	v_mfma_f32_16x16x32_f16 v[24:27], v[156:159], v[228:231], v[24:27]
	v_mfma_f32_16x16x32_f16 v[12:15], v[148:151], v[236:239], v[12:15]
	v_mfma_f32_16x16x32_f16 v[8:11], v[156:159], v[236:239], v[8:11]
	v_mfma_f32_16x16x32_f16 v[54:57], v[160:163], v[208:211], v[54:57]
	v_mfma_f32_16x16x32_f16 v[50:53], v[168:171], v[208:211], v[50:53]
	v_mfma_f32_16x16x32_f16 v[38:41], v[160:163], v[216:219], v[38:41]
	v_mfma_f32_16x16x32_f16 v[34:37], v[168:171], v[216:219], v[34:37]
	v_mfma_f32_16x16x32_f16 v[20:23], v[160:163], v[224:227], v[20:23]
	v_mfma_f32_16x16x32_f16 v[16:19], v[168:171], v[224:227], v[16:19]
	v_mfma_f32_16x16x32_f16 v[4:7], v[160:163], v[232:235], v[4:7]
	v_mfma_f32_16x16x32_f16 v[0:3], v[168:171], v[232:235], v[0:3]
	v_mfma_f32_16x16x32_f16 v[54:57], v[164:167], v[212:215], v[54:57]
	v_mfma_f32_16x16x32_f16 v[50:53], v[204:207], v[212:215], v[50:53]
	v_mfma_f32_16x16x32_f16 v[38:41], v[164:167], v[220:223], v[38:41]
	v_mfma_f32_16x16x32_f16 v[34:37], v[204:207], v[220:223], v[34:37]
	v_mfma_f32_16x16x32_f16 v[20:23], v[164:167], v[228:231], v[20:23]
	v_mfma_f32_16x16x32_f16 v[16:19], v[204:207], v[228:231], v[16:19]
	v_mfma_f32_16x16x32_f16 v[4:7], v[164:167], v[236:239], v[4:7]
	v_mfma_f32_16x16x32_f16 v[0:3], v[204:207], v[236:239], v[0:3]
	s_setprio 2
	s_barrier
	s_add_u32 s28, s28, 0x100
	s_addc_u32 s29, s29, 0
	s_add_u32 s22, s22, 0x100
	s_addc_u32 s23, s23, 0
	s_cmp_ge_u32 s30, s88
	s_mov_b32 s26, s30
	s_cbranch_scc0 .LBB0_631
	s_setprio 0
	s_and_b64 vcc, exec, s[18:19]
	s_cbranch_vccz .LBB0_634
	s_barrier

; #define PG8_STAGE(bufoff, gbase, voff) do { _Pragma("unroll") for (int _i = 0; _i < 2; ++_i) \
;         __builtin_amdgcn_global_load_lds((const unsigned*)((const char*)(gbase) + (voff)[_i]), (LAS unsigned*)(lds + (bufoff) + ldsw + _i * 8192), 16, 0, 0); } while (0)
; #define PG8_LDA(dst, b, h) do { _Pragma("unroll") for (int m = 0; m < 4; ++m) _Pragma("unroll") for (int k = 0; k < 2; ++k) dst[m][k] = *(const LAS h16x8*)(lds + PG8_SA(b, h) + aoff + m * 2048 + k * 1024); } while (0)
; #define PG8_LDB(dst, b, h) do { _Pragma("unroll") for (int n = 0; n < 2; ++n) _Pragma("unroll") for (int k = 0; k < 2; ++k) dst[n][k] = *(const LAS h16x8*)(lds + PG8_SB(b, h) + boff + n * 2048 + k * 1024); } while (0)
; #define PG8_MMA(ai, bj, At, Bt) do { __builtin_amdgcn_s_setprio(1); _Pragma("unroll") for (int m = 0; m < 4; ++m) _Pragma("unroll") for (int n = 0; n < 2; ++n) _Pragma("unroll") for (int k = 0; k < 2; ++k) \
;         acc[ai][bj][m][n] = __builtin_amdgcn_mfma_f32_16x16x32_f16(Bt[n][k], At[m][k], acc[ai][bj][m][n], 0, 0, 0); __builtin_amdgcn_s_setprio(0); } while (0)
; #define PG8_WAIT_V(n) asm volatile("s_waitcnt vmcnt(" #n ")" ::: "memory")
; #define PG8_WAIT_L(n) asm volatile("s_waitcnt lgkmcnt(" #n ")" ::: "memory")
; #define PG8_BAR __builtin_amdgcn_s_barrier()
; #define PG8_SCHED __builtin_amdgcn_sched_barrier(0)
; template <class Epi>
; __device__ __forceinline__ void gemm_phase(LAS unsigned char* lds, const Gemm g, const StaticOrder& S, const Epi& E) {
;     ...
;             const bool last = (t == nt - 2);
;             const char* a1 = cA + (size_t)(t + 1) * kstep;
;             const char* a2 = last ? nA : cA + (size_t)(t + 2) * kstep; const char* b2 = last ? nB : cB + (size_t)(t + 2) * kstep;
;             const char* a3 = a2 + kstep; const char* b3 = b2 + kstep;
;             PG8_LDB(B0, 0, 0); PG8_LDB(B1, 0, 1); PG8_SCHED; PG8_LDA(At, 0, 0); PG8_STAGE(PG8_SA(1, 1), a1 + hstepA, voffA);
;             PG8_WAIT_V(8); PG8_WAIT_L(0); PG8_BAR; PG8_MMA(0, 0, At, B0); PG8_MMA(0, 1, At, B1); PG8_BAR; PG8_SCHED;
;             PG8_LDA(At, 0, 1); PG8_STAGE(PG8_SB(0, 0), b2, voffB); PG8_STAGE(PG8_SB(0, 1), b2 + hstepB, voffB); PG8_STAGE(PG8_SA(0, 0), a2, voffA);
.Lprio_699:
.LBB0_699:
	s_add_u32 s20, s18, 0x100
	s_addc_u32 s21, s19, 0
	s_add_i32 s79, 0, 0x10000
	s_cmp_eq_u32 s78, 40
	s_cselect_b32 s27, s1, s21
	s_cselect_b32 s26, s0, s20
	v_add_u32_e32 v32, s79, v172
	s_cselect_b32 s23, s17, s76
	s_cselect_b32 s22, s16, s75
	s_add_i32 s80, 0, 0x14000
	ds_read_b128 v[144:147], v32
	ds_read_b128 v[148:151], v32 offset:1024
	ds_read_b128 v[152:155], v32 offset:2048
	ds_read_b128 v[156:159], v32 offset:3072
	v_add_u32_e32 v32, s80, v172
	ds_read_b128 v[160:163], v32
	ds_read_b128 v[164:167], v32 offset:1024
	ds_read_b128 v[168:171], v32 offset:2048
	ds_read_b128 v[204:207], v32 offset:3072
	v_lshl_add_u64 v[190:191], s[18:19], 0, v[142:143]
	s_add_i32 m0, s28, 0xc000
	ds_read_b128 v[208:211], v179
	ds_read_b128 v[212:215], v179 offset:1024
	ds_read_b128 v[216:219], v179 offset:2048
	ds_read_b128 v[220:223], v179 offset:3072
	ds_read_b128 v[224:227], v179 offset:4096
	ds_read_b128 v[228:231], v179 offset:5120
	ds_read_b128 v[232:235], v179 offset:6144
	ds_read_b128 v[236:239], v179 offset:7168
	global_load_lds_dwordx4 v[190:191], off
	v_lshl_add_u64 v[190:191], s[18:19], 0, v[140:141]
	s_add_i32 m0, s28, 0xe000
	s_nop 0
	global_load_lds_dwordx4 v[190:191], off
	s_waitcnt vmcnt(8)
	s_waitcnt lgkmcnt(0)
	s_barrier
	s_setprio 0
	s_waitcnt lgkmcnt(0)
	v_mfma_f32_16x16x32_f16 v[126:129], v[144:147], v[208:211], v[126:129]
	v_mfma_f32_16x16x32_f16 v[122:125], v[152:155], v[208:211], v[122:125]
	v_mfma_f32_16x16x32_f16 v[110:113], v[144:147], v[216:219], v[110:113]
	v_mfma_f32_16x16x32_f16 v[106:109], v[152:155], v[216:219], v[106:109]
	v_mfma_f32_16x16x32_f16 v[94:97], v[144:147], v[224:227], v[94:97]
	v_mfma_f32_16x16x32_f16 v[90:93], v[152:155], v[224:227], v[90:93]
	v_mfma_f32_16x16x32_f16 v[78:81], v[144:147], v[232:235], v[78:81]
	v_mfma_f32_16x16x32_f16 v[74:77], v[152:155], v[232:235], v[74:77]
	v_mfma_f32_16x16x32_f16 v[126:129], v[148:151], v[212:215], v[126:129]
	v_mfma_f32_16x16x32_f16 v[122:125], v[156:159], v[212:215], v[122:125]
	v_mfma_f32_16x16x32_f16 v[110:113], v[148:151], v[220:223], v[110:113]
	v_mfma_f32_16x16x32_f16 v[106:109], v[156:159], v[220:223], v[106:109]
	v_mfma_f32_16x16x32_f16 v[94:97], v[148:151], v[228:231], v[94:97]
	v_mfma_f32_16x16x32_f16 v[90:93], v[156:159], v[228:231], v[90:93]
	v_mfma_f32_16x16x32_f16 v[78:81], v[148:151], v[236:239], v[78:81]
	v_mfma_f32_16x16x32_f16 v[74:77], v[156:159], v[236:239], v[74:77]
	v_mfma_f32_16x16x32_f16 v[118:121], v[160:163], v[208:211], v[118:121]
	v_mfma_f32_16x16x32_f16 v[114:117], v[168:171], v[208:211], v[114:117]
	v_mfma_f32_16x16x32_f16 v[102:105], v[160:163], v[216:219], v[102:105]
	v_mfma_f32_16x16x32_f16 v[98:101], v[168:171], v[216:219], v[98:101]
	v_mfma_f32_16x16x32_f16 v[86:89], v[160:163], v[224:227], v[86:89]
	v_mfma_f32_16x16x32_f16 v[82:85], v[168:171], v[224:227], v[82:85]
	v_mfma_f32_16x16x32_f16 v[70:73], v[160:163], v[232:235], v[70:73]
	v_mfma_f32_16x16x32_f16 v[66:69], v[168:171], v[232:235], v[66:69]
	v_mfma_f32_16x16x32_f16 v[118:121], v[164:167], v[212:215], v[118:121]
	v_mfma_f32_16x16x32_f16 v[114:117], v[204:207], v[212:215], v[114:117]
	v_mfma_f32_16x16x32_f16 v[102:105], v[164:167], v[220:223], v[102:105]
	v_mfma_f32_16x16x32_f16 v[98:101], v[204:207], v[220:223], v[98:101]
	v_mfma_f32_16x16x32_f16 v[86:89], v[164:167], v[228:231], v[86:89]
	v_mfma_f32_16x16x32_f16 v[82:85], v[204:207], v[228:231], v[82:85]
	v_mfma_f32_16x16x32_f16 v[70:73], v[164:167], v[236:239], v[70:73]
	v_mfma_f32_16x16x32_f16 v[66:69], v[204:207], v[236:239], v[66:69]
	s_setprio 2
	s_barrier
	s_add_i32 s18, s79, s3
	v_lshl_add_u64 v[190:191], s[22:23], 0, v[132:133]
	s_mov_b32 m0, s18
	ds_read_b128 v[208:211], v179 offset:16384
	ds_read_b128 v[212:215], v179 offset:17408
	ds_read_b128 v[216:219], v179 offset:18432
	ds_read_b128 v[220:223], v179 offset:19456
	ds_read_b128 v[224:227], v179 offset:20480
	ds_read_b128 v[228:231], v179 offset:21504
	ds_read_b128 v[232:235], v179 offset:22528
	ds_read_b128 v[236:239], v179 offset:23552
	global_load_lds_dwordx4 v[190:191], off
	s_add_i32 m0, s18, 0x2000
	s_add_u32 s18, s22, 0xb0000
	v_lshl_add_u64 v[196:197], s[22:23], 0, v[136:137]
	s_addc_u32 s19, s23, 0
	s_add_i32 s79, s80, s3
	global_load_lds_dwordx4 v[196:197], off
	v_lshl_add_u64 v[198:199], s[18:19], 0, v[132:133]
	s_mov_b32 m0, s79
	v_lshl_add_u64 v[240:241], s[26:27], 0, v[134:135]
	global_load_lds_dwordx4 v[198:199], off
	v_lshl_add_u64 v[198:199], s[18:19], 0, v[136:137]
	s_add_i32 m0, s79, 0x2000
	s_nop 0
	global_load_lds_dwordx4 v[198:199], off
	v_lshl_add_u64 v[198:199], s[26:27], 0, v[130:131]
	s_mov_b32 m0, s28
	s_nop 0
	global_load_lds_dwordx4 v[198:199], off
	s_mov_b32 m0, s29
	s_nop 0
	global_load_lds_dwordx4 v[240:241], off
	s_waitcnt vmcnt(8)
	s_waitcnt lgkmcnt(0)
	s_barrier
; #define PG8_STAGE(bufoff, gbase, voff) do { _Pragma("unroll") for (int _i = 0; _i < 2; ++_i) \
;         __builtin_amdgcn_global_load_lds((const unsigned*)((const char*)(gbase) + (voff)[_i]), (LAS unsigned*)(lds + (bufoff) + ldsw + _i * 8192), 16, 0, 0); } while (0)
; #define PG8_LDA(dst, b, h) do { _Pragma("unroll") for (int m = 0; m < 4; ++m) _Pragma("unroll") for (int k = 0; k < 2; ++k) dst[m][k] = *(const LAS h16x8*)(lds + PG8_SA(b, h) + aoff + m * 2048 + k * 1024); } while (0)
; #define PG8_LDB(dst, b, h) do { _Pragma("unroll") for (int n = 0; n < 2; ++n) _Pragma("unroll") for (int k = 0; k < 2; ++k) dst[n][k] = *(const LAS h16x8*)(lds + PG8_SB(b, h) + boff + n * 2048 + k * 1024); } while (0)
; #define PG8_MMA(ai, bj, At, Bt) do { __builtin_amdgcn_s_setprio(1); _Pragma("unroll") for (int m = 0; m < 4; ++m) _Pragma("unroll") for (int n = 0; n < 2; ++n) _Pragma("unroll") for (int k = 0; k < 2; ++k) \
;         acc[ai][bj][m][n] = __builtin_amdgcn_mfma_f32_16x16x32_f16(Bt[n][k], At[m][k], acc[ai][bj][m][n], 0, 0, 0); __builtin_amdgcn_s_setprio(0); } while (0)
; #define PG8_WAIT_V(n) asm volatile("s_waitcnt vmcnt(" #n ")" ::: "memory")
; #define PG8_WAIT_L(n) asm volatile("s_waitcnt lgkmcnt(" #n ")" ::: "memory")
; #define PG8_BAR __builtin_amdgcn_s_barrier()
; #define PG8_SCHED __builtin_amdgcn_sched_barrier(0)
; template <class Epi>
; __device__ __forceinline__ void gemm_phase(LAS unsigned char* lds, const Gemm g, const StaticOrder& S, const Epi& E) {
;     ...
;             PG8_WAIT_V(8); PG8_WAIT_L(0); PG8_BAR; PG8_MMA(1, 0, At, B0); PG8_MMA(1, 1, At, B1); PG8_BAR; PG8_SCHED;
;             PG8_LDB(B0, 1, 0); PG8_LDB(B1, 1, 1); PG8_SCHED; PG8_LDA(At, 1, 0); PG8_STAGE(PG8_SA(0, 1), a2 + hstepA, voffA);
;             PG8_WAIT_V(8); PG8_WAIT_L(0); PG8_BAR; PG8_MMA(0, 0, At, B0); PG8_MMA(0, 1, At, B1); PG8_BAR; PG8_SCHED;
	s_setprio 0
	s_waitcnt lgkmcnt(0)
	v_mfma_f32_16x16x32_f16 v[62:65], v[144:147], v[208:211], v[62:65]
	v_mfma_f32_16x16x32_f16 v[58:61], v[152:155], v[208:211], v[58:61]
	v_mfma_f32_16x16x32_f16 v[46:49], v[144:147], v[216:219], v[46:49]
	v_mfma_f32_16x16x32_f16 v[42:45], v[152:155], v[216:219], v[42:45]
	v_mfma_f32_16x16x32_f16 v[28:31], v[144:147], v[224:227], v[28:31]
	v_mfma_f32_16x16x32_f16 v[24:27], v[152:155], v[224:227], v[24:27]
	v_mfma_f32_16x16x32_f16 v[12:15], v[144:147], v[232:235], v[12:15]
	v_mfma_f32_16x16x32_f16 v[8:11], v[152:155], v[232:235], v[8:11]
	v_mfma_f32_16x16x32_f16 v[62:65], v[148:151], v[212:215], v[62:65]
	v_mfma_f32_16x16x32_f16 v[58:61], v[156:159], v[212:215], v[58:61]
	v_mfma_f32_16x16x32_f16 v[46:49], v[148:151], v[220:223], v[46:49]
	v_mfma_f32_16x16x32_f16 v[42:45], v[156:159], v[220:223], v[42:45]
	v_mfma_f32_16x16x32_f16 v[28:31], v[148:151], v[228:231], v[28:31]
	v_mfma_f32_16x16x32_f16 v[24:27], v[156:159], v[228:231], v[24:27]
	v_mfma_f32_16x16x32_f16 v[12:15], v[148:151], v[236:239], v[12:15]
	v_mfma_f32_16x16x32_f16 v[8:11], v[156:159], v[236:239], v[8:11]
	v_mfma_f32_16x16x32_f16 v[54:57], v[160:163], v[208:211], v[54:57]
	v_mfma_f32_16x16x32_f16 v[50:53], v[168:171], v[208:211], v[50:53]
	v_mfma_f32_16x16x32_f16 v[38:41], v[160:163], v[216:219], v[38:41]
	v_mfma_f32_16x16x32_f16 v[34:37], v[168:171], v[216:219], v[34:37]
	v_mfma_f32_16x16x32_f16 v[20:23], v[160:163], v[224:227], v[20:23]
	v_mfma_f32_16x16x32_f16 v[16:19], v[168:171], v[224:227], v[16:19]
	v_mfma_f32_16x16x32_f16 v[4:7], v[160:163], v[232:235], v[4:7]
	v_mfma_f32_16x16x32_f16 v[0:3], v[168:171], v[232:235], v[0:3]
	v_mfma_f32_16x16x32_f16 v[54:57], v[164:167], v[212:215], v[54:57]
	v_mfma_f32_16x16x32_f16 v[50:53], v[204:207], v[212:215], v[50:53]
	v_mfma_f32_16x16x32_f16 v[38:41], v[164:167], v[220:223], v[38:41]
	v_mfma_f32_16x16x32_f16 v[34:37], v[204:207], v[220:223], v[34:37]
	v_mfma_f32_16x16x32_f16 v[20:23], v[164:167], v[228:231], v[20:23]
	v_mfma_f32_16x16x32_f16 v[16:19], v[204:207], v[228:231], v[16:19]
	v_mfma_f32_16x16x32_f16 v[4:7], v[164:167], v[236:239], v[4:7]
	v_mfma_f32_16x16x32_f16 v[0:3], v[204:207], v[236:239], v[0:3]
	s_setprio 2
	s_barrier
	s_add_i32 s79, 0, 0x18000
	v_add_u32_e32 v32, s79, v172
	s_add_i32 s80, 0, 0x1c000
	ds_read_b128 v[144:147], v32
	ds_read_b128 v[148:151], v32 offset:1024
	ds_read_b128 v[152:155], v32 offset:2048
	ds_read_b128 v[156:159], v32 offset:3072
	v_add_u32_e32 v32, s80, v172
	ds_read_b128 v[160:163], v32
	ds_read_b128 v[164:167], v32 offset:1024
	ds_read_b128 v[168:171], v32 offset:2048
	ds_read_b128 v[204:207], v32 offset:3072
	s_add_u32 s18, s26, 0xb0000
	s_addc_u32 s19, s27, 0
	s_mov_b32 m0, s30
	v_lshl_add_u64 v[242:243], s[18:19], 0, v[130:131]
	ds_read_b128 v[208:211], v179 offset:32768
	ds_read_b128 v[212:215], v179 offset:33792
	ds_read_b128 v[216:219], v179 offset:34816
	ds_read_b128 v[220:223], v179 offset:35840
	ds_read_b128 v[224:227], v179 offset:36864
	ds_read_b128 v[228:231], v179 offset:37888
	ds_read_b128 v[232:235], v179 offset:38912
	ds_read_b128 v[236:239], v179 offset:39936
	global_load_lds_dwordx4 v[242:243], off
	v_lshl_add_u64 v[242:243], s[18:19], 0, v[134:135]
	s_mov_b32 m0, s31
	s_nop 0
	global_load_lds_dwordx4 v[242:243], off
	s_waitcnt vmcnt(8)
	s_waitcnt lgkmcnt(0)
	s_barrier
	s_setprio 0
	s_waitcnt lgkmcnt(0)
	v_mfma_f32_16x16x32_f16 v[126:129], v[144:147], v[208:211], v[126:129]
	v_mfma_f32_16x16x32_f16 v[122:125], v[152:155], v[208:211], v[122:125]
	v_mfma_f32_16x16x32_f16 v[110:113], v[144:147], v[216:219], v[110:113]
	v_mfma_f32_16x16x32_f16 v[106:109], v[152:155], v[216:219], v[106:109]
	v_mfma_f32_16x16x32_f16 v[94:97], v[144:147], v[224:227], v[94:97]
	v_mfma_f32_16x16x32_f16 v[90:93], v[152:155], v[224:227], v[90:93]
	v_mfma_f32_16x16x32_f16 v[78:81], v[144:147], v[232:235], v[78:81]
	v_mfma_f32_16x16x32_f16 v[74:77], v[152:155], v[232:235], v[74:77]
	v_mfma_f32_16x16x32_f16 v[126:129], v[148:151], v[212:215], v[126:129]
	v_mfma_f32_16x16x32_f16 v[122:125], v[156:159], v[212:215], v[122:125]
	v_mfma_f32_16x16x32_f16 v[110:113], v[148:151], v[220:223], v[110:113]
	v_mfma_f32_16x16x32_f16 v[106:109], v[156:159], v[220:223], v[106:109]
	v_mfma_f32_16x16x32_f16 v[94:97], v[148:151], v[228:231], v[94:97]
	v_mfma_f32_16x16x32_f16 v[90:93], v[156:159], v[228:231], v[90:93]
	v_mfma_f32_16x16x32_f16 v[78:81], v[148:151], v[236:239], v[78:81]
	v_mfma_f32_16x16x32_f16 v[74:77], v[156:159], v[236:239], v[74:77]
	v_mfma_f32_16x16x32_f16 v[118:121], v[160:163], v[208:211], v[118:121]
	v_mfma_f32_16x16x32_f16 v[114:117], v[168:171], v[208:211], v[114:117]
	v_mfma_f32_16x16x32_f16 v[102:105], v[160:163], v[216:219], v[102:105]
	v_mfma_f32_16x16x32_f16 v[98:101], v[168:171], v[216:219], v[98:101]
	v_mfma_f32_16x16x32_f16 v[86:89], v[160:163], v[224:227], v[86:89]
	v_mfma_f32_16x16x32_f16 v[82:85], v[168:171], v[224:227], v[82:85]
	v_mfma_f32_16x16x32_f16 v[70:73], v[160:163], v[232:235], v[70:73]
	v_mfma_f32_16x16x32_f16 v[66:69], v[168:171], v[232:235], v[66:69]
	v_mfma_f32_16x16x32_f16 v[118:121], v[164:167], v[212:215], v[118:121]
	v_mfma_f32_16x16x32_f16 v[114:117], v[204:207], v[212:215], v[114:117]
	v_mfma_f32_16x16x32_f16 v[102:105], v[164:167], v[220:223], v[102:105]
	v_mfma_f32_16x16x32_f16 v[98:101], v[204:207], v[220:223], v[98:101]
	v_mfma_f32_16x16x32_f16 v[86:89], v[164:167], v[228:231], v[86:89]
	v_mfma_f32_16x16x32_f16 v[82:85], v[204:207], v[228:231], v[82:85]
	v_mfma_f32_16x16x32_f16 v[70:73], v[164:167], v[236:239], v[70:73]
	v_mfma_f32_16x16x32_f16 v[66:69], v[204:207], v[236:239], v[66:69]
	s_setprio 2
	s_barrier
; #define PG8_STAGE(bufoff, gbase, voff) do { _Pragma("unroll") for (int _i = 0; _i < 2; ++_i) \
;         __builtin_amdgcn_global_load_lds((const unsigned*)((const char*)(gbase) + (voff)[_i]), (LAS unsigned*)(lds + (bufoff) + ldsw + _i * 8192), 16, 0, 0); } while (0)
; #define PG8_LDA(dst, b, h) do { _Pragma("unroll") for (int m = 0; m < 4; ++m) _Pragma("unroll") for (int k = 0; k < 2; ++k) dst[m][k] = *(const LAS h16x8*)(lds + PG8_SA(b, h) + aoff + m * 2048 + k * 1024); } while (0)
; #define PG8_LDB(dst, b, h) do { _Pragma("unroll") for (int n = 0; n < 2; ++n) _Pragma("unroll") for (int k = 0; k < 2; ++k) dst[n][k] = *(const LAS h16x8*)(lds + PG8_SB(b, h) + boff + n * 2048 + k * 1024); } while (0)
; #define PG8_WAIT_V(n) asm volatile("s_waitcnt vmcnt(" #n ")" ::: "memory")
; template <class Epi>
; __device__ __forceinline__ void gemm_phase(LAS unsigned char* lds, const Gemm g, const StaticOrder& S, const Epi& E) {
;     ...
;         for (int t = 0; t < nt; t += 2) {
;             const bool last = (t == nt - 2);
;             const char* a1 = cA + (size_t)(t + 1) * kstep;
;             const char* a2 = last ? nA : cA + (size_t)(t + 2) * kstep; const char* b2 = last ? nB : cB + (size_t)(t + 2) * kstep;
;             const char* a3 = a2 + kstep; const char* b3 = b2 + kstep;
;             PG8_LDB(B0, 0, 0); PG8_LDB(B1, 0, 1); PG8_SCHED; PG8_LDA(At, 0, 0); PG8_STAGE(PG8_SA(1, 1), a1 + hstepA, voffA);
;             PG8_WAIT_V(8); PG8_WAIT_L(0); PG8_BAR; PG8_MMA(0, 0, At, B0); PG8_MMA(0, 1, At, B1); PG8_BAR; PG8_SCHED;
;             PG8_LDA(At, 0, 1); PG8_STAGE(PG8_SB(0, 0), b2, voffB); PG8_STAGE(PG8_SB(0, 1), b2 + hstepB, voffB); PG8_STAGE(PG8_SA(0, 0), a2, voffA);
;             PG8_WAIT_V(8); PG8_WAIT_L(0); PG8_BAR; PG8_MMA(1, 0, At, B0); PG8_MMA(1, 1, At, B1); PG8_BAR; PG8_SCHED;
;             PG8_LDB(B0, 1, 0); PG8_LDB(B1, 1, 1); PG8_SCHED; PG8_LDA(At, 1, 0); PG8_STAGE(PG8_SA(0, 1), a2 + hstepA, voffA);
;             PG8_WAIT_V(8); PG8_WAIT_L(0); PG8_BAR; PG8_MMA(0, 0, At, B0); PG8_MMA(0, 1, At, B1); PG8_BAR; PG8_SCHED;
;             PG8_LDA(At, 1, 1); PG8_STAGE(PG8_SB(1, 0), b3, voffB); PG8_STAGE(PG8_SB(1, 1), b3 + hstepB, voffB); PG8_STAGE(PG8_SA(1, 0), a3, voffA);
;             PG8_WAIT_V(8); PG8_WAIT_L(0); PG8_BAR; PG8_MMA(1, 0, At, B0); PG8_MMA(1, 1, At, B1); PG8_BAR; PG8_SCHED;
;         }
;         if (wr == 0) PG8_BAR;
	s_add_i32 s18, s79, s3
	v_lshl_add_u64 v[190:191], v[190:191], 0, s[90:91]
	s_mov_b32 m0, s18
	ds_read_b128 v[208:211], v179 offset:49152
	ds_read_b128 v[212:215], v179 offset:50176
	ds_read_b128 v[216:219], v179 offset:51200
	ds_read_b128 v[220:223], v179 offset:52224
	ds_read_b128 v[224:227], v179 offset:53248
	ds_read_b128 v[228:231], v179 offset:54272
	ds_read_b128 v[232:235], v179 offset:55296
	ds_read_b128 v[236:239], v179 offset:56320
	global_load_lds_dwordx4 v[190:191], off
	s_add_i32 m0, s18, 0x2000
	s_add_u32 s18, s22, 0xb0080
	v_lshl_add_u64 v[190:191], v[196:197], 0, s[90:91]
	s_addc_u32 s19, s23, 0
	s_add_i32 s22, s80, s3
	global_load_lds_dwordx4 v[190:191], off
	v_lshl_add_u64 v[190:191], s[18:19], 0, v[132:133]
	s_mov_b32 m0, s22
	s_nop 0
	global_load_lds_dwordx4 v[190:191], off
	v_lshl_add_u64 v[190:191], s[18:19], 0, v[136:137]
	s_add_i32 m0, s22, 0x2000
	s_nop 0
	global_load_lds_dwordx4 v[190:191], off
	v_lshl_add_u64 v[190:191], v[198:199], 0, s[90:91]
	s_mov_b32 m0, s55
	s_nop 0
	global_load_lds_dwordx4 v[190:191], off
	v_lshl_add_u64 v[190:191], v[240:241], 0, s[90:91]
	s_mov_b32 m0, s68
	s_nop 0
	global_load_lds_dwordx4 v[190:191], off
	s_waitcnt vmcnt(8)
	s_waitcnt lgkmcnt(0)
	s_barrier
	s_setprio 0
	s_waitcnt lgkmcnt(0)
	v_mfma_f32_16x16x32_f16 v[62:65], v[144:147], v[208:211], v[62:65]
	v_mfma_f32_16x16x32_f16 v[58:61], v[152:155], v[208:211], v[58:61]
	v_mfma_f32_16x16x32_f16 v[46:49], v[144:147], v[216:219], v[46:49]
	v_mfma_f32_16x16x32_f16 v[42:45], v[152:155], v[216:219], v[42:45]
	v_mfma_f32_16x16x32_f16 v[28:31], v[144:147], v[224:227], v[28:31]
	v_mfma_f32_16x16x32_f16 v[24:27], v[152:155], v[224:227], v[24:27]
	v_mfma_f32_16x16x32_f16 v[12:15], v[144:147], v[232:235], v[12:15]
	v_mfma_f32_16x16x32_f16 v[8:11], v[152:155], v[232:235], v[8:11]
	v_mfma_f32_16x16x32_f16 v[62:65], v[148:151], v[212:215], v[62:65]
	v_mfma_f32_16x16x32_f16 v[58:61], v[156:159], v[212:215], v[58:61]
	v_mfma_f32_16x16x32_f16 v[46:49], v[148:151], v[220:223], v[46:49]
	v_mfma_f32_16x16x32_f16 v[42:45], v[156:159], v[220:223], v[42:45]
	v_mfma_f32_16x16x32_f16 v[28:31], v[148:151], v[228:231], v[28:31]
	v_mfma_f32_16x16x32_f16 v[24:27], v[156:159], v[228:231], v[24:27]
	v_mfma_f32_16x16x32_f16 v[12:15], v[148:151], v[236:239], v[12:15]
	v_mfma_f32_16x16x32_f16 v[8:11], v[156:159], v[236:239], v[8:11]
	v_mfma_f32_16x16x32_f16 v[54:57], v[160:163], v[208:211], v[54:57]
	v_mfma_f32_16x16x32_f16 v[50:53], v[168:171], v[208:211], v[50:53]
	v_mfma_f32_16x16x32_f16 v[38:41], v[160:163], v[216:219], v[38:41]
	v_mfma_f32_16x16x32_f16 v[34:37], v[168:171], v[216:219], v[34:37]
	v_mfma_f32_16x16x32_f16 v[20:23], v[160:163], v[224:227], v[20:23]
	v_mfma_f32_16x16x32_f16 v[16:19], v[168:171], v[224:227], v[16:19]
	v_mfma_f32_16x16x32_f16 v[4:7], v[160:163], v[232:235], v[4:7]
	v_mfma_f32_16x16x32_f16 v[0:3], v[168:171], v[232:235], v[0:3]
	v_mfma_f32_16x16x32_f16 v[54:57], v[164:167], v[212:215], v[54:57]
	v_mfma_f32_16x16x32_f16 v[50:53], v[204:207], v[212:215], v[50:53]
	v_mfma_f32_16x16x32_f16 v[38:41], v[164:167], v[220:223], v[38:41]
	v_mfma_f32_16x16x32_f16 v[34:37], v[204:207], v[220:223], v[34:37]
	v_mfma_f32_16x16x32_f16 v[20:23], v[164:167], v[228:231], v[20:23]
	v_mfma_f32_16x16x32_f16 v[16:19], v[204:207], v[228:231], v[16:19]
	v_mfma_f32_16x16x32_f16 v[4:7], v[164:167], v[236:239], v[4:7]
	v_mfma_f32_16x16x32_f16 v[0:3], v[204:207], v[236:239], v[0:3]
	s_setprio 2
	s_barrier
	s_add_i32 s78, s78, 2
	s_add_u32 s75, s75, 0x100
	s_addc_u32 s76, s76, 0
	s_cmp_gt_u32 s78, 41
	s_mov_b64 s[18:19], s[20:21]
	s_cbranch_scc0 .LBB0_699
	s_setprio 0
	s_and_b64 vcc, exec, s[14:15]
	s_cbranch_vccz .LBB0_702
	s_barrier

; #define PG8_STAGE(bufoff, gbase, voff) do { _Pragma("unroll") for (int _i = 0; _i < 2; ++_i) \
;         __builtin_amdgcn_global_load_lds((const unsigned*)((const char*)(gbase) + (voff)[_i]), (LAS unsigned*)(lds + (bufoff) + ldsw + _i * 8192), 16, 0, 0); } while (0)
; #define PG8_LDA(dst, b, h) do { _Pragma("unroll") for (int m = 0; m < 4; ++m) _Pragma("unroll") for (int k = 0; k < 2; ++k) dst[m][k] = *(const LAS h16x8*)(lds + PG8_SA(b, h) + aoff + m * 2048 + k * 1024); } while (0)
; #define PG8_LDB(dst, b, h) do { _Pragma("unroll") for (int n = 0; n < 2; ++n) _Pragma("unroll") for (int k = 0; k < 2; ++k) dst[n][k] = *(const LAS h16x8*)(lds + PG8_SB(b, h) + boff + n * 2048 + k * 1024); } while (0)
; #define PG8_MMA(ai, bj, At, Bt) do { __builtin_amdgcn_s_setprio(1); _Pragma("unroll") for (int m = 0; m < 4; ++m) _Pragma("unroll") for (int n = 0; n < 2; ++n) _Pragma("unroll") for (int k = 0; k < 2; ++k) \
;         acc[ai][bj][m][n] = __builtin_amdgcn_mfma_f32_16x16x32_f16(Bt[n][k], At[m][k], acc[ai][bj][m][n], 0, 0, 0); __builtin_amdgcn_s_setprio(0); } while (0)
; #define PG8_WAIT_V(n) asm volatile("s_waitcnt vmcnt(" #n ")" ::: "memory")
; #define PG8_WAIT_L(n) asm volatile("s_waitcnt lgkmcnt(" #n ")" ::: "memory")
; #define PG8_BAR __builtin_amdgcn_s_barrier()
; #define PG8_SCHED __builtin_amdgcn_sched_barrier(0)
; template <class Epi>
; __device__ __forceinline__ void gemm_phase(LAS unsigned char* lds, const Gemm g, const StaticOrder& S, const Epi& E) {
;     ...
;             const bool last = (t == nt - 2);
;             const char* a1 = cA + (size_t)(t + 1) * kstep;
;             const char* a2 = last ? nA : cA + (size_t)(t + 2) * kstep; const char* b2 = last ? nB : cB + (size_t)(t + 2) * kstep;
;             const char* a3 = a2 + kstep; const char* b3 = b2 + kstep;
;             PG8_LDB(B0, 0, 0); PG8_LDB(B1, 0, 1); PG8_SCHED; PG8_LDA(At, 0, 0); PG8_STAGE(PG8_SA(1, 1), a1 + hstepA, voffA);
;             PG8_WAIT_V(8); PG8_WAIT_L(0); PG8_BAR; PG8_MMA(0, 0, At, B0); PG8_MMA(0, 1, At, B1); PG8_BAR; PG8_SCHED;
;             PG8_LDA(At, 0, 1); PG8_STAGE(PG8_SB(0, 0), b2, voffB); PG8_STAGE(PG8_SB(0, 1), b2 + hstepB, voffB); PG8_STAGE(PG8_SA(0, 0), a2, voffA);
.Lprio_753:
.LBB0_753:
	s_add_u32 s20, s18, 0xfffc0080
	s_addc_u32 s21, s19, -1
	s_add_i32 s73, 0, 0x10000
	s_cmp_eq_u32 s72, 12
	s_cselect_b32 s23, s11, s21
	s_cselect_b32 s22, s68, s20
	v_add_u32_e32 v32, s73, v143
	s_cselect_b32 s21, s9, s71
	s_cselect_b32 s20, s69, s70
	s_add_i32 s75, 0, 0x14000
	ds_read_b128 v[146:149], v32
	ds_read_b128 v[150:153], v32 offset:1024
	ds_read_b128 v[154:157], v32 offset:2048
	ds_read_b128 v[158:161], v32 offset:3072
	v_add_u32_e32 v32, s75, v143
	ds_read_b128 v[162:165], v32
	ds_read_b128 v[166:169], v32 offset:1024
	ds_read_b128 v[170:173], v32 offset:2048
	ds_read_b128 v[174:177], v32 offset:3072
	v_lshl_add_u64 v[190:191], s[18:19], 0, v[140:141]
	s_add_i32 m0, s28, 0xc000
	ds_read_b128 v[178:181], v145
	ds_read_b128 v[204:207], v145 offset:1024
	ds_read_b128 v[208:211], v145 offset:2048
	ds_read_b128 v[212:215], v145 offset:3072
	ds_read_b128 v[216:219], v145 offset:4096
	ds_read_b128 v[220:223], v145 offset:5120
	ds_read_b128 v[224:227], v145 offset:6144
	ds_read_b128 v[228:231], v145 offset:7168
	global_load_lds_dwordx4 v[190:191], off
	v_lshl_add_u64 v[190:191], s[18:19], 0, v[138:139]
	s_add_i32 m0, s28, 0xe000
	s_nop 0
	global_load_lds_dwordx4 v[190:191], off
	s_waitcnt vmcnt(8)
	s_waitcnt lgkmcnt(0)
	s_barrier
	s_setprio 0
	s_waitcnt lgkmcnt(0)
	v_mfma_f32_16x16x32_f16 v[126:129], v[146:149], v[178:181], v[126:129]
	v_mfma_f32_16x16x32_f16 v[118:121], v[154:157], v[178:181], v[118:121]
	v_mfma_f32_16x16x32_f16 v[110:113], v[146:149], v[208:211], v[110:113]
	v_mfma_f32_16x16x32_f16 v[102:105], v[154:157], v[208:211], v[102:105]
	v_mfma_f32_16x16x32_f16 v[94:97], v[146:149], v[216:219], v[94:97]
	v_mfma_f32_16x16x32_f16 v[86:89], v[154:157], v[216:219], v[86:89]
	v_mfma_f32_16x16x32_f16 v[78:81], v[146:149], v[224:227], v[78:81]
	v_mfma_f32_16x16x32_f16 v[70:73], v[154:157], v[224:227], v[70:73]
	v_mfma_f32_16x16x32_f16 v[126:129], v[150:153], v[204:207], v[126:129]
	v_mfma_f32_16x16x32_f16 v[118:121], v[158:161], v[204:207], v[118:121]
	v_mfma_f32_16x16x32_f16 v[110:113], v[150:153], v[212:215], v[110:113]
	v_mfma_f32_16x16x32_f16 v[102:105], v[158:161], v[212:215], v[102:105]
	v_mfma_f32_16x16x32_f16 v[94:97], v[150:153], v[220:223], v[94:97]
	v_mfma_f32_16x16x32_f16 v[86:89], v[158:161], v[220:223], v[86:89]
	v_mfma_f32_16x16x32_f16 v[78:81], v[150:153], v[228:231], v[78:81]
	v_mfma_f32_16x16x32_f16 v[70:73], v[158:161], v[228:231], v[70:73]
	v_mfma_f32_16x16x32_f16 v[122:125], v[162:165], v[178:181], v[122:125]
	v_mfma_f32_16x16x32_f16 v[114:117], v[170:173], v[178:181], v[114:117]
	v_mfma_f32_16x16x32_f16 v[106:109], v[162:165], v[208:211], v[106:109]
	v_mfma_f32_16x16x32_f16 v[98:101], v[170:173], v[208:211], v[98:101]
	v_mfma_f32_16x16x32_f16 v[90:93], v[162:165], v[216:219], v[90:93]
	v_mfma_f32_16x16x32_f16 v[82:85], v[170:173], v[216:219], v[82:85]
	v_mfma_f32_16x16x32_f16 v[74:77], v[162:165], v[224:227], v[74:77]
	v_mfma_f32_16x16x32_f16 v[66:69], v[170:173], v[224:227], v[66:69]
	v_mfma_f32_16x16x32_f16 v[122:125], v[166:169], v[204:207], v[122:125]
	v_mfma_f32_16x16x32_f16 v[114:117], v[174:177], v[204:207], v[114:117]
	v_mfma_f32_16x16x32_f16 v[106:109], v[166:169], v[212:215], v[106:109]
	v_mfma_f32_16x16x32_f16 v[98:101], v[174:177], v[212:215], v[98:101]
	v_mfma_f32_16x16x32_f16 v[90:93], v[166:169], v[220:223], v[90:93]
	v_mfma_f32_16x16x32_f16 v[82:85], v[174:177], v[220:223], v[82:85]
	v_mfma_f32_16x16x32_f16 v[74:77], v[166:169], v[228:231], v[74:77]
	v_mfma_f32_16x16x32_f16 v[66:69], v[174:177], v[228:231], v[66:69]
	s_setprio 2
	s_barrier
	s_add_i32 s73, s73, s3
	v_lshl_add_u64 v[190:191], s[20:21], 0, v[134:135]
	s_mov_b32 m0, s73
	ds_read_b128 v[178:181], v145 offset:16384
	ds_read_b128 v[204:207], v145 offset:17408
	ds_read_b128 v[208:211], v145 offset:18432
	ds_read_b128 v[212:215], v145 offset:19456
	ds_read_b128 v[216:219], v145 offset:20480
	ds_read_b128 v[220:223], v145 offset:21504
	ds_read_b128 v[224:227], v145 offset:22528
	ds_read_b128 v[228:231], v145 offset:23552
	global_load_lds_dwordx4 v[190:191], off
	s_add_i32 m0, s73, 0x2000
	s_add_u32 s76, s20, 0x40000
	v_lshl_add_u64 v[196:197], s[20:21], 0, v[130:131]
	s_addc_u32 s77, s21, 0
	s_add_i32 s73, s75, s3
	global_load_lds_dwordx4 v[196:197], off
	v_lshl_add_u64 v[198:199], s[76:77], 0, v[134:135]
	s_mov_b32 m0, s73
	v_lshl_add_u64 v[232:233], s[22:23], 0, v[132:133]
	global_load_lds_dwordx4 v[198:199], off
	v_lshl_add_u64 v[198:199], s[76:77], 0, v[130:131]
	s_add_i32 m0, s73, 0x2000
	s_nop 0
	global_load_lds_dwordx4 v[198:199], off
	v_lshl_add_u64 v[198:199], s[22:23], 0, v[136:137]
	s_mov_b32 m0, s28
	s_nop 0
	global_load_lds_dwordx4 v[198:199], off
	s_mov_b32 m0, s29
	s_nop 0
	global_load_lds_dwordx4 v[232:233], off
	s_waitcnt vmcnt(8)
	s_waitcnt lgkmcnt(0)
	s_barrier
; #define PG8_STAGE(bufoff, gbase, voff) do { _Pragma("unroll") for (int _i = 0; _i < 2; ++_i) \
;         __builtin_amdgcn_global_load_lds((const unsigned*)((const char*)(gbase) + (voff)[_i]), (LAS unsigned*)(lds + (bufoff) + ldsw + _i * 8192), 16, 0, 0); } while (0)
; #define PG8_LDA(dst, b, h) do { _Pragma("unroll") for (int m = 0; m < 4; ++m) _Pragma("unroll") for (int k = 0; k < 2; ++k) dst[m][k] = *(const LAS h16x8*)(lds + PG8_SA(b, h) + aoff + m * 2048 + k * 1024); } while (0)
; #define PG8_LDB(dst, b, h) do { _Pragma("unroll") for (int n = 0; n < 2; ++n) _Pragma("unroll") for (int k = 0; k < 2; ++k) dst[n][k] = *(const LAS h16x8*)(lds + PG8_SB(b, h) + boff + n * 2048 + k * 1024); } while (0)
; #define PG8_MMA(ai, bj, At, Bt) do { __builtin_amdgcn_s_setprio(1); _Pragma("unroll") for (int m = 0; m < 4; ++m) _Pragma("unroll") for (int n = 0; n < 2; ++n) _Pragma("unroll") for (int k = 0; k < 2; ++k) \
;         acc[ai][bj][m][n] = __builtin_amdgcn_mfma_f32_16x16x32_f16(Bt[n][k], At[m][k], acc[ai][bj][m][n], 0, 0, 0); __builtin_amdgcn_s_setprio(0); } while (0)
; #define PG8_WAIT_V(n) asm volatile("s_waitcnt vmcnt(" #n ")" ::: "memory")
; #define PG8_WAIT_L(n) asm volatile("s_waitcnt lgkmcnt(" #n ")" ::: "memory")
; #define PG8_BAR __builtin_amdgcn_s_barrier()
; #define PG8_SCHED __builtin_amdgcn_sched_barrier(0)
; template <class Epi>
; __device__ __forceinline__ void gemm_phase(LAS unsigned char* lds, const Gemm g, const StaticOrder& S, const Epi& E) {
;     ...
;             PG8_WAIT_V(8); PG8_WAIT_L(0); PG8_BAR; PG8_MMA(1, 0, At, B0); PG8_MMA(1, 1, At, B1); PG8_BAR; PG8_SCHED;
;             PG8_LDB(B0, 1, 0); PG8_LDB(B1, 1, 1); PG8_SCHED; PG8_LDA(At, 1, 0); PG8_STAGE(PG8_SA(0, 1), a2 + hstepA, voffA);
;             PG8_WAIT_V(8); PG8_WAIT_L(0); PG8_BAR; PG8_MMA(0, 0, At, B0); PG8_MMA(0, 1, At, B1); PG8_BAR; PG8_SCHED;
	s_setprio 0
	s_waitcnt lgkmcnt(0)
	v_mfma_f32_16x16x32_f16 v[62:65], v[146:149], v[178:181], v[62:65]
	v_mfma_f32_16x16x32_f16 v[54:57], v[154:157], v[178:181], v[54:57]
	v_mfma_f32_16x16x32_f16 v[46:49], v[146:149], v[208:211], v[46:49]
	v_mfma_f32_16x16x32_f16 v[38:41], v[154:157], v[208:211], v[38:41]
	v_mfma_f32_16x16x32_f16 v[28:31], v[146:149], v[216:219], v[28:31]
	v_mfma_f32_16x16x32_f16 v[20:23], v[154:157], v[216:219], v[20:23]
	v_mfma_f32_16x16x32_f16 v[12:15], v[146:149], v[224:227], v[12:15]
	v_mfma_f32_16x16x32_f16 v[4:7], v[154:157], v[224:227], v[4:7]
	v_mfma_f32_16x16x32_f16 v[62:65], v[150:153], v[204:207], v[62:65]
	v_mfma_f32_16x16x32_f16 v[54:57], v[158:161], v[204:207], v[54:57]
	v_mfma_f32_16x16x32_f16 v[46:49], v[150:153], v[212:215], v[46:49]
	v_mfma_f32_16x16x32_f16 v[38:41], v[158:161], v[212:215], v[38:41]
	v_mfma_f32_16x16x32_f16 v[28:31], v[150:153], v[220:223], v[28:31]
	v_mfma_f32_16x16x32_f16 v[20:23], v[158:161], v[220:223], v[20:23]
	v_mfma_f32_16x16x32_f16 v[12:15], v[150:153], v[228:231], v[12:15]
	v_mfma_f32_16x16x32_f16 v[4:7], v[158:161], v[228:231], v[4:7]
	v_mfma_f32_16x16x32_f16 v[58:61], v[162:165], v[178:181], v[58:61]
	v_mfma_f32_16x16x32_f16 v[50:53], v[170:173], v[178:181], v[50:53]
	v_mfma_f32_16x16x32_f16 v[42:45], v[162:165], v[208:211], v[42:45]
	v_mfma_f32_16x16x32_f16 v[34:37], v[170:173], v[208:211], v[34:37]
	v_mfma_f32_16x16x32_f16 v[24:27], v[162:165], v[216:219], v[24:27]
	v_mfma_f32_16x16x32_f16 v[16:19], v[170:173], v[216:219], v[16:19]
	v_mfma_f32_16x16x32_f16 v[8:11], v[162:165], v[224:227], v[8:11]
	v_mfma_f32_16x16x32_f16 v[0:3], v[170:173], v[224:227], v[0:3]
	v_mfma_f32_16x16x32_f16 v[58:61], v[166:169], v[204:207], v[58:61]
	v_mfma_f32_16x16x32_f16 v[50:53], v[174:177], v[204:207], v[50:53]
	v_mfma_f32_16x16x32_f16 v[42:45], v[166:169], v[212:215], v[42:45]
	v_mfma_f32_16x16x32_f16 v[34:37], v[174:177], v[212:215], v[34:37]
	v_mfma_f32_16x16x32_f16 v[24:27], v[166:169], v[220:223], v[24:27]
	v_mfma_f32_16x16x32_f16 v[16:19], v[174:177], v[220:223], v[16:19]
	v_mfma_f32_16x16x32_f16 v[8:11], v[166:169], v[228:231], v[8:11]
	v_mfma_f32_16x16x32_f16 v[0:3], v[174:177], v[228:231], v[0:3]
	s_setprio 2
	s_barrier
	s_add_i32 s73, 0, 0x18000
	v_add_u32_e32 v32, s73, v143
	s_add_i32 s75, 0, 0x1c000
	ds_read_b128 v[146:149], v32
	ds_read_b128 v[150:153], v32 offset:1024
	ds_read_b128 v[154:157], v32 offset:2048
	ds_read_b128 v[158:161], v32 offset:3072
	v_add_u32_e32 v32, s75, v143
	ds_read_b128 v[162:165], v32
	ds_read_b128 v[166:169], v32 offset:1024
	ds_read_b128 v[170:173], v32 offset:2048
	ds_read_b128 v[174:177], v32 offset:3072
	s_add_u32 s22, s22, 0x40000
	s_addc_u32 s23, s23, 0
	s_mov_b32 m0, s30
	v_lshl_add_u64 v[234:235], s[22:23], 0, v[136:137]
	ds_read_b128 v[178:181], v145 offset:32768
	ds_read_b128 v[204:207], v145 offset:33792
	ds_read_b128 v[208:211], v145 offset:34816
	ds_read_b128 v[212:215], v145 offset:35840
	ds_read_b128 v[216:219], v145 offset:36864
	ds_read_b128 v[220:223], v145 offset:37888
	ds_read_b128 v[224:227], v145 offset:38912
	ds_read_b128 v[228:231], v145 offset:39936
	global_load_lds_dwordx4 v[234:235], off
	v_lshl_add_u64 v[234:235], s[22:23], 0, v[132:133]
	s_mov_b32 m0, s31
	s_nop 0
	global_load_lds_dwordx4 v[234:235], off
	s_waitcnt vmcnt(8)
	s_waitcnt lgkmcnt(0)
	s_barrier
	s_setprio 0
	s_waitcnt lgkmcnt(0)
	v_mfma_f32_16x16x32_f16 v[126:129], v[146:149], v[178:181], v[126:129]
	v_mfma_f32_16x16x32_f16 v[118:121], v[154:157], v[178:181], v[118:121]
	v_mfma_f32_16x16x32_f16 v[110:113], v[146:149], v[208:211], v[110:113]
	v_mfma_f32_16x16x32_f16 v[102:105], v[154:157], v[208:211], v[102:105]
	v_mfma_f32_16x16x32_f16 v[94:97], v[146:149], v[216:219], v[94:97]
	v_mfma_f32_16x16x32_f16 v[86:89], v[154:157], v[216:219], v[86:89]
	v_mfma_f32_16x16x32_f16 v[78:81], v[146:149], v[224:227], v[78:81]
	v_mfma_f32_16x16x32_f16 v[70:73], v[154:157], v[224:227], v[70:73]
	v_mfma_f32_16x16x32_f16 v[126:129], v[150:153], v[204:207], v[126:129]
	v_mfma_f32_16x16x32_f16 v[118:121], v[158:161], v[204:207], v[118:121]
	v_mfma_f32_16x16x32_f16 v[110:113], v[150:153], v[212:215], v[110:113]
	v_mfma_f32_16x16x32_f16 v[102:105], v[158:161], v[212:215], v[102:105]
	v_mfma_f32_16x16x32_f16 v[94:97], v[150:153], v[220:223], v[94:97]
	v_mfma_f32_16x16x32_f16 v[86:89], v[158:161], v[220:223], v[86:89]
	v_mfma_f32_16x16x32_f16 v[78:81], v[150:153], v[228:231], v[78:81]
	v_mfma_f32_16x16x32_f16 v[70:73], v[158:161], v[228:231], v[70:73]
	v_mfma_f32_16x16x32_f16 v[122:125], v[162:165], v[178:181], v[122:125]
	v_mfma_f32_16x16x32_f16 v[114:117], v[170:173], v[178:181], v[114:117]
	v_mfma_f32_16x16x32_f16 v[106:109], v[162:165], v[208:211], v[106:109]
	v_mfma_f32_16x16x32_f16 v[98:101], v[170:173], v[208:211], v[98:101]
	v_mfma_f32_16x16x32_f16 v[90:93], v[162:165], v[216:219], v[90:93]
	v_mfma_f32_16x16x32_f16 v[82:85], v[170:173], v[216:219], v[82:85]
	v_mfma_f32_16x16x32_f16 v[74:77], v[162:165], v[224:227], v[74:77]
	v_mfma_f32_16x16x32_f16 v[66:69], v[170:173], v[224:227], v[66:69]
	v_mfma_f32_16x16x32_f16 v[122:125], v[166:169], v[204:207], v[122:125]
	v_mfma_f32_16x16x32_f16 v[114:117], v[174:177], v[204:207], v[114:117]
	v_mfma_f32_16x16x32_f16 v[106:109], v[166:169], v[212:215], v[106:109]
	v_mfma_f32_16x16x32_f16 v[98:101], v[174:177], v[212:215], v[98:101]
	v_mfma_f32_16x16x32_f16 v[90:93], v[166:169], v[220:223], v[90:93]
	v_mfma_f32_16x16x32_f16 v[82:85], v[174:177], v[220:223], v[82:85]
	v_mfma_f32_16x16x32_f16 v[74:77], v[166:169], v[228:231], v[74:77]
	v_mfma_f32_16x16x32_f16 v[66:69], v[174:177], v[228:231], v[66:69]
	s_setprio 2
	s_barrier
; #define PG8_STAGE(bufoff, gbase, voff) do { _Pragma("unroll") for (int _i = 0; _i < 2; ++_i) \
;         __builtin_amdgcn_global_load_lds((const unsigned*)((const char*)(gbase) + (voff)[_i]), (LAS unsigned*)(lds + (bufoff) + ldsw + _i * 8192), 16, 0, 0); } while (0)
; #define PG8_LDA(dst, b, h) do { _Pragma("unroll") for (int m = 0; m < 4; ++m) _Pragma("unroll") for (int k = 0; k < 2; ++k) dst[m][k] = *(const LAS h16x8*)(lds + PG8_SA(b, h) + aoff + m * 2048 + k * 1024); } while (0)
; #define PG8_LDB(dst, b, h) do { _Pragma("unroll") for (int n = 0; n < 2; ++n) _Pragma("unroll") for (int k = 0; k < 2; ++k) dst[n][k] = *(const LAS h16x8*)(lds + PG8_SB(b, h) + boff + n * 2048 + k * 1024); } while (0)
; #define PG8_WAIT_V(n) asm volatile("s_waitcnt vmcnt(" #n ")" ::: "memory")
; template <class Epi>
; __device__ __forceinline__ void gemm_phase(LAS unsigned char* lds, const Gemm g, const StaticOrder& S, const Epi& E) {
;     ...
;         for (int t = 0; t < nt; t += 2) {
;             const bool last = (t == nt - 2);
;             const char* a1 = cA + (size_t)(t + 1) * kstep;
;             const char* a2 = last ? nA : cA + (size_t)(t + 2) * kstep; const char* b2 = last ? nB : cB + (size_t)(t + 2) * kstep;
;             const char* a3 = a2 + kstep; const char* b3 = b2 + kstep;
;             PG8_LDB(B0, 0, 0); PG8_LDB(B1, 0, 1); PG8_SCHED; PG8_LDA(At, 0, 0); PG8_STAGE(PG8_SA(1, 1), a1 + hstepA, voffA);
;             PG8_WAIT_V(8); PG8_WAIT_L(0); PG8_BAR; PG8_MMA(0, 0, At, B0); PG8_MMA(0, 1, At, B1); PG8_BAR; PG8_SCHED;
;             PG8_LDA(At, 0, 1); PG8_STAGE(PG8_SB(0, 0), b2, voffB); PG8_STAGE(PG8_SB(0, 1), b2 + hstepB, voffB); PG8_STAGE(PG8_SA(0, 0), a2, voffA);
;             PG8_WAIT_V(8); PG8_WAIT_L(0); PG8_BAR; PG8_MMA(1, 0, At, B0); PG8_MMA(1, 1, At, B1); PG8_BAR; PG8_SCHED;
;             PG8_LDB(B0, 1, 0); PG8_LDB(B1, 1, 1); PG8_SCHED; PG8_LDA(At, 1, 0); PG8_STAGE(PG8_SA(0, 1), a2 + hstepA, voffA);
;             PG8_WAIT_V(8); PG8_WAIT_L(0); PG8_BAR; PG8_MMA(0, 0, At, B0); PG8_MMA(0, 1, At, B1); PG8_BAR; PG8_SCHED;
;             PG8_LDA(At, 1, 1); PG8_STAGE(PG8_SB(1, 0), b3, voffB); PG8_STAGE(PG8_SB(1, 1), b3 + hstepB, voffB); PG8_STAGE(PG8_SA(1, 0), a3, voffA);
;             PG8_WAIT_V(8); PG8_WAIT_L(0); PG8_BAR; PG8_MMA(1, 0, At, B0); PG8_MMA(1, 1, At, B1); PG8_BAR; PG8_SCHED;
;         }
;         if (wr == 0) PG8_BAR;
	s_add_i32 s22, s73, s3
	v_lshl_add_u64 v[190:191], v[190:191], 0, s[90:91]
	s_mov_b32 m0, s22
	ds_read_b128 v[178:181], v145 offset:49152
	ds_read_b128 v[204:207], v145 offset:50176
	ds_read_b128 v[208:211], v145 offset:51200
	ds_read_b128 v[212:215], v145 offset:52224
	ds_read_b128 v[216:219], v145 offset:53248
	ds_read_b128 v[220:223], v145 offset:54272
	ds_read_b128 v[224:227], v145 offset:55296
	ds_read_b128 v[228:231], v145 offset:56320
	global_load_lds_dwordx4 v[190:191], off
	s_add_i32 m0, s22, 0x2000
	s_add_u32 s20, s20, 0x40080
	v_lshl_add_u64 v[190:191], v[196:197], 0, s[90:91]
	s_addc_u32 s21, s21, 0
	s_add_i32 s22, s75, s3
	global_load_lds_dwordx4 v[190:191], off
	v_lshl_add_u64 v[190:191], s[20:21], 0, v[134:135]
	s_mov_b32 m0, s22
	s_nop 0
	global_load_lds_dwordx4 v[190:191], off
	v_lshl_add_u64 v[190:191], s[20:21], 0, v[130:131]
	s_add_i32 m0, s22, 0x2000
	s_nop 0
	global_load_lds_dwordx4 v[190:191], off
	v_lshl_add_u64 v[190:191], v[198:199], 0, s[90:91]
	s_mov_b32 m0, s35
	s_nop 0
	global_load_lds_dwordx4 v[190:191], off
	v_lshl_add_u64 v[190:191], v[232:233], 0, s[90:91]
	s_mov_b32 m0, s54
	s_nop 0
	global_load_lds_dwordx4 v[190:191], off
	s_waitcnt vmcnt(8)
	s_waitcnt lgkmcnt(0)
	s_barrier
	s_setprio 0
	s_waitcnt lgkmcnt(0)
	v_mfma_f32_16x16x32_f16 v[62:65], v[146:149], v[178:181], v[62:65]
	v_mfma_f32_16x16x32_f16 v[54:57], v[154:157], v[178:181], v[54:57]
	v_mfma_f32_16x16x32_f16 v[46:49], v[146:149], v[208:211], v[46:49]
	v_mfma_f32_16x16x32_f16 v[38:41], v[154:157], v[208:211], v[38:41]
	v_mfma_f32_16x16x32_f16 v[28:31], v[146:149], v[216:219], v[28:31]
	v_mfma_f32_16x16x32_f16 v[20:23], v[154:157], v[216:219], v[20:23]
	v_mfma_f32_16x16x32_f16 v[12:15], v[146:149], v[224:227], v[12:15]
	v_mfma_f32_16x16x32_f16 v[4:7], v[154:157], v[224:227], v[4:7]
	v_mfma_f32_16x16x32_f16 v[62:65], v[150:153], v[204:207], v[62:65]
	v_mfma_f32_16x16x32_f16 v[54:57], v[158:161], v[204:207], v[54:57]
	v_mfma_f32_16x16x32_f16 v[46:49], v[150:153], v[212:215], v[46:49]
	v_mfma_f32_16x16x32_f16 v[38:41], v[158:161], v[212:215], v[38:41]
	v_mfma_f32_16x16x32_f16 v[28:31], v[150:153], v[220:223], v[28:31]
	v_mfma_f32_16x16x32_f16 v[20:23], v[158:161], v[220:223], v[20:23]
	v_mfma_f32_16x16x32_f16 v[12:15], v[150:153], v[228:231], v[12:15]
	v_mfma_f32_16x16x32_f16 v[4:7], v[158:161], v[228:231], v[4:7]
	v_mfma_f32_16x16x32_f16 v[58:61], v[162:165], v[178:181], v[58:61]
	v_mfma_f32_16x16x32_f16 v[50:53], v[170:173], v[178:181], v[50:53]
	v_mfma_f32_16x16x32_f16 v[42:45], v[162:165], v[208:211], v[42:45]
	v_mfma_f32_16x16x32_f16 v[34:37], v[170:173], v[208:211], v[34:37]
	v_mfma_f32_16x16x32_f16 v[24:27], v[162:165], v[216:219], v[24:27]
	v_mfma_f32_16x16x32_f16 v[16:19], v[170:173], v[216:219], v[16:19]
	v_mfma_f32_16x16x32_f16 v[8:11], v[162:165], v[224:227], v[8:11]
	v_mfma_f32_16x16x32_f16 v[0:3], v[170:173], v[224:227], v[0:3]
	v_mfma_f32_16x16x32_f16 v[58:61], v[166:169], v[204:207], v[58:61]
	v_mfma_f32_16x16x32_f16 v[50:53], v[174:177], v[204:207], v[50:53]
	v_mfma_f32_16x16x32_f16 v[42:45], v[166:169], v[212:215], v[42:45]
	v_mfma_f32_16x16x32_f16 v[34:37], v[174:177], v[212:215], v[34:37]
	v_mfma_f32_16x16x32_f16 v[24:27], v[166:169], v[220:223], v[24:27]
	v_mfma_f32_16x16x32_f16 v[16:19], v[174:177], v[220:223], v[16:19]
	v_mfma_f32_16x16x32_f16 v[8:11], v[166:169], v[228:231], v[8:11]
	v_mfma_f32_16x16x32_f16 v[0:3], v[174:177], v[228:231], v[0:3]
	s_setprio 2
	s_barrier
	s_add_i32 s72, s72, 2
	s_add_u32 s70, s70, 0x100
	s_addc_u32 s71, s71, 0
	s_add_u32 s18, s18, 0x100
	s_addc_u32 s19, s19, 0
	s_cmp_gt_u32 s72, 13
	s_cbranch_scc0 .LBB0_753
	s_setprio 0
	s_and_b64 vcc, exec, s[6:7]
	s_cbranch_vccz .LBB0_756
	s_barrier

; #define PG8_STAGE(bufoff, gbase, voff) do { _Pragma("unroll") for (int _i = 0; _i < 2; ++_i) \
;         __builtin_amdgcn_global_load_lds((const unsigned*)((const char*)(gbase) + (voff)[_i]), (LAS unsigned*)(lds + (bufoff) + ldsw + _i * 8192), 16, 0, 0); } while (0)
; #define PG8_LDA(dst, b, h) do { _Pragma("unroll") for (int m = 0; m < 4; ++m) _Pragma("unroll") for (int k = 0; k < 2; ++k) dst[m][k] = *(const LAS h16x8*)(lds + PG8_SA(b, h) + aoff + m * 2048 + k * 1024); } while (0)
; #define PG8_LDB(dst, b, h) do { _Pragma("unroll") for (int n = 0; n < 2; ++n) _Pragma("unroll") for (int k = 0; k < 2; ++k) dst[n][k] = *(const LAS h16x8*)(lds + PG8_SB(b, h) + boff + n * 2048 + k * 1024); } while (0)
; #define PG8_MMA(ai, bj, At, Bt) do { __builtin_amdgcn_s_setprio(1); _Pragma("unroll") for (int m = 0; m < 4; ++m) _Pragma("unroll") for (int n = 0; n < 2; ++n) _Pragma("unroll") for (int k = 0; k < 2; ++k) \
;         acc[ai][bj][m][n] = __builtin_amdgcn_mfma_f32_16x16x32_f16(Bt[n][k], At[m][k], acc[ai][bj][m][n], 0, 0, 0); __builtin_amdgcn_s_setprio(0); } while (0)
; #define PG8_WAIT_V(n) asm volatile("s_waitcnt vmcnt(" #n ")" ::: "memory")
; #define PG8_WAIT_L(n) asm volatile("s_waitcnt lgkmcnt(" #n ")" ::: "memory")
; #define PG8_BAR __builtin_amdgcn_s_barrier()
; #define PG8_SCHED __builtin_amdgcn_sched_barrier(0)
; template <class Epi>
; __device__ __forceinline__ void gemm_phase(LAS unsigned char* lds, const Gemm g, const StaticOrder& S, const Epi& E) {
;     ...
;             const bool last = (t == nt - 2);
;             const char* a1 = cA + (size_t)(t + 1) * kstep;
;             const char* a2 = last ? nA : cA + (size_t)(t + 2) * kstep; const char* b2 = last ? nB : cB + (size_t)(t + 2) * kstep;
;             const char* a3 = a2 + kstep; const char* b3 = b2 + kstep;
;             PG8_LDB(B0, 0, 0); PG8_LDB(B1, 0, 1); PG8_SCHED; PG8_LDA(At, 0, 0); PG8_STAGE(PG8_SA(1, 1), a1 + hstepA, voffA);
;             PG8_WAIT_V(8); PG8_WAIT_L(0); PG8_BAR; PG8_MMA(0, 0, At, B0); PG8_MMA(0, 1, At, B1); PG8_BAR; PG8_SCHED;
;             PG8_LDA(At, 0, 1); PG8_STAGE(PG8_SB(0, 0), b2, voffB); PG8_STAGE(PG8_SB(0, 1), b2 + hstepB, voffB); PG8_STAGE(PG8_SA(0, 0), a2, voffA);
.Lprio_916:
.LBB0_916:
	s_add_u32 s30, s28, 0xfffc0080
	s_addc_u32 s31, s29, -1
	s_add_i32 vcc_lo, 0, 0x10000
	s_cmp_eq_u32 s97, 12
	s_cselect_b32 s69, s19, s31
	s_cselect_b32 s68, s27, s30
	v_add_u32_e32 v32, vcc_lo, v147
	s_cselect_b32 s31, s17, s96
	s_cselect_b32 s30, s94, s95
	s_add_i32 s0, 0, 0x14000
	ds_read_b128 v[152:155], v32
	ds_read_b128 v[156:159], v32 offset:1024
	ds_read_b128 v[160:163], v32 offset:2048
	ds_read_b128 v[164:167], v32 offset:3072
	v_add_u32_e32 v32, s0, v147
	ds_read_b128 v[168:171], v32
	ds_read_b128 v[172:175], v32 offset:1024
	ds_read_b128 v[176:179], v32 offset:2048
	ds_read_b128 v[204:207], v32 offset:3072
	v_lshl_add_u64 v[144:145], s[28:29], 0, v[142:143]
	s_add_i32 m0, s73, 0xc000
	ds_read_b128 v[208:211], v150
	ds_read_b128 v[212:215], v150 offset:1024
	ds_read_b128 v[216:219], v150 offset:2048
	ds_read_b128 v[220:223], v150 offset:3072
	ds_read_b128 v[224:227], v150 offset:4096
	ds_read_b128 v[228:231], v150 offset:5120
	ds_read_b128 v[232:235], v150 offset:6144
	ds_read_b128 v[236:239], v150 offset:7168
	global_load_lds_dwordx4 v[144:145], off
	v_lshl_add_u64 v[144:145], s[28:29], 0, v[140:141]
	s_add_i32 m0, s73, 0xe000
	s_nop 0
	global_load_lds_dwordx4 v[144:145], off
	s_waitcnt vmcnt(8)
	s_waitcnt lgkmcnt(0)
	s_barrier
	s_setprio 0
	s_waitcnt lgkmcnt(0)
	v_mfma_f32_16x16x32_f16 v[126:129], v[152:155], v[208:211], v[126:129]
	v_mfma_f32_16x16x32_f16 v[122:125], v[160:163], v[208:211], v[122:125]
	v_mfma_f32_16x16x32_f16 v[110:113], v[152:155], v[216:219], v[110:113]
	v_mfma_f32_16x16x32_f16 v[106:109], v[160:163], v[216:219], v[106:109]
	v_mfma_f32_16x16x32_f16 v[94:97], v[152:155], v[224:227], v[94:97]
	v_mfma_f32_16x16x32_f16 v[90:93], v[160:163], v[224:227], v[90:93]
	v_mfma_f32_16x16x32_f16 v[78:81], v[152:155], v[232:235], v[78:81]
	v_mfma_f32_16x16x32_f16 v[74:77], v[160:163], v[232:235], v[74:77]
	v_mfma_f32_16x16x32_f16 v[126:129], v[156:159], v[212:215], v[126:129]
	v_mfma_f32_16x16x32_f16 v[122:125], v[164:167], v[212:215], v[122:125]
	v_mfma_f32_16x16x32_f16 v[110:113], v[156:159], v[220:223], v[110:113]
	v_mfma_f32_16x16x32_f16 v[106:109], v[164:167], v[220:223], v[106:109]
	v_mfma_f32_16x16x32_f16 v[94:97], v[156:159], v[228:231], v[94:97]
	v_mfma_f32_16x16x32_f16 v[90:93], v[164:167], v[228:231], v[90:93]
	v_mfma_f32_16x16x32_f16 v[78:81], v[156:159], v[236:239], v[78:81]
	v_mfma_f32_16x16x32_f16 v[74:77], v[164:167], v[236:239], v[74:77]
	v_mfma_f32_16x16x32_f16 v[118:121], v[168:171], v[208:211], v[118:121]
	v_mfma_f32_16x16x32_f16 v[114:117], v[176:179], v[208:211], v[114:117]
	v_mfma_f32_16x16x32_f16 v[102:105], v[168:171], v[216:219], v[102:105]
	v_mfma_f32_16x16x32_f16 v[98:101], v[176:179], v[216:219], v[98:101]
	v_mfma_f32_16x16x32_f16 v[86:89], v[168:171], v[224:227], v[86:89]
	v_mfma_f32_16x16x32_f16 v[82:85], v[176:179], v[224:227], v[82:85]
	v_mfma_f32_16x16x32_f16 v[70:73], v[168:171], v[232:235], v[70:73]
	v_mfma_f32_16x16x32_f16 v[66:69], v[176:179], v[232:235], v[66:69]
	v_mfma_f32_16x16x32_f16 v[118:121], v[172:175], v[212:215], v[118:121]
	v_mfma_f32_16x16x32_f16 v[114:117], v[204:207], v[212:215], v[114:117]
	v_mfma_f32_16x16x32_f16 v[102:105], v[172:175], v[220:223], v[102:105]
	v_mfma_f32_16x16x32_f16 v[98:101], v[204:207], v[220:223], v[98:101]
	v_mfma_f32_16x16x32_f16 v[86:89], v[172:175], v[228:231], v[86:89]
	v_mfma_f32_16x16x32_f16 v[82:85], v[204:207], v[228:231], v[82:85]
	v_mfma_f32_16x16x32_f16 v[70:73], v[172:175], v[236:239], v[70:73]
	v_mfma_f32_16x16x32_f16 v[66:69], v[204:207], v[236:239], v[66:69]
	s_setprio 2
	s_barrier
	s_add_i32 s1, vcc_lo, s54
	v_lshl_add_u64 v[144:145], s[30:31], 0, v[134:135]
	s_mov_b32 m0, s1
	ds_read_b128 v[208:211], v150 offset:16384
	ds_read_b128 v[212:215], v150 offset:17408
	ds_read_b128 v[216:219], v150 offset:18432
	ds_read_b128 v[220:223], v150 offset:19456
	ds_read_b128 v[224:227], v150 offset:20480
	ds_read_b128 v[228:231], v150 offset:21504
	ds_read_b128 v[232:235], v150 offset:22528
	ds_read_b128 v[236:239], v150 offset:23552
	global_load_lds_dwordx4 v[144:145], off
	s_add_i32 m0, s1, 0x2000
	s_add_u32 vcc_lo, s30, 0x40000
	v_lshl_add_u64 v[180:181], s[30:31], 0, v[130:131]
	s_addc_u32 vcc_hi, s31, 0
	s_add_i32 s0, s0, s54
	global_load_lds_dwordx4 v[180:181], off
	v_lshl_add_u64 v[190:191], vcc, 0, v[134:135]
	s_mov_b32 m0, s0
	v_lshl_add_u64 v[196:197], s[68:69], 0, v[132:133]
	global_load_lds_dwordx4 v[190:191], off
	v_lshl_add_u64 v[190:191], vcc, 0, v[130:131]
	s_add_i32 m0, s0, 0x2000
	s_nop 0
	global_load_lds_dwordx4 v[190:191], off
	v_lshl_add_u64 v[190:191], s[68:69], 0, v[136:137]
	s_mov_b32 m0, s73
	s_nop 0
	global_load_lds_dwordx4 v[190:191], off
	s_mov_b32 m0, s75
	s_nop 0
	global_load_lds_dwordx4 v[196:197], off
	s_waitcnt vmcnt(8)
	s_waitcnt lgkmcnt(0)
	s_barrier
; #define PG8_STAGE(bufoff, gbase, voff) do { _Pragma("unroll") for (int _i = 0; _i < 2; ++_i) \
;         __builtin_amdgcn_global_load_lds((const unsigned*)((const char*)(gbase) + (voff)[_i]), (LAS unsigned*)(lds + (bufoff) + ldsw + _i * 8192), 16, 0, 0); } while (0)
; #define PG8_LDA(dst, b, h) do { _Pragma("unroll") for (int m = 0; m < 4; ++m) _Pragma("unroll") for (int k = 0; k < 2; ++k) dst[m][k] = *(const LAS h16x8*)(lds + PG8_SA(b, h) + aoff + m * 2048 + k * 1024); } while (0)
; #define PG8_LDB(dst, b, h) do { _Pragma("unroll") for (int n = 0; n < 2; ++n) _Pragma("unroll") for (int k = 0; k < 2; ++k) dst[n][k] = *(const LAS h16x8*)(lds + PG8_SB(b, h) + boff + n * 2048 + k * 1024); } while (0)
; #define PG8_MMA(ai, bj, At, Bt) do { __builtin_amdgcn_s_setprio(1); _Pragma("unroll") for (int m = 0; m < 4; ++m) _Pragma("unroll") for (int n = 0; n < 2; ++n) _Pragma("unroll") for (int k = 0; k < 2; ++k) \
;         acc[ai][bj][m][n] = __builtin_amdgcn_mfma_f32_16x16x32_f16(Bt[n][k], At[m][k], acc[ai][bj][m][n], 0, 0, 0); __builtin_amdgcn_s_setprio(0); } while (0)
; #define PG8_WAIT_V(n) asm volatile("s_waitcnt vmcnt(" #n ")" ::: "memory")
; #define PG8_WAIT_L(n) asm volatile("s_waitcnt lgkmcnt(" #n ")" ::: "memory")
; #define PG8_BAR __builtin_amdgcn_s_barrier()
; #define PG8_SCHED __builtin_amdgcn_sched_barrier(0)
; template <class Epi>
; __device__ __forceinline__ void gemm_phase(LAS unsigned char* lds, const Gemm g, const StaticOrder& S, const Epi& E) {
;     ...
;             PG8_WAIT_V(8); PG8_WAIT_L(0); PG8_BAR; PG8_MMA(1, 0, At, B0); PG8_MMA(1, 1, At, B1); PG8_BAR; PG8_SCHED;
;             PG8_LDB(B0, 1, 0); PG8_LDB(B1, 1, 1); PG8_SCHED; PG8_LDA(At, 1, 0); PG8_STAGE(PG8_SA(0, 1), a2 + hstepA, voffA);
;             PG8_WAIT_V(8); PG8_WAIT_L(0); PG8_BAR; PG8_MMA(0, 0, At, B0); PG8_MMA(0, 1, At, B1); PG8_BAR; PG8_SCHED;
	s_setprio 0
	s_waitcnt lgkmcnt(0)
	v_mfma_f32_16x16x32_f16 v[62:65], v[152:155], v[208:211], v[62:65]
	v_mfma_f32_16x16x32_f16 v[58:61], v[160:163], v[208:211], v[58:61]
	v_mfma_f32_16x16x32_f16 v[46:49], v[152:155], v[216:219], v[46:49]
	v_mfma_f32_16x16x32_f16 v[42:45], v[160:163], v[216:219], v[42:45]
	v_mfma_f32_16x16x32_f16 v[28:31], v[152:155], v[224:227], v[28:31]
	v_mfma_f32_16x16x32_f16 v[24:27], v[160:163], v[224:227], v[24:27]
	v_mfma_f32_16x16x32_f16 v[12:15], v[152:155], v[232:235], v[12:15]
	v_mfma_f32_16x16x32_f16 v[8:11], v[160:163], v[232:235], v[8:11]
	v_mfma_f32_16x16x32_f16 v[62:65], v[156:159], v[212:215], v[62:65]
	v_mfma_f32_16x16x32_f16 v[58:61], v[164:167], v[212:215], v[58:61]
	v_mfma_f32_16x16x32_f16 v[46:49], v[156:159], v[220:223], v[46:49]
	v_mfma_f32_16x16x32_f16 v[42:45], v[164:167], v[220:223], v[42:45]
	v_mfma_f32_16x16x32_f16 v[28:31], v[156:159], v[228:231], v[28:31]
	v_mfma_f32_16x16x32_f16 v[24:27], v[164:167], v[228:231], v[24:27]
	v_mfma_f32_16x16x32_f16 v[12:15], v[156:159], v[236:239], v[12:15]
	v_mfma_f32_16x16x32_f16 v[8:11], v[164:167], v[236:239], v[8:11]
	v_mfma_f32_16x16x32_f16 v[54:57], v[168:171], v[208:211], v[54:57]
	v_mfma_f32_16x16x32_f16 v[50:53], v[176:179], v[208:211], v[50:53]
	v_mfma_f32_16x16x32_f16 v[38:41], v[168:171], v[216:219], v[38:41]
	v_mfma_f32_16x16x32_f16 v[34:37], v[176:179], v[216:219], v[34:37]
	v_mfma_f32_16x16x32_f16 v[20:23], v[168:171], v[224:227], v[20:23]
	v_mfma_f32_16x16x32_f16 v[16:19], v[176:179], v[224:227], v[16:19]
	v_mfma_f32_16x16x32_f16 v[4:7], v[168:171], v[232:235], v[4:7]
	v_mfma_f32_16x16x32_f16 v[0:3], v[176:179], v[232:235], v[0:3]
	v_mfma_f32_16x16x32_f16 v[54:57], v[172:175], v[212:215], v[54:57]
	v_mfma_f32_16x16x32_f16 v[50:53], v[204:207], v[212:215], v[50:53]
	v_mfma_f32_16x16x32_f16 v[38:41], v[172:175], v[220:223], v[38:41]
	v_mfma_f32_16x16x32_f16 v[34:37], v[204:207], v[220:223], v[34:37]
	v_mfma_f32_16x16x32_f16 v[20:23], v[172:175], v[228:231], v[20:23]
	v_mfma_f32_16x16x32_f16 v[16:19], v[204:207], v[228:231], v[16:19]
	v_mfma_f32_16x16x32_f16 v[4:7], v[172:175], v[236:239], v[4:7]
	v_mfma_f32_16x16x32_f16 v[0:3], v[204:207], v[236:239], v[0:3]
	s_setprio 2
	s_barrier
	s_add_i32 s0, 0, 0x18000
	v_add_u32_e32 v32, s0, v147
	s_add_i32 s1, 0, 0x1c000
	ds_read_b128 v[152:155], v32
	ds_read_b128 v[156:159], v32 offset:1024
	ds_read_b128 v[160:163], v32 offset:2048
	ds_read_b128 v[164:167], v32 offset:3072
	v_add_u32_e32 v32, s1, v147
	ds_read_b128 v[168:171], v32
	ds_read_b128 v[172:175], v32 offset:1024
	ds_read_b128 v[176:179], v32 offset:2048
	ds_read_b128 v[204:207], v32 offset:3072
	s_add_u32 s68, s68, 0x40000
	s_addc_u32 s69, s69, 0
	s_mov_b32 m0, s76
	v_lshl_add_u64 v[198:199], s[68:69], 0, v[136:137]
	ds_read_b128 v[208:211], v150 offset:32768
	ds_read_b128 v[212:215], v150 offset:33792
	ds_read_b128 v[216:219], v150 offset:34816
	ds_read_b128 v[220:223], v150 offset:35840
	ds_read_b128 v[224:227], v150 offset:36864
	ds_read_b128 v[228:231], v150 offset:37888
	ds_read_b128 v[232:235], v150 offset:38912
	ds_read_b128 v[236:239], v150 offset:39936
	global_load_lds_dwordx4 v[198:199], off
	v_lshl_add_u64 v[198:199], s[68:69], 0, v[132:133]
	s_mov_b32 m0, s77
	s_nop 0
	global_load_lds_dwordx4 v[198:199], off
	s_waitcnt vmcnt(8)
	s_waitcnt lgkmcnt(0)
	s_barrier
	s_setprio 0
	s_waitcnt lgkmcnt(0)
	v_mfma_f32_16x16x32_f16 v[126:129], v[152:155], v[208:211], v[126:129]
	v_mfma_f32_16x16x32_f16 v[122:125], v[160:163], v[208:211], v[122:125]
	v_mfma_f32_16x16x32_f16 v[110:113], v[152:155], v[216:219], v[110:113]
	v_mfma_f32_16x16x32_f16 v[106:109], v[160:163], v[216:219], v[106:109]
	v_mfma_f32_16x16x32_f16 v[94:97], v[152:155], v[224:227], v[94:97]
	v_mfma_f32_16x16x32_f16 v[90:93], v[160:163], v[224:227], v[90:93]
	v_mfma_f32_16x16x32_f16 v[78:81], v[152:155], v[232:235], v[78:81]
	v_mfma_f32_16x16x32_f16 v[74:77], v[160:163], v[232:235], v[74:77]
	v_mfma_f32_16x16x32_f16 v[126:129], v[156:159], v[212:215], v[126:129]
	v_mfma_f32_16x16x32_f16 v[122:125], v[164:167], v[212:215], v[122:125]
	v_mfma_f32_16x16x32_f16 v[110:113], v[156:159], v[220:223], v[110:113]
	v_mfma_f32_16x16x32_f16 v[106:109], v[164:167], v[220:223], v[106:109]
	v_mfma_f32_16x16x32_f16 v[94:97], v[156:159], v[228:231], v[94:97]
	v_mfma_f32_16x16x32_f16 v[90:93], v[164:167], v[228:231], v[90:93]
	v_mfma_f32_16x16x32_f16 v[78:81], v[156:159], v[236:239], v[78:81]
	v_mfma_f32_16x16x32_f16 v[74:77], v[164:167], v[236:239], v[74:77]
	v_mfma_f32_16x16x32_f16 v[118:121], v[168:171], v[208:211], v[118:121]
	v_mfma_f32_16x16x32_f16 v[114:117], v[176:179], v[208:211], v[114:117]
	v_mfma_f32_16x16x32_f16 v[102:105], v[168:171], v[216:219], v[102:105]
	v_mfma_f32_16x16x32_f16 v[98:101], v[176:179], v[216:219], v[98:101]
	v_mfma_f32_16x16x32_f16 v[86:89], v[168:171], v[224:227], v[86:89]
	v_mfma_f32_16x16x32_f16 v[82:85], v[176:179], v[224:227], v[82:85]
	v_mfma_f32_16x16x32_f16 v[70:73], v[168:171], v[232:235], v[70:73]
	v_mfma_f32_16x16x32_f16 v[66:69], v[176:179], v[232:235], v[66:69]
	v_mfma_f32_16x16x32_f16 v[118:121], v[172:175], v[212:215], v[118:121]
	v_mfma_f32_16x16x32_f16 v[114:117], v[204:207], v[212:215], v[114:117]
	v_mfma_f32_16x16x32_f16 v[102:105], v[172:175], v[220:223], v[102:105]
	v_mfma_f32_16x16x32_f16 v[98:101], v[204:207], v[220:223], v[98:101]
	v_mfma_f32_16x16x32_f16 v[86:89], v[172:175], v[228:231], v[86:89]
	v_mfma_f32_16x16x32_f16 v[82:85], v[204:207], v[228:231], v[82:85]
	v_mfma_f32_16x16x32_f16 v[70:73], v[172:175], v[236:239], v[70:73]
	v_mfma_f32_16x16x32_f16 v[66:69], v[204:207], v[236:239], v[66:69]
	s_setprio 2
	s_barrier
; #define PG8_STAGE(bufoff, gbase, voff) do { _Pragma("unroll") for (int _i = 0; _i < 2; ++_i) \
;         __builtin_amdgcn_global_load_lds((const unsigned*)((const char*)(gbase) + (voff)[_i]), (LAS unsigned*)(lds + (bufoff) + ldsw + _i * 8192), 16, 0, 0); } while (0)
; #define PG8_LDA(dst, b, h) do { _Pragma("unroll") for (int m = 0; m < 4; ++m) _Pragma("unroll") for (int k = 0; k < 2; ++k) dst[m][k] = *(const LAS h16x8*)(lds + PG8_SA(b, h) + aoff + m * 2048 + k * 1024); } while (0)
; #define PG8_LDB(dst, b, h) do { _Pragma("unroll") for (int n = 0; n < 2; ++n) _Pragma("unroll") for (int k = 0; k < 2; ++k) dst[n][k] = *(const LAS h16x8*)(lds + PG8_SB(b, h) + boff + n * 2048 + k * 1024); } while (0)
; #define PG8_WAIT_V(n) asm volatile("s_waitcnt vmcnt(" #n ")" ::: "memory")
; template <class Epi>
; __device__ __forceinline__ void gemm_phase(LAS unsigned char* lds, const Gemm g, const StaticOrder& S, const Epi& E) {
;     ...
;         for (int t = 0; t < nt; t += 2) {
;             const bool last = (t == nt - 2);
;             const char* a1 = cA + (size_t)(t + 1) * kstep;
;             const char* a2 = last ? nA : cA + (size_t)(t + 2) * kstep; const char* b2 = last ? nB : cB + (size_t)(t + 2) * kstep;
;             const char* a3 = a2 + kstep; const char* b3 = b2 + kstep;
;             PG8_LDB(B0, 0, 0); PG8_LDB(B1, 0, 1); PG8_SCHED; PG8_LDA(At, 0, 0); PG8_STAGE(PG8_SA(1, 1), a1 + hstepA, voffA);
;             PG8_WAIT_V(8); PG8_WAIT_L(0); PG8_BAR; PG8_MMA(0, 0, At, B0); PG8_MMA(0, 1, At, B1); PG8_BAR; PG8_SCHED;
;             PG8_LDA(At, 0, 1); PG8_STAGE(PG8_SB(0, 0), b2, voffB); PG8_STAGE(PG8_SB(0, 1), b2 + hstepB, voffB); PG8_STAGE(PG8_SA(0, 0), a2, voffA);
;             PG8_WAIT_V(8); PG8_WAIT_L(0); PG8_BAR; PG8_MMA(1, 0, At, B0); PG8_MMA(1, 1, At, B1); PG8_BAR; PG8_SCHED;
;             PG8_LDB(B0, 1, 0); PG8_LDB(B1, 1, 1); PG8_SCHED; PG8_LDA(At, 1, 0); PG8_STAGE(PG8_SA(0, 1), a2 + hstepA, voffA);
;             PG8_WAIT_V(8); PG8_WAIT_L(0); PG8_BAR; PG8_MMA(0, 0, At, B0); PG8_MMA(0, 1, At, B1); PG8_BAR; PG8_SCHED;
;             PG8_LDA(At, 1, 1); PG8_STAGE(PG8_SB(1, 0), b3, voffB); PG8_STAGE(PG8_SB(1, 1), b3 + hstepB, voffB); PG8_STAGE(PG8_SA(1, 0), a3, voffA);
;             PG8_WAIT_V(8); PG8_WAIT_L(0); PG8_BAR; PG8_MMA(1, 0, At, B0); PG8_MMA(1, 1, At, B1); PG8_BAR; PG8_SCHED;
;         }
;         if (wr == 0) PG8_BAR;
	s_add_i32 s0, s0, s54
	v_lshl_add_u64 v[144:145], v[144:145], 0, s[90:91]
	s_mov_b32 m0, s0
	ds_read_b128 v[208:211], v150 offset:49152
	ds_read_b128 v[212:215], v150 offset:50176
	ds_read_b128 v[216:219], v150 offset:51200
	ds_read_b128 v[220:223], v150 offset:52224
	ds_read_b128 v[224:227], v150 offset:53248
	ds_read_b128 v[228:231], v150 offset:54272
	ds_read_b128 v[232:235], v150 offset:55296
	ds_read_b128 v[236:239], v150 offset:56320
	global_load_lds_dwordx4 v[144:145], off
	s_add_i32 m0, s0, 0x2000
	s_add_u32 s30, s30, 0x40080
	v_lshl_add_u64 v[144:145], v[180:181], 0, s[90:91]
	s_addc_u32 s31, s31, 0
	s_add_i32 s0, s1, s54
	global_load_lds_dwordx4 v[144:145], off
	v_lshl_add_u64 v[144:145], s[30:31], 0, v[134:135]
	s_mov_b32 m0, s0
	s_nop 0
	global_load_lds_dwordx4 v[144:145], off
	v_lshl_add_u64 v[144:145], s[30:31], 0, v[130:131]
	s_add_i32 m0, s0, 0x2000
	s_nop 0
	global_load_lds_dwordx4 v[144:145], off
	v_lshl_add_u64 v[144:145], v[190:191], 0, s[90:91]
	s_mov_b32 m0, s81
	s_nop 0
	global_load_lds_dwordx4 v[144:145], off
	v_lshl_add_u64 v[144:145], v[196:197], 0, s[90:91]
	s_mov_b32 m0, s88
	s_nop 0
	global_load_lds_dwordx4 v[144:145], off
	s_waitcnt vmcnt(8)
	s_waitcnt lgkmcnt(0)
	s_barrier
	s_setprio 0
	s_waitcnt lgkmcnt(0)
	v_mfma_f32_16x16x32_f16 v[62:65], v[152:155], v[208:211], v[62:65]
	v_mfma_f32_16x16x32_f16 v[58:61], v[160:163], v[208:211], v[58:61]
	v_mfma_f32_16x16x32_f16 v[46:49], v[152:155], v[216:219], v[46:49]
	v_mfma_f32_16x16x32_f16 v[42:45], v[160:163], v[216:219], v[42:45]
	v_mfma_f32_16x16x32_f16 v[28:31], v[152:155], v[224:227], v[28:31]
	v_mfma_f32_16x16x32_f16 v[24:27], v[160:163], v[224:227], v[24:27]
	v_mfma_f32_16x16x32_f16 v[12:15], v[152:155], v[232:235], v[12:15]
	v_mfma_f32_16x16x32_f16 v[8:11], v[160:163], v[232:235], v[8:11]
	v_mfma_f32_16x16x32_f16 v[62:65], v[156:159], v[212:215], v[62:65]
	v_mfma_f32_16x16x32_f16 v[58:61], v[164:167], v[212:215], v[58:61]
	v_mfma_f32_16x16x32_f16 v[46:49], v[156:159], v[220:223], v[46:49]
	v_mfma_f32_16x16x32_f16 v[42:45], v[164:167], v[220:223], v[42:45]
	v_mfma_f32_16x16x32_f16 v[28:31], v[156:159], v[228:231], v[28:31]
	v_mfma_f32_16x16x32_f16 v[24:27], v[164:167], v[228:231], v[24:27]
	v_mfma_f32_16x16x32_f16 v[12:15], v[156:159], v[236:239], v[12:15]
	v_mfma_f32_16x16x32_f16 v[8:11], v[164:167], v[236:239], v[8:11]
	v_mfma_f32_16x16x32_f16 v[54:57], v[168:171], v[208:211], v[54:57]
	v_mfma_f32_16x16x32_f16 v[50:53], v[176:179], v[208:211], v[50:53]
	v_mfma_f32_16x16x32_f16 v[38:41], v[168:171], v[216:219], v[38:41]
	v_mfma_f32_16x16x32_f16 v[34:37], v[176:179], v[216:219], v[34:37]
	v_mfma_f32_16x16x32_f16 v[20:23], v[168:171], v[224:227], v[20:23]
	v_mfma_f32_16x16x32_f16 v[16:19], v[176:179], v[224:227], v[16:19]
	v_mfma_f32_16x16x32_f16 v[4:7], v[168:171], v[232:235], v[4:7]
	v_mfma_f32_16x16x32_f16 v[0:3], v[176:179], v[232:235], v[0:3]
	v_mfma_f32_16x16x32_f16 v[54:57], v[172:175], v[212:215], v[54:57]
	v_mfma_f32_16x16x32_f16 v[50:53], v[204:207], v[212:215], v[50:53]
	v_mfma_f32_16x16x32_f16 v[38:41], v[172:175], v[220:223], v[38:41]
	v_mfma_f32_16x16x32_f16 v[34:37], v[204:207], v[220:223], v[34:37]
	v_mfma_f32_16x16x32_f16 v[20:23], v[172:175], v[228:231], v[20:23]
	v_mfma_f32_16x16x32_f16 v[16:19], v[204:207], v[228:231], v[16:19]
	v_mfma_f32_16x16x32_f16 v[4:7], v[172:175], v[236:239], v[4:7]
	v_mfma_f32_16x16x32_f16 v[0:3], v[204:207], v[236:239], v[0:3]
	s_setprio 2
	s_barrier
	s_add_i32 s97, s97, 2
	s_add_u32 s95, s95, 0x100
	s_addc_u32 s96, s96, 0
	s_add_u32 s28, s28, 0x100
	s_addc_u32 s29, s29, 0
	s_cmp_gt_u32 s97, 13
	s_cbranch_scc0 .LBB0_916
	s_setprio 0
	s_and_b64 vcc, exec, s[10:11]
	s_cbranch_vccz .LBB0_919
	s_barrier
